# speedup vs baseline: 1.0114x; 1.0035x over previous
; template <int DH, int MODE>
; __device__ void attn_item(const Params& p, int layer, int b, int blk, int head, char* smem) {
;     ...
;     V_SCATTER_(vr0, 0);
;     V_SCATTER_(vr1, 1);
;     if (KCH > 2) {
;       V_SCATTER_(vr2, 2);
;       V_SCATTER_(vr3, 3);
;     }
;     KV_LOAD_(it + 1);
;     if (!wskip) {
;       float4* s4 = reinterpret_cast<float4*>(Sf + row * SSTR + half * 32);
;       char* prow = Pb + half * 8192 + row * 64;
;       if (MODE == 0) {
;         const int kjb = kj0 + half * 32;
;         float tmax = -1e30f;
; #pragma unroll
;         for (int c = 0; c < 8; ++c) {
;           float4 v = s4[c];
;           float e[4] = {v.x, v.y, v.z, v.w};
; #pragma unroll
;           for (int k = 0; k < 4; ++k) {
;             int kj = kjb + c * 4 + k;
;             bool valid = (kj > row) && (kj <= row + 128);
;             tmax = valid ? fmaxf(tmax, e[k]) : tmax;
;           }
;         }
;         tmax = fmaxf(tmax, __shfl_xor(tmax, 1));
.LBB0_166:
	s_or_b64 exec, exec, s[6:7]
	s_add_i32 s86, s86, 1
	s_min_i32 s6, s86, s84
	s_add_i32 s6, s6, s83
	s_lshl_b32 s6, s6, 6
	s_add_i32 s6, s6, s85
	s_ashr_i32 s7, s6, 31
	s_add_u32 s6, s6, s81
	s_addc_u32 s7, s7, 0
	s_waitcnt lgkmcnt(0)
	s_barrier
	ds_write_b16 v96, v48
	ds_write_b16_d16_hi v96, v48 offset:64
	ds_write_b16 v96, v49 offset:128
	ds_write_b16_d16_hi v96, v49 offset:192
	ds_write_b16 v96, v50 offset:256
	ds_write_b16_d16_hi v96, v50 offset:320
	ds_write_b16 v96, v51 offset:384
	ds_write_b16_d16_hi v96, v51 offset:448
	s_waitcnt vmcnt(0)
	ds_write_b16 v96, v52 offset:2048
	ds_write_b16_d16_hi v96, v52 offset:2112
	ds_write_b16 v96, v53 offset:2176
	ds_write_b16_d16_hi v96, v53 offset:2240
	ds_write_b16 v96, v54 offset:2304
	ds_write_b16_d16_hi v96, v54 offset:2368
	ds_write_b16 v96, v55 offset:2432
	ds_write_b16_d16_hi v96, v55 offset:2496
	v_lshl_add_u64 v[48:49], s[6:7], 0, v[66:67]
	v_mad_u64_u32 v[52:53], s[10:11], v48, s55, v[76:77]
	v_or_b32_e32 v48, s6, v72
	v_mad_i32_i24 v53, v49, s55, v53
	v_mad_u64_u32 v[54:55], s[10:11], v48, s55, v[78:79]
	v_add_co_u32_e32 v48, vcc, 0x4c000, v52
	v_mad_i32_i24 v55, s7, v160, v55
	s_nop 0
	v_addc_co_u32_e32 v49, vcc, 0, v53, vcc
	global_load_dwordx4 v[60:63], v[48:49], off
	s_nop 0
	global_load_dwordx4 v[48:51], v[54:55], off
	global_load_dwordx4 v[56:59], v[52:53], off
	s_nop 0
	global_load_dwordx4 v[52:55], v[54:55], off offset:64
	s_and_saveexec_b64 s[52:53], s[50:51]
	s_cbranch_execz .LBB0_188
	v_or_b32_e32 v101, s8, v89
	s_movk_i32 s91, 0x80
	ds_read_b128 v[164:167], v90 offset:16384
	ds_read_b128 v[168:171], v90 offset:16400
	ds_read_b128 v[172:175], v90 offset:16416
	ds_read_b128 v[176:179], v90 offset:16432
	ds_read_b128 v[180:183], v90 offset:16448
	ds_read_b128 v[184:187], v90 offset:16464
	ds_read_b128 v[188:191], v90 offset:16480
	ds_read_b128 v[192:195], v90 offset:16496
	v_sub_u32_e32 v102, v80, v101
	v_mov_b32_e32 v83, 0xf149f2ca
	v_add_u32_e32 v103, -31, v102
	v_cmp_gt_u32_e32 vcc, 0x61, v103
	s_cmp_eq_u64 vcc, exec
	s_cbranch_scc1 .Lswa_tfast_3
	v_mov_b32_e32 v196, v102
	v_add_u32_e32 v197, -1, v102
	v_add_u32_e32 v198, -2, v102
	v_cmp_gt_u32_e32 vcc, s91, v196
	v_cmp_gt_u32_e64 s[92:93], s91, v197
	v_cmp_gt_u32_e64 s[94:95], s91, v198
	s_waitcnt lgkmcnt(7)
	v_cndmask_b32_e32 v164, v83, v164, vcc
	v_cndmask_b32_e64 v165, v83, v165, s[92:93]
	v_cndmask_b32_e64 v166, v83, v166, s[94:95]
	v_add_u32_e32 v196, -3, v102
	v_add_u32_e32 v197, -4, v102
	v_add_u32_e32 v198, -5, v102
	v_cmp_gt_u32_e32 vcc, s91, v196
	v_cmp_gt_u32_e64 s[92:93], s91, v197
	v_cmp_gt_u32_e64 s[94:95], s91, v198
	s_waitcnt lgkmcnt(6)
	v_cndmask_b32_e32 v167, v83, v167, vcc
	v_cndmask_b32_e64 v168, v83, v168, s[92:93]
	v_cndmask_b32_e64 v169, v83, v169, s[94:95]
	v_add_u32_e32 v196, -6, v102
	v_add_u32_e32 v197, -7, v102
	v_add_u32_e32 v198, -8, v102
	v_cmp_gt_u32_e32 vcc, s91, v196
	v_cmp_gt_u32_e64 s[92:93], s91, v197
	v_cmp_gt_u32_e64 s[94:95], s91, v198
	s_waitcnt lgkmcnt(5)
	v_cndmask_b32_e32 v170, v83, v170, vcc
	v_cndmask_b32_e64 v171, v83, v171, s[92:93]
	v_cndmask_b32_e64 v172, v83, v172, s[94:95]
	v_add_u32_e32 v196, -9, v102
	v_add_u32_e32 v197, -10, v102
	v_add_u32_e32 v198, -11, v102
	v_cmp_gt_u32_e32 vcc, s91, v196
	v_cmp_gt_u32_e64 s[92:93], s91, v197
	v_cmp_gt_u32_e64 s[94:95], s91, v198
	v_cndmask_b32_e32 v173, v83, v173, vcc
	v_cndmask_b32_e64 v174, v83, v174, s[92:93]
	v_cndmask_b32_e64 v175, v83, v175, s[94:95]
	v_add_u32_e32 v196, -12, v102
	v_add_u32_e32 v197, -13, v102
	v_add_u32_e32 v198, -14, v102
	v_cmp_gt_u32_e32 vcc, s91, v196
	v_cmp_gt_u32_e64 s[92:93], s91, v197
	v_cmp_gt_u32_e64 s[94:95], s91, v198
	s_waitcnt lgkmcnt(4)
	v_cndmask_b32_e32 v176, v83, v176, vcc
	v_cndmask_b32_e64 v177, v83, v177, s[92:93]
	v_cndmask_b32_e64 v178, v83, v178, s[94:95]
	v_add_u32_e32 v196, -15, v102
	v_add_u32_e32 v197, -16, v102
	v_add_u32_e32 v198, 0xffffffef, v102
	v_cmp_gt_u32_e32 vcc, s91, v196
	v_cmp_gt_u32_e64 s[92:93], s91, v197
	v_cmp_gt_u32_e64 s[94:95], s91, v198
	s_waitcnt lgkmcnt(3)
	v_cndmask_b32_e32 v179, v83, v179, vcc
	v_cndmask_b32_e64 v180, v83, v180, s[92:93]
	v_cndmask_b32_e64 v181, v83, v181, s[94:95]
	v_add_u32_e32 v196, 0xffffffee, v102
	v_add_u32_e32 v197, 0xffffffed, v102
	v_add_u32_e32 v198, 0xffffffec, v102
	v_cmp_gt_u32_e32 vcc, s91, v196
	v_cmp_gt_u32_e64 s[92:93], s91, v197
	v_cmp_gt_u32_e64 s[94:95], s91, v198
	s_waitcnt lgkmcnt(2)
	v_cndmask_b32_e32 v182, v83, v182, vcc
	v_cndmask_b32_e64 v183, v83, v183, s[92:93]
	v_cndmask_b32_e64 v184, v83, v184, s[94:95]
	v_add_u32_e32 v196, 0xffffffeb, v102
	v_add_u32_e32 v197, 0xffffffea, v102
	v_add_u32_e32 v198, 0xffffffe9, v102
	v_cmp_gt_u32_e32 vcc, s91, v196
	v_cmp_gt_u32_e64 s[92:93], s91, v197
	v_cmp_gt_u32_e64 s[94:95], s91, v198
	v_cndmask_b32_e32 v185, v83, v185, vcc
	v_cndmask_b32_e64 v186, v83, v186, s[92:93]
	v_cndmask_b32_e64 v187, v83, v187, s[94:95]
	v_add_u32_e32 v196, 0xffffffe8, v102
	v_add_u32_e32 v197, 0xffffffe7, v102
	v_add_u32_e32 v198, 0xffffffe6, v102
	v_cmp_gt_u32_e32 vcc, s91, v196
	v_cmp_gt_u32_e64 s[92:93], s91, v197
	v_cmp_gt_u32_e64 s[94:95], s91, v198
	s_waitcnt lgkmcnt(1)
	v_cndmask_b32_e32 v188, v83, v188, vcc
	v_cndmask_b32_e64 v189, v83, v189, s[92:93]
	v_cndmask_b32_e64 v190, v83, v190, s[94:95]
	v_add_u32_e32 v196, 0xffffffe5, v102
	v_add_u32_e32 v197, 0xffffffe4, v102
	v_add_u32_e32 v198, 0xffffffe3, v102
	v_cmp_gt_u32_e32 vcc, s91, v196
	v_cmp_gt_u32_e64 s[92:93], s91, v197
	v_cmp_gt_u32_e64 s[94:95], s91, v198
	s_waitcnt lgkmcnt(0)
	v_cndmask_b32_e32 v191, v83, v191, vcc
	v_cndmask_b32_e64 v192, v83, v192, s[92:93]
	v_cndmask_b32_e64 v193, v83, v193, s[94:95]
	v_add_u32_e32 v196, 0xffffffe2, v102
	v_add_u32_e32 v197, 0xffffffe1, v102
	v_cmp_gt_u32_e32 vcc, s91, v196
	v_cmp_gt_u32_e64 s[92:93], s91, v197
	s_nop 0
	v_cndmask_b32_e32 v194, v83, v194, vcc
	v_cndmask_b32_e64 v195, v83, v195, s[92:93]
	v_max3_f32 v164, v164, v165, v166
	v_max3_f32 v167, v167, v168, v169
	v_max3_f32 v170, v170, v171, v172
	v_max3_f32 v173, v173, v174, v175
	v_max3_f32 v176, v176, v177, v178
	v_max3_f32 v179, v179, v180, v181
	v_max3_f32 v182, v182, v183, v184
	v_max3_f32 v185, v185, v186, v187
	v_max3_f32 v188, v188, v189, v190
	v_max3_f32 v191, v191, v192, v193
	v_max_f32_e32 v194, v194, v195
	v_max3_f32 v164, v164, v167, v170
	v_max3_f32 v173, v173, v176, v179
	v_max3_f32 v182, v182, v185, v188
	v_max_f32_e32 v191, v191, v194
	v_max3_f32 v164, v164, v173, v182
	v_max_f32_e32 v164, v164, v191
	v_mov_b32_e32 v82, v164
	s_branch .Lswa_tdone_3
; template <int DH, int MODE>
; __device__ void attn_item(const Params& p, int layer, int b, int blk, int head, char* smem) {
;     ...
;         const int kjb = kj0 + half * 32;
;         float tmax = -1e30f;
; #pragma unroll
;         for (int c = 0; c < 8; ++c) {
;           float4 v = s4[c];
;           float e[4] = {v.x, v.y, v.z, v.w};
; #pragma unroll
;           for (int k = 0; k < 4; ++k) {
;             int kj = kjb + c * 4 + k;
;             bool valid = (kj > row) && (kj <= row + 128);
;             tmax = valid ? fmaxf(tmax, e[k]) : tmax;
;           }
;         }
;         tmax = fmaxf(tmax, __shfl_xor(tmax, 1));
;         float m_new = fmaxf(m_run, tmax);
;         float alpha = __builtin_amdgcn_exp2f(m_run - m_new);
;         float psum = 0.f;
; #pragma unroll 2
;         for (int s8 = 0; s8 < 4; ++s8) {
;           float4 va = s4[2 * s8], vb = s4[2 * s8 + 1];
;           float e[8] = {va.x, va.y, va.z, va.w, vb.x, vb.y, vb.z, vb.w};
;           float pv[8];
; #pragma unroll
;           for (int k = 0; k < 8; ++k) {
;             int kj = kjb + s8 * 8 + k;
;             bool valid = (kj > row) && (kj <= row + 128);
;             float pe = valid ? __builtin_amdgcn_exp2f(e[k] - m_new) : 0.f;
;             pv[k] = pe;
;             psum += pe;
;           }
.Lswa_tfast_3:
	s_waitcnt lgkmcnt(0)
	v_max3_f32 v164, v164, v165, v166
	v_max3_f32 v167, v167, v168, v169
	v_max3_f32 v170, v170, v171, v172
	v_max3_f32 v173, v173, v174, v175
	v_max3_f32 v176, v176, v177, v178
	v_max3_f32 v179, v179, v180, v181
	v_max3_f32 v182, v182, v183, v184
	v_max3_f32 v185, v185, v186, v187
	v_max3_f32 v188, v188, v189, v190
	v_max3_f32 v191, v191, v192, v193
	v_max3_f32 v194, v194, v195, v83
	v_max3_f32 v164, v164, v167, v170
	v_max3_f32 v173, v173, v176, v179
	v_max3_f32 v182, v182, v185, v188
	v_max_f32_e32 v191, v191, v194
	v_max3_f32 v164, v164, v173, v182
	v_max_f32_e32 v164, v164, v191
	v_mov_b32_e32 v82, v164
.Lswa_tdone_3:
	v_cmp_lt_i32_e32 vcc, v157, v158
	s_mov_b32 s87, 0
	v_mov_b32_e32 v103, 0
	v_cndmask_b32_e32 v83, v156, v157, vcc
	v_lshlrev_b32_e32 v83, 2, v83
	ds_bpermute_b32 v101, v83, v82
	v_mov_b32_e32 v102, v91
	s_waitcnt lgkmcnt(0)
	v_max3_f32 v82, v87, v82, v101
	v_mov_b32_e32 v101, v93
	ds_read_b128 v[164:167], v102
	ds_read_b128 v[168:171], v102 offset:16
	ds_read_b128 v[172:175], v102 offset:32
	ds_read_b128 v[176:179], v102 offset:48
	ds_read_b128 v[180:183], v102 offset:64
	ds_read_b128 v[184:187], v102 offset:80
	ds_read_b128 v[188:191], v102 offset:96
	ds_read_b128 v[192:195], v102 offset:112
	s_movk_i32 s91, 0x80
	v_sub_u32_e32 v112, v80, v92
	v_add_u32_e32 v113, -31, v112
	v_cmp_gt_u32_e32 vcc, 0x61, v113
	s_cmp_eq_u64 vcc, exec
	s_cbranch_scc1 .Lswa_pfast_3
	s_waitcnt lgkmcnt(7)
	v_sub_f32_e32 v164, v164, v82
	v_sub_f32_e32 v165, v165, v82
	v_sub_f32_e32 v166, v166, v82
	v_exp_f32_e32 v164, v164
	v_exp_f32_e32 v165, v165
	v_exp_f32_e32 v166, v166
	v_mov_b32_e32 v196, v112
	v_add_u32_e32 v197, -1, v112
	v_add_u32_e32 v198, -2, v112
	v_cmp_gt_u32_e32 vcc, s91, v196
	v_cmp_gt_u32_e64 s[92:93], s91, v197
	v_cmp_gt_u32_e64 s[94:95], s91, v198
	v_cndmask_b32_e32 v164, 0, v164, vcc
	v_cndmask_b32_e64 v165, 0, v165, s[92:93]
	v_cndmask_b32_e64 v166, 0, v166, s[94:95]
	v_add_f32_e32 v103, v103, v164
	v_add_f32_e32 v103, v103, v165
	v_add_f32_e32 v103, v103, v166
	s_waitcnt lgkmcnt(6)
	v_sub_f32_e32 v167, v167, v82
	v_sub_f32_e32 v168, v168, v82
	v_sub_f32_e32 v169, v169, v82
	v_exp_f32_e32 v167, v167
	v_exp_f32_e32 v168, v168
	v_exp_f32_e32 v169, v169
	v_add_u32_e32 v196, -3, v112
	v_add_u32_e32 v197, -4, v112
	v_add_u32_e32 v198, -5, v112
	v_cmp_gt_u32_e32 vcc, s91, v196
	v_cmp_gt_u32_e64 s[92:93], s91, v197
	v_cmp_gt_u32_e64 s[94:95], s91, v198
	v_cndmask_b32_e32 v167, 0, v167, vcc
	v_cndmask_b32_e64 v168, 0, v168, s[92:93]
	v_cndmask_b32_e64 v169, 0, v169, s[94:95]
	v_add_f32_e32 v103, v103, v167
	v_add_f32_e32 v103, v103, v168
	v_add_f32_e32 v103, v103, v169
	s_waitcnt lgkmcnt(5)
	v_sub_f32_e32 v170, v170, v82
	v_sub_f32_e32 v171, v171, v82
	v_sub_f32_e32 v172, v172, v82
	v_exp_f32_e32 v170, v170
	v_exp_f32_e32 v171, v171
	v_exp_f32_e32 v172, v172
	v_add_u32_e32 v196, -6, v112
	v_add_u32_e32 v197, -7, v112
	v_add_u32_e32 v198, -8, v112
	v_cmp_gt_u32_e32 vcc, s91, v196
	v_cmp_gt_u32_e64 s[92:93], s91, v197
	v_cmp_gt_u32_e64 s[94:95], s91, v198
	v_cndmask_b32_e32 v170, 0, v170, vcc
	v_cndmask_b32_e64 v171, 0, v171, s[92:93]
	v_cndmask_b32_e64 v172, 0, v172, s[94:95]
	v_add_f32_e32 v103, v103, v170
	v_add_f32_e32 v103, v103, v171
	v_add_f32_e32 v103, v103, v172
	v_sub_f32_e32 v173, v173, v82
	v_sub_f32_e32 v174, v174, v82
	v_sub_f32_e32 v175, v175, v82
	v_exp_f32_e32 v173, v173
	v_exp_f32_e32 v174, v174
	v_exp_f32_e32 v175, v175
	v_add_u32_e32 v196, -9, v112
	v_add_u32_e32 v197, -10, v112
	v_add_u32_e32 v198, -11, v112
	v_cmp_gt_u32_e32 vcc, s91, v196
	v_cmp_gt_u32_e64 s[92:93], s91, v197
	v_cmp_gt_u32_e64 s[94:95], s91, v198
	v_cndmask_b32_e32 v173, 0, v173, vcc
	v_cndmask_b32_e64 v174, 0, v174, s[92:93]
	v_cndmask_b32_e64 v175, 0, v175, s[94:95]
	v_add_f32_e32 v103, v103, v173
	v_add_f32_e32 v103, v103, v174
	v_add_f32_e32 v103, v103, v175
	s_waitcnt lgkmcnt(4)
	v_sub_f32_e32 v176, v176, v82
	v_sub_f32_e32 v177, v177, v82
	v_sub_f32_e32 v178, v178, v82
	v_exp_f32_e32 v176, v176
	v_exp_f32_e32 v177, v177
	v_exp_f32_e32 v178, v178
	v_add_u32_e32 v196, -12, v112
	v_add_u32_e32 v197, -13, v112
	v_add_u32_e32 v198, -14, v112
	v_cmp_gt_u32_e32 vcc, s91, v196
	v_cmp_gt_u32_e64 s[92:93], s91, v197
	v_cmp_gt_u32_e64 s[94:95], s91, v198
	v_cndmask_b32_e32 v176, 0, v176, vcc
	v_cndmask_b32_e64 v177, 0, v177, s[92:93]
	v_cndmask_b32_e64 v178, 0, v178, s[94:95]
	v_add_f32_e32 v103, v103, v176
	v_add_f32_e32 v103, v103, v177
	v_add_f32_e32 v103, v103, v178
	s_waitcnt lgkmcnt(3)
	v_sub_f32_e32 v179, v179, v82
	v_sub_f32_e32 v180, v180, v82
	v_sub_f32_e32 v181, v181, v82
	v_exp_f32_e32 v179, v179
	v_exp_f32_e32 v180, v180
	v_exp_f32_e32 v181, v181
	v_add_u32_e32 v196, -15, v112
	v_add_u32_e32 v197, -16, v112
	v_add_u32_e32 v198, 0xffffffef, v112
	v_cmp_gt_u32_e32 vcc, s91, v196
	v_cmp_gt_u32_e64 s[92:93], s91, v197
	v_cmp_gt_u32_e64 s[94:95], s91, v198
	v_cndmask_b32_e32 v179, 0, v179, vcc
	v_cndmask_b32_e64 v180, 0, v180, s[92:93]
	v_cndmask_b32_e64 v181, 0, v181, s[94:95]
	v_add_f32_e32 v103, v103, v179
	v_add_f32_e32 v103, v103, v180
	v_add_f32_e32 v103, v103, v181
	s_waitcnt lgkmcnt(2)
; __device__ __forceinline__ unsigned pack2(float a, float b) { return (unsigned)f2bf(a) | ((unsigned)f2bf(b) << 16); }
; template <int DH, int MODE>
; __device__ void attn_item(const Params& p, int layer, int b, int blk, int head, char* smem) {
;     ...
; #pragma unroll 2
;         for (int s8 = 0; s8 < 4; ++s8) {
;           float4 va = s4[2 * s8], vb = s4[2 * s8 + 1];
;           float e[8] = {va.x, va.y, va.z, va.w, vb.x, vb.y, vb.z, vb.w};
;           float pv[8];
; #pragma unroll
;           for (int k = 0; k < 8; ++k) {
;             int kj = kjb + s8 * 8 + k;
;             bool valid = (kj > row) && (kj <= row + 128);
;             float pe = valid ? __builtin_amdgcn_exp2f(e[k] - m_new) : 0.f;
;             pv[k] = pe;
;             psum += pe;
;           }
;           uint4 ov;
;           ov.x = pack2(pv[0], pv[1]); ov.y = pack2(pv[2], pv[3]);
;           ov.z = pack2(pv[4], pv[5]); ov.w = pack2(pv[6], pv[7]);
;           *reinterpret_cast<uint4*>(prow + s8 * 16) = ov;
;         }
	v_sub_f32_e32 v182, v182, v82
	v_sub_f32_e32 v183, v183, v82
	v_sub_f32_e32 v184, v184, v82
	v_exp_f32_e32 v182, v182
	v_exp_f32_e32 v183, v183
	v_exp_f32_e32 v184, v184
	v_add_u32_e32 v196, 0xffffffee, v112
	v_add_u32_e32 v197, 0xffffffed, v112
	v_add_u32_e32 v198, 0xffffffec, v112
	v_cmp_gt_u32_e32 vcc, s91, v196
	v_cmp_gt_u32_e64 s[92:93], s91, v197
	v_cmp_gt_u32_e64 s[94:95], s91, v198
	v_cndmask_b32_e32 v182, 0, v182, vcc
	v_cndmask_b32_e64 v183, 0, v183, s[92:93]
	v_cndmask_b32_e64 v184, 0, v184, s[94:95]
	v_add_f32_e32 v103, v103, v182
	v_add_f32_e32 v103, v103, v183
	v_add_f32_e32 v103, v103, v184
	v_sub_f32_e32 v185, v185, v82
	v_sub_f32_e32 v186, v186, v82
	v_sub_f32_e32 v187, v187, v82
	v_exp_f32_e32 v185, v185
	v_exp_f32_e32 v186, v186
	v_exp_f32_e32 v187, v187
	v_add_u32_e32 v196, 0xffffffeb, v112
	v_add_u32_e32 v197, 0xffffffea, v112
	v_add_u32_e32 v198, 0xffffffe9, v112
	v_cmp_gt_u32_e32 vcc, s91, v196
	v_cmp_gt_u32_e64 s[92:93], s91, v197
	v_cmp_gt_u32_e64 s[94:95], s91, v198
	v_cndmask_b32_e32 v185, 0, v185, vcc
	v_cndmask_b32_e64 v186, 0, v186, s[92:93]
	v_cndmask_b32_e64 v187, 0, v187, s[94:95]
	v_add_f32_e32 v103, v103, v185
	v_add_f32_e32 v103, v103, v186
	v_add_f32_e32 v103, v103, v187
	s_waitcnt lgkmcnt(1)
	v_sub_f32_e32 v188, v188, v82
	v_sub_f32_e32 v189, v189, v82
	v_sub_f32_e32 v190, v190, v82
	v_exp_f32_e32 v188, v188
	v_exp_f32_e32 v189, v189
	v_exp_f32_e32 v190, v190
	v_add_u32_e32 v196, 0xffffffe8, v112
	v_add_u32_e32 v197, 0xffffffe7, v112
	v_add_u32_e32 v198, 0xffffffe6, v112
	v_cmp_gt_u32_e32 vcc, s91, v196
	v_cmp_gt_u32_e64 s[92:93], s91, v197
	v_cmp_gt_u32_e64 s[94:95], s91, v198
	v_cndmask_b32_e32 v188, 0, v188, vcc
	v_cndmask_b32_e64 v189, 0, v189, s[92:93]
	v_cndmask_b32_e64 v190, 0, v190, s[94:95]
	v_add_f32_e32 v103, v103, v188
	v_add_f32_e32 v103, v103, v189
	v_add_f32_e32 v103, v103, v190
	s_waitcnt lgkmcnt(0)
	v_sub_f32_e32 v191, v191, v82
	v_sub_f32_e32 v192, v192, v82
	v_sub_f32_e32 v193, v193, v82
	v_exp_f32_e32 v191, v191
	v_exp_f32_e32 v192, v192
	v_exp_f32_e32 v193, v193
	v_add_u32_e32 v196, 0xffffffe5, v112
	v_add_u32_e32 v197, 0xffffffe4, v112
	v_add_u32_e32 v198, 0xffffffe3, v112
	v_cmp_gt_u32_e32 vcc, s91, v196
	v_cmp_gt_u32_e64 s[92:93], s91, v197
	v_cmp_gt_u32_e64 s[94:95], s91, v198
	v_cndmask_b32_e32 v191, 0, v191, vcc
	v_cndmask_b32_e64 v192, 0, v192, s[92:93]
	v_cndmask_b32_e64 v193, 0, v193, s[94:95]
	v_add_f32_e32 v103, v103, v191
	v_add_f32_e32 v103, v103, v192
	v_add_f32_e32 v103, v103, v193
	v_sub_f32_e32 v194, v194, v82
	v_sub_f32_e32 v195, v195, v82
	v_exp_f32_e32 v194, v194
	v_exp_f32_e32 v195, v195
	v_add_u32_e32 v196, 0xffffffe2, v112
	v_add_u32_e32 v197, 0xffffffe1, v112
	v_cmp_gt_u32_e32 vcc, s91, v196
	v_cmp_gt_u32_e64 s[92:93], s91, v197
	s_nop 0
	v_cndmask_b32_e32 v194, 0, v194, vcc
	v_cndmask_b32_e64 v195, 0, v195, s[92:93]
	v_add_f32_e32 v103, v103, v194
	v_add_f32_e32 v103, v103, v195
	v_cvt_pk_bf16_f32 v104, v164, v165
	v_cvt_pk_bf16_f32 v105, v166, v167
	v_cvt_pk_bf16_f32 v106, v168, v169
	v_cvt_pk_bf16_f32 v107, v170, v171
	ds_write_b128 v101, v[104:107]
	s_nop 0
	v_cvt_pk_bf16_f32 v104, v172, v173
	v_cvt_pk_bf16_f32 v105, v174, v175
	v_cvt_pk_bf16_f32 v106, v176, v177
	v_cvt_pk_bf16_f32 v107, v178, v179
	ds_write_b128 v101, v[104:107] offset:16
	s_nop 0
	v_cvt_pk_bf16_f32 v104, v180, v181
	v_cvt_pk_bf16_f32 v105, v182, v183
	v_cvt_pk_bf16_f32 v106, v184, v185
	v_cvt_pk_bf16_f32 v107, v186, v187
	ds_write_b128 v101, v[104:107] offset:32
	s_nop 0
	v_cvt_pk_bf16_f32 v104, v188, v189
	v_cvt_pk_bf16_f32 v105, v190, v191
	v_cvt_pk_bf16_f32 v106, v192, v193
	v_cvt_pk_bf16_f32 v107, v194, v195
	ds_write_b128 v101, v[104:107] offset:48
	s_branch .Lswa_pdone_3
; __device__ __forceinline__ unsigned pack2(float a, float b) { return (unsigned)f2bf(a) | ((unsigned)f2bf(b) << 16); }
; template <int DH, int MODE>
; __device__ void attn_item(const Params& p, int layer, int b, int blk, int head, char* smem) {
;     ...
;         float m_new = fmaxf(m_run, tmax);
;         float alpha = __builtin_amdgcn_exp2f(m_run - m_new);
;         float psum = 0.f;
; #pragma unroll 2
;         for (int s8 = 0; s8 < 4; ++s8) {
;           float4 va = s4[2 * s8], vb = s4[2 * s8 + 1];
;           float e[8] = {va.x, va.y, va.z, va.w, vb.x, vb.y, vb.z, vb.w};
;           float pv[8];
; #pragma unroll
;           for (int k = 0; k < 8; ++k) {
;             int kj = kjb + s8 * 8 + k;
;             bool valid = (kj > row) && (kj <= row + 128);
;             float pe = valid ? __builtin_amdgcn_exp2f(e[k] - m_new) : 0.f;
;             pv[k] = pe;
;             psum += pe;
;           }
;           uint4 ov;
;           ov.x = pack2(pv[0], pv[1]); ov.y = pack2(pv[2], pv[3]);
;           ov.z = pack2(pv[4], pv[5]); ov.w = pack2(pv[6], pv[7]);
;           *reinterpret_cast<uint4*>(prow + s8 * 16) = ov;
;         }
;         psum += __shfl_xor(psum, 1);
;         l_run = l_run * alpha + psum;
;         m_run = m_new;
;         if (half == 0) alpha_s[row] = alpha;
.Lswa_pfast_3:
	s_waitcnt lgkmcnt(7)
	v_sub_f32_e32 v164, v164, v82
	v_sub_f32_e32 v165, v165, v82
	v_sub_f32_e32 v166, v166, v82
	v_sub_f32_e32 v167, v167, v82
	v_exp_f32_e32 v164, v164
	v_exp_f32_e32 v165, v165
	v_exp_f32_e32 v166, v166
	v_exp_f32_e32 v167, v167
	v_add_f32_e32 v103, v103, v164
	v_add_f32_e32 v103, v103, v165
	v_add_f32_e32 v103, v103, v166
	v_add_f32_e32 v103, v103, v167
	s_waitcnt lgkmcnt(6)
	v_sub_f32_e32 v168, v168, v82
	v_sub_f32_e32 v169, v169, v82
	v_sub_f32_e32 v170, v170, v82
	v_sub_f32_e32 v171, v171, v82
	v_exp_f32_e32 v168, v168
	v_exp_f32_e32 v169, v169
	v_exp_f32_e32 v170, v170
	v_exp_f32_e32 v171, v171
	v_add_f32_e32 v103, v103, v168
	v_add_f32_e32 v103, v103, v169
	v_add_f32_e32 v103, v103, v170
	v_add_f32_e32 v103, v103, v171
	s_waitcnt lgkmcnt(5)
	v_sub_f32_e32 v172, v172, v82
	v_sub_f32_e32 v173, v173, v82
	v_sub_f32_e32 v174, v174, v82
	v_sub_f32_e32 v175, v175, v82
	v_exp_f32_e32 v172, v172
	v_exp_f32_e32 v173, v173
	v_exp_f32_e32 v174, v174
	v_exp_f32_e32 v175, v175
	v_add_f32_e32 v103, v103, v172
	v_add_f32_e32 v103, v103, v173
	v_add_f32_e32 v103, v103, v174
	v_add_f32_e32 v103, v103, v175
	s_waitcnt lgkmcnt(4)
	v_sub_f32_e32 v176, v176, v82
	v_sub_f32_e32 v177, v177, v82
	v_sub_f32_e32 v178, v178, v82
	v_sub_f32_e32 v179, v179, v82
	v_exp_f32_e32 v176, v176
	v_exp_f32_e32 v177, v177
	v_exp_f32_e32 v178, v178
	v_exp_f32_e32 v179, v179
	v_add_f32_e32 v103, v103, v176
	v_add_f32_e32 v103, v103, v177
	v_add_f32_e32 v103, v103, v178
	v_add_f32_e32 v103, v103, v179
	s_waitcnt lgkmcnt(3)
	v_sub_f32_e32 v180, v180, v82
	v_sub_f32_e32 v181, v181, v82
	v_sub_f32_e32 v182, v182, v82
	v_sub_f32_e32 v183, v183, v82
	v_exp_f32_e32 v180, v180
	v_exp_f32_e32 v181, v181
	v_exp_f32_e32 v182, v182
	v_exp_f32_e32 v183, v183
	v_add_f32_e32 v103, v103, v180
	v_add_f32_e32 v103, v103, v181
	v_add_f32_e32 v103, v103, v182
	v_add_f32_e32 v103, v103, v183
	s_waitcnt lgkmcnt(2)
	v_sub_f32_e32 v184, v184, v82
	v_sub_f32_e32 v185, v185, v82
	v_sub_f32_e32 v186, v186, v82
	v_sub_f32_e32 v187, v187, v82
	v_exp_f32_e32 v184, v184
	v_exp_f32_e32 v185, v185
	v_exp_f32_e32 v186, v186
	v_exp_f32_e32 v187, v187
	v_add_f32_e32 v103, v103, v184
	v_add_f32_e32 v103, v103, v185
	v_add_f32_e32 v103, v103, v186
	v_add_f32_e32 v103, v103, v187
	s_waitcnt lgkmcnt(1)
	v_sub_f32_e32 v188, v188, v82
	v_sub_f32_e32 v189, v189, v82
	v_sub_f32_e32 v190, v190, v82
	v_sub_f32_e32 v191, v191, v82
	v_exp_f32_e32 v188, v188
	v_exp_f32_e32 v189, v189
	v_exp_f32_e32 v190, v190
	v_exp_f32_e32 v191, v191
	v_add_f32_e32 v103, v103, v188
	v_add_f32_e32 v103, v103, v189
	v_add_f32_e32 v103, v103, v190
	v_add_f32_e32 v103, v103, v191
	s_waitcnt lgkmcnt(0)
	v_sub_f32_e32 v192, v192, v82
	v_sub_f32_e32 v193, v193, v82
	v_sub_f32_e32 v194, v194, v82
	v_sub_f32_e32 v195, v195, v82
	v_exp_f32_e32 v192, v192
	v_exp_f32_e32 v193, v193
	v_exp_f32_e32 v194, v194
	v_exp_f32_e32 v195, v195
	v_add_f32_e32 v103, v103, v192
	v_add_f32_e32 v103, v103, v193
	v_add_f32_e32 v103, v103, v194
	v_add_f32_e32 v103, v103, v195
	v_cvt_pk_bf16_f32 v104, v164, v165
	v_cvt_pk_bf16_f32 v105, v166, v167
	v_cvt_pk_bf16_f32 v106, v168, v169
	v_cvt_pk_bf16_f32 v107, v170, v171
	ds_write_b128 v101, v[104:107]
	s_nop 0
	v_cvt_pk_bf16_f32 v104, v172, v173
	v_cvt_pk_bf16_f32 v105, v174, v175
	v_cvt_pk_bf16_f32 v106, v176, v177
	v_cvt_pk_bf16_f32 v107, v178, v179
	ds_write_b128 v101, v[104:107] offset:16
	s_nop 0
	v_cvt_pk_bf16_f32 v104, v180, v181
	v_cvt_pk_bf16_f32 v105, v182, v183
	v_cvt_pk_bf16_f32 v106, v184, v185
	v_cvt_pk_bf16_f32 v107, v186, v187
	ds_write_b128 v101, v[104:107] offset:32
	s_nop 0
	v_cvt_pk_bf16_f32 v104, v188, v189
	v_cvt_pk_bf16_f32 v105, v190, v191
	v_cvt_pk_bf16_f32 v106, v192, v193
	v_cvt_pk_bf16_f32 v107, v194, v195
	ds_write_b128 v101, v[104:107] offset:48
.Lswa_pdone_3:
	v_sub_f32_e32 v101, v87, v82
	ds_bpermute_b32 v87, v83, v103
	v_exp_f32_e32 v83, v101
	s_and_saveexec_b64 s[6:7], s[4:5]
	ds_write_b32 v97, v83 offset:8192
	s_or_b64 exec, exec, s[6:7]
	s_waitcnt lgkmcnt(0)
	v_add_f32_e32 v101, v103, v87
	v_fmac_f32_e32 v101, v88, v83
	v_mov_b32_e32 v87, v82
	v_mov_b32_e32 v88, v101

; template <int DH, int MODE>
; __device__ void attn_item(const Params& p, int layer, int b, int blk, int head, char* smem) {
;     ...
;         const int qpos = blk * 128 + row;
;         const int kpb = ktok + half * 32;
;         float run = 0.f;
; #pragma unroll 2
;         for (int c = 7; c >= 0; --c) {
;           float4 v = s4[c];
;           float e[4] = {v.x, v.y, v.z, v.w};
; #pragma unroll
;           for (int k = 3; k >= 0; --k) {
;             float z = e[k];
;             bool valid = (kpb + c * 4 + k) < qpos;
;             float sp = fmaxf(z, 0.f) + __builtin_amdgcn_logf(1.f + __builtin_amdgcn_exp2f(-fabsf(z)));
;             run += valid ? -sp : 0.f;
;             e[k] = z + run;
;           }
;           s4[c] = make_float4(e[0], e[1], e[2], e[3]);
;         }
.LBB0_203:
	s_or_b64 exec, exec, s[50:51]
	s_add_i32 s26, s84, 1
	s_min_i32 s50, s26, s82
	s_sub_i32 s50, s82, s50
	s_lshl_b32 s50, s50, 6
	s_ashr_i32 s51, s50, 31
	s_add_u32 s50, s50, s81
	s_addc_u32 s51, s51, 0
	s_waitcnt lgkmcnt(0)
	s_barrier
	ds_write_b16 v171, v96
	ds_write_b16_d16_hi v171, v96 offset:64
	ds_write_b16 v171, v97 offset:128
	ds_write_b16_d16_hi v171, v97 offset:192
	ds_write_b16 v171, v98 offset:256
	ds_write_b16_d16_hi v171, v98 offset:320
	ds_write_b16 v171, v99 offset:384
	ds_write_b16_d16_hi v171, v99 offset:448
	ds_write_b16 v171, v100 offset:2048
	ds_write_b16_d16_hi v171, v100 offset:2112
	ds_write_b16 v171, v101 offset:2176
	ds_write_b16_d16_hi v171, v101 offset:2240
	ds_write_b16 v171, v102 offset:2304
	ds_write_b16_d16_hi v171, v102 offset:2368
	ds_write_b16 v171, v103 offset:2432
	ds_write_b16_d16_hi v171, v103 offset:2496
	s_waitcnt vmcnt(1)
	ds_write_b16 v171, v108 offset:4096
	ds_write_b16_d16_hi v171, v108 offset:4160
	ds_write_b16 v171, v109 offset:4224
	ds_write_b16_d16_hi v171, v109 offset:4288
	ds_write_b16 v171, v110 offset:4352
	ds_write_b16_d16_hi v171, v110 offset:4416
	ds_write_b16 v171, v111 offset:4480
	ds_write_b16_d16_hi v171, v111 offset:4544
	s_waitcnt vmcnt(0)
	ds_write_b16 v171, v104 offset:6144
	ds_write_b16_d16_hi v171, v104 offset:6208
	ds_write_b16 v171, v105 offset:6272
	ds_write_b16_d16_hi v171, v105 offset:6336
	ds_write_b16 v171, v106 offset:6400
	ds_write_b16_d16_hi v171, v106 offset:6464
	ds_write_b16 v171, v107 offset:6528
	ds_write_b16_d16_hi v171, v107 offset:6592
	v_lshl_add_u64 v[96:97], s[50:51], 0, v[134:135]
	v_mad_u64_u32 v[104:105], s[52:53], v96, s55, v[140:141]
	v_or_b32_e32 v96, s50, v132
	v_mad_i32_i24 v105, v97, s55, v105
	v_mad_u64_u32 v[106:107], s[52:53], v96, s55, v[142:143]
	v_add_co_u32_e32 v96, vcc, s69, v104
	v_mad_i32_i24 v107, s51, v160, v107
	s_nop 0
	v_addc_co_u32_e32 v97, vcc, 0, v105, vcc
	v_add_co_u32_e32 v98, vcc, 0x4c000, v104
	s_nop 1
	v_addc_co_u32_e32 v99, vcc, 0, v105, vcc
	v_add_co_u32_e32 v100, vcc, 0x72000, v104
	global_load_dwordx4 v[120:123], v[96:97], off
	global_load_dwordx4 v[116:119], v[98:99], off
	v_addc_co_u32_e32 v101, vcc, 0, v105, vcc
	global_load_dwordx4 v[96:99], v[106:107], off
	global_load_dwordx4 v[124:127], v[100:101], off
	s_nop 0
	global_load_dwordx4 v[100:103], v[106:107], off offset:64
	global_load_dwordx4 v[108:111], v[106:107], off offset:128
	global_load_dwordx4 v[112:115], v[104:105], off
	s_nop 0
	global_load_dwordx4 v[104:107], v[106:107], off offset:192
	s_and_saveexec_b64 s[50:51], s[8:9]
	s_cbranch_execz .LBB0_214
	v_mov_b32_e32 v146, 0
	s_mov_b32 s52, 0
	v_mov_b32_e32 v148, v166
	ds_read_b128 v[208:211], v167 offset:112
	ds_read_b128 v[204:207], v167 offset:96
	ds_read_b128 v[200:203], v167 offset:80
	ds_read_b128 v[196:199], v167 offset:64
	ds_read_b128 v[192:195], v167 offset:48
	ds_read_b128 v[188:191], v167 offset:32
	ds_read_b128 v[184:187], v167 offset:16
	ds_read_b128 v[180:183], v167
	v_sub_u32_e32 v212, v144, v173
	v_add_u32_e32 v212, 0xffffc040, v212
	v_cmp_lt_i32_e32 vcc, 31, v212
	s_cmp_eq_u64 vcc, exec
	s_cbranch_scc1 .Lsb_p1fast_3
	s_waitcnt lgkmcnt(7)
	v_exp_f32_e64 v213, -|v211|
	v_exp_f32_e64 v214, -|v210|
	v_exp_f32_e64 v215, -|v209|
	v_max_f32_e32 v216, 0, v211
	v_max_f32_e32 v217, 0, v210
	v_max_f32_e32 v218, 0, v209
	v_add_f32_e32 v213, 1.0, v213
	v_add_f32_e32 v214, 1.0, v214
	v_add_f32_e32 v215, 1.0, v215
	v_log_f32_e32 v213, v213
	v_log_f32_e32 v214, v214
	v_log_f32_e32 v215, v215
	v_cmp_lt_i32_e32 vcc, 31, v212
	v_cmp_lt_i32_e64 s[92:93], 30, v212
	v_cmp_lt_i32_e64 s[94:95], 29, v212
	v_add_f32_e32 v213, v216, v213
	v_add_f32_e32 v214, v217, v214
	v_add_f32_e32 v215, v218, v215
	v_cndmask_b32_e64 v213, 0, -v213, vcc
	v_cndmask_b32_e64 v214, 0, -v214, s[92:93]
	v_cndmask_b32_e64 v215, 0, -v215, s[94:95]
	v_add_f32_e32 v146, v146, v213
	v_add_f32_e32 v211, v211, v146
	v_add_f32_e32 v146, v146, v214
	v_add_f32_e32 v210, v210, v146
	v_add_f32_e32 v146, v146, v215
	v_add_f32_e32 v209, v209, v146
	s_waitcnt lgkmcnt(6)
	v_exp_f32_e64 v213, -|v208|
	v_exp_f32_e64 v214, -|v207|
	v_exp_f32_e64 v215, -|v206|
	v_max_f32_e32 v216, 0, v208
	v_max_f32_e32 v217, 0, v207
	v_max_f32_e32 v218, 0, v206
	v_add_f32_e32 v213, 1.0, v213
	v_add_f32_e32 v214, 1.0, v214
	v_add_f32_e32 v215, 1.0, v215
	v_log_f32_e32 v213, v213
	v_log_f32_e32 v214, v214
	v_log_f32_e32 v215, v215
	v_cmp_lt_i32_e32 vcc, 28, v212
	v_cmp_lt_i32_e64 s[92:93], 27, v212
	v_cmp_lt_i32_e64 s[94:95], 26, v212
	v_add_f32_e32 v213, v216, v213
	v_add_f32_e32 v214, v217, v214
	v_add_f32_e32 v215, v218, v215
	v_cndmask_b32_e64 v213, 0, -v213, vcc
	v_cndmask_b32_e64 v214, 0, -v214, s[92:93]
	v_cndmask_b32_e64 v215, 0, -v215, s[94:95]
	v_add_f32_e32 v146, v146, v213
	v_add_f32_e32 v208, v208, v146
	v_add_f32_e32 v146, v146, v214
	v_add_f32_e32 v207, v207, v146
	v_add_f32_e32 v146, v146, v215
	v_add_f32_e32 v206, v206, v146
	s_waitcnt lgkmcnt(5)
; template <int DH, int MODE>
; __device__ void attn_item(const Params& p, int layer, int b, int blk, int head, char* smem) {
;     ...
; #pragma unroll 2
;         for (int c = 7; c >= 0; --c) {
;           float4 v = s4[c];
;           float e[4] = {v.x, v.y, v.z, v.w};
; #pragma unroll
;           for (int k = 3; k >= 0; --k) {
;             float z = e[k];
;             bool valid = (kpb + c * 4 + k) < qpos;
;             float sp = fmaxf(z, 0.f) + __builtin_amdgcn_logf(1.f + __builtin_amdgcn_exp2f(-fabsf(z)));
;             run += valid ? -sp : 0.f;
;             e[k] = z + run;
;           }
;           s4[c] = make_float4(e[0], e[1], e[2], e[3]);
;         }
	v_exp_f32_e64 v213, -|v205|
	v_exp_f32_e64 v214, -|v204|
	v_exp_f32_e64 v215, -|v203|
	v_max_f32_e32 v216, 0, v205
	v_max_f32_e32 v217, 0, v204
	v_max_f32_e32 v218, 0, v203
	v_add_f32_e32 v213, 1.0, v213
	v_add_f32_e32 v214, 1.0, v214
	v_add_f32_e32 v215, 1.0, v215
	v_log_f32_e32 v213, v213
	v_log_f32_e32 v214, v214
	v_log_f32_e32 v215, v215
	v_cmp_lt_i32_e32 vcc, 25, v212
	v_cmp_lt_i32_e64 s[92:93], 24, v212
	v_cmp_lt_i32_e64 s[94:95], 23, v212
	v_add_f32_e32 v213, v216, v213
	v_add_f32_e32 v214, v217, v214
	v_add_f32_e32 v215, v218, v215
	v_cndmask_b32_e64 v213, 0, -v213, vcc
	v_cndmask_b32_e64 v214, 0, -v214, s[92:93]
	v_cndmask_b32_e64 v215, 0, -v215, s[94:95]
	v_add_f32_e32 v146, v146, v213
	v_add_f32_e32 v205, v205, v146
	v_add_f32_e32 v146, v146, v214
	v_add_f32_e32 v204, v204, v146
	v_add_f32_e32 v146, v146, v215
	v_add_f32_e32 v203, v203, v146
	v_exp_f32_e64 v213, -|v202|
	v_exp_f32_e64 v214, -|v201|
	v_exp_f32_e64 v215, -|v200|
	v_max_f32_e32 v216, 0, v202
	v_max_f32_e32 v217, 0, v201
	v_max_f32_e32 v218, 0, v200
	v_add_f32_e32 v213, 1.0, v213
	v_add_f32_e32 v214, 1.0, v214
	v_add_f32_e32 v215, 1.0, v215
	v_log_f32_e32 v213, v213
	v_log_f32_e32 v214, v214
	v_log_f32_e32 v215, v215
	v_cmp_lt_i32_e32 vcc, 22, v212
	v_cmp_lt_i32_e64 s[92:93], 21, v212
	v_cmp_lt_i32_e64 s[94:95], 20, v212
	v_add_f32_e32 v213, v216, v213
	v_add_f32_e32 v214, v217, v214
	v_add_f32_e32 v215, v218, v215
	v_cndmask_b32_e64 v213, 0, -v213, vcc
	v_cndmask_b32_e64 v214, 0, -v214, s[92:93]
	v_cndmask_b32_e64 v215, 0, -v215, s[94:95]
	v_add_f32_e32 v146, v146, v213
	v_add_f32_e32 v202, v202, v146
	v_add_f32_e32 v146, v146, v214
	v_add_f32_e32 v201, v201, v146
	v_add_f32_e32 v146, v146, v215
	v_add_f32_e32 v200, v200, v146
	s_waitcnt lgkmcnt(4)
	v_exp_f32_e64 v213, -|v199|
	v_exp_f32_e64 v214, -|v198|
	v_exp_f32_e64 v215, -|v197|
	v_max_f32_e32 v216, 0, v199
	v_max_f32_e32 v217, 0, v198
	v_max_f32_e32 v218, 0, v197
	v_add_f32_e32 v213, 1.0, v213
	v_add_f32_e32 v214, 1.0, v214
	v_add_f32_e32 v215, 1.0, v215
	v_log_f32_e32 v213, v213
	v_log_f32_e32 v214, v214
	v_log_f32_e32 v215, v215
	v_cmp_lt_i32_e32 vcc, 19, v212
	v_cmp_lt_i32_e64 s[92:93], 18, v212
	v_cmp_lt_i32_e64 s[94:95], 17, v212
	v_add_f32_e32 v213, v216, v213
	v_add_f32_e32 v214, v217, v214
	v_add_f32_e32 v215, v218, v215
	v_cndmask_b32_e64 v213, 0, -v213, vcc
	v_cndmask_b32_e64 v214, 0, -v214, s[92:93]
	v_cndmask_b32_e64 v215, 0, -v215, s[94:95]
	v_add_f32_e32 v146, v146, v213
	v_add_f32_e32 v199, v199, v146
	v_add_f32_e32 v146, v146, v214
	v_add_f32_e32 v198, v198, v146
	v_add_f32_e32 v146, v146, v215
	v_add_f32_e32 v197, v197, v146
	s_waitcnt lgkmcnt(3)
	v_exp_f32_e64 v213, -|v196|
	v_exp_f32_e64 v214, -|v195|
	v_exp_f32_e64 v215, -|v194|
	v_max_f32_e32 v216, 0, v196
	v_max_f32_e32 v217, 0, v195
	v_max_f32_e32 v218, 0, v194
	v_add_f32_e32 v213, 1.0, v213
	v_add_f32_e32 v214, 1.0, v214
	v_add_f32_e32 v215, 1.0, v215
	v_log_f32_e32 v213, v213
	v_log_f32_e32 v214, v214
	v_log_f32_e32 v215, v215
	v_cmp_lt_i32_e32 vcc, 16, v212
	v_cmp_lt_i32_e64 s[92:93], 15, v212
	v_cmp_lt_i32_e64 s[94:95], 14, v212
	v_add_f32_e32 v213, v216, v213
	v_add_f32_e32 v214, v217, v214
	v_add_f32_e32 v215, v218, v215
	v_cndmask_b32_e64 v213, 0, -v213, vcc
	v_cndmask_b32_e64 v214, 0, -v214, s[92:93]
	v_cndmask_b32_e64 v215, 0, -v215, s[94:95]
	v_add_f32_e32 v146, v146, v213
	v_add_f32_e32 v196, v196, v146
	v_add_f32_e32 v146, v146, v214
	v_add_f32_e32 v195, v195, v146
	v_add_f32_e32 v146, v146, v215
	v_add_f32_e32 v194, v194, v146
	s_waitcnt lgkmcnt(2)
	v_exp_f32_e64 v213, -|v193|
	v_exp_f32_e64 v214, -|v192|
	v_exp_f32_e64 v215, -|v191|
	v_max_f32_e32 v216, 0, v193
	v_max_f32_e32 v217, 0, v192
	v_max_f32_e32 v218, 0, v191
	v_add_f32_e32 v213, 1.0, v213
	v_add_f32_e32 v214, 1.0, v214
	v_add_f32_e32 v215, 1.0, v215
	v_log_f32_e32 v213, v213
	v_log_f32_e32 v214, v214
	v_log_f32_e32 v215, v215
	v_cmp_lt_i32_e32 vcc, 13, v212
	v_cmp_lt_i32_e64 s[92:93], 12, v212
	v_cmp_lt_i32_e64 s[94:95], 11, v212
	v_add_f32_e32 v213, v216, v213
	v_add_f32_e32 v214, v217, v214
	v_add_f32_e32 v215, v218, v215
	v_cndmask_b32_e64 v213, 0, -v213, vcc
	v_cndmask_b32_e64 v214, 0, -v214, s[92:93]
	v_cndmask_b32_e64 v215, 0, -v215, s[94:95]
	v_add_f32_e32 v146, v146, v213
	v_add_f32_e32 v193, v193, v146
	v_add_f32_e32 v146, v146, v214
	v_add_f32_e32 v192, v192, v146
	v_add_f32_e32 v146, v146, v215
	v_add_f32_e32 v191, v191, v146
	v_exp_f32_e64 v213, -|v190|
	v_exp_f32_e64 v214, -|v189|
	v_exp_f32_e64 v215, -|v188|
	v_max_f32_e32 v216, 0, v190
	v_max_f32_e32 v217, 0, v189
	v_max_f32_e32 v218, 0, v188
	v_add_f32_e32 v213, 1.0, v213
	v_add_f32_e32 v214, 1.0, v214
	v_add_f32_e32 v215, 1.0, v215
	v_log_f32_e32 v213, v213
	v_log_f32_e32 v214, v214
	v_log_f32_e32 v215, v215
	v_cmp_lt_i32_e32 vcc, 10, v212
	v_cmp_lt_i32_e64 s[92:93], 9, v212
	v_cmp_lt_i32_e64 s[94:95], 8, v212
	v_add_f32_e32 v213, v216, v213
	v_add_f32_e32 v214, v217, v214
	v_add_f32_e32 v215, v218, v215
	v_cndmask_b32_e64 v213, 0, -v213, vcc
	v_cndmask_b32_e64 v214, 0, -v214, s[92:93]
	v_cndmask_b32_e64 v215, 0, -v215, s[94:95]
	v_add_f32_e32 v146, v146, v213
	v_add_f32_e32 v190, v190, v146
	v_add_f32_e32 v146, v146, v214
	v_add_f32_e32 v189, v189, v146
	v_add_f32_e32 v146, v146, v215
	v_add_f32_e32 v188, v188, v146
	s_waitcnt lgkmcnt(1)
; template <int DH, int MODE>
; __device__ void attn_item(const Params& p, int layer, int b, int blk, int head, char* smem) {
;     ...
; #pragma unroll 2
;         for (int c = 7; c >= 0; --c) {
;           float4 v = s4[c];
;           float e[4] = {v.x, v.y, v.z, v.w};
; #pragma unroll
;           for (int k = 3; k >= 0; --k) {
;             float z = e[k];
;             bool valid = (kpb + c * 4 + k) < qpos;
;             float sp = fmaxf(z, 0.f) + __builtin_amdgcn_logf(1.f + __builtin_amdgcn_exp2f(-fabsf(z)));
;             run += valid ? -sp : 0.f;
;             e[k] = z + run;
;           }
;           s4[c] = make_float4(e[0], e[1], e[2], e[3]);
;         }
	v_exp_f32_e64 v213, -|v187|
	v_exp_f32_e64 v214, -|v186|
	v_exp_f32_e64 v215, -|v185|
	v_max_f32_e32 v216, 0, v187
	v_max_f32_e32 v217, 0, v186
	v_max_f32_e32 v218, 0, v185
	v_add_f32_e32 v213, 1.0, v213
	v_add_f32_e32 v214, 1.0, v214
	v_add_f32_e32 v215, 1.0, v215
	v_log_f32_e32 v213, v213
	v_log_f32_e32 v214, v214
	v_log_f32_e32 v215, v215
	v_cmp_lt_i32_e32 vcc, 7, v212
	v_cmp_lt_i32_e64 s[92:93], 6, v212
	v_cmp_lt_i32_e64 s[94:95], 5, v212
	v_add_f32_e32 v213, v216, v213
	v_add_f32_e32 v214, v217, v214
	v_add_f32_e32 v215, v218, v215
	v_cndmask_b32_e64 v213, 0, -v213, vcc
	v_cndmask_b32_e64 v214, 0, -v214, s[92:93]
	v_cndmask_b32_e64 v215, 0, -v215, s[94:95]
	v_add_f32_e32 v146, v146, v213
	v_add_f32_e32 v187, v187, v146
	v_add_f32_e32 v146, v146, v214
	v_add_f32_e32 v186, v186, v146
	v_add_f32_e32 v146, v146, v215
	v_add_f32_e32 v185, v185, v146
	s_waitcnt lgkmcnt(0)
	v_exp_f32_e64 v213, -|v184|
	v_exp_f32_e64 v214, -|v183|
	v_exp_f32_e64 v215, -|v182|
	v_max_f32_e32 v216, 0, v184
	v_max_f32_e32 v217, 0, v183
	v_max_f32_e32 v218, 0, v182
	v_add_f32_e32 v213, 1.0, v213
	v_add_f32_e32 v214, 1.0, v214
	v_add_f32_e32 v215, 1.0, v215
	v_log_f32_e32 v213, v213
	v_log_f32_e32 v214, v214
	v_log_f32_e32 v215, v215
	v_cmp_lt_i32_e32 vcc, 4, v212
	v_cmp_lt_i32_e64 s[92:93], 3, v212
	v_cmp_lt_i32_e64 s[94:95], 2, v212
	v_add_f32_e32 v213, v216, v213
	v_add_f32_e32 v214, v217, v214
	v_add_f32_e32 v215, v218, v215
	v_cndmask_b32_e64 v213, 0, -v213, vcc
	v_cndmask_b32_e64 v214, 0, -v214, s[92:93]
	v_cndmask_b32_e64 v215, 0, -v215, s[94:95]
	v_add_f32_e32 v146, v146, v213
	v_add_f32_e32 v184, v184, v146
	v_add_f32_e32 v146, v146, v214
	v_add_f32_e32 v183, v183, v146
	v_add_f32_e32 v146, v146, v215
	v_add_f32_e32 v182, v182, v146
	v_exp_f32_e64 v213, -|v181|
	v_exp_f32_e64 v214, -|v180|
	v_max_f32_e32 v216, 0, v181
	v_max_f32_e32 v217, 0, v180
	v_add_f32_e32 v213, 1.0, v213
	v_add_f32_e32 v214, 1.0, v214
	v_log_f32_e32 v213, v213
	v_log_f32_e32 v214, v214
	v_cmp_lt_i32_e32 vcc, 1, v212
	v_cmp_lt_i32_e64 s[92:93], 0, v212
	s_nop 0
	v_add_f32_e32 v213, v216, v213
	v_add_f32_e32 v214, v217, v214
	v_cndmask_b32_e64 v213, 0, -v213, vcc
	v_cndmask_b32_e64 v214, 0, -v214, s[92:93]
	v_add_f32_e32 v146, v146, v213
	v_add_f32_e32 v181, v181, v146
	v_add_f32_e32 v146, v146, v214
	v_add_f32_e32 v180, v180, v146
	s_branch .Lsb_p1done_3
.Lsb_p1fast_3:
	s_waitcnt lgkmcnt(7)
	v_exp_f32_e64 v213, -|v211|
	v_exp_f32_e64 v214, -|v210|
	v_exp_f32_e64 v215, -|v209|
	v_max_f32_e32 v216, 0, v211
	v_max_f32_e32 v217, 0, v210
	v_max_f32_e32 v218, 0, v209
	v_add_f32_e32 v213, 1.0, v213
	v_add_f32_e32 v214, 1.0, v214
	v_add_f32_e32 v215, 1.0, v215
	v_log_f32_e32 v213, v213
	v_log_f32_e32 v214, v214
	v_log_f32_e32 v215, v215
	v_add_f32_e32 v213, v216, v213
	v_add_f32_e32 v214, v217, v214
	v_add_f32_e32 v215, v218, v215
	v_sub_f32_e32 v146, v146, v213
	v_add_f32_e32 v211, v211, v146
	v_sub_f32_e32 v146, v146, v214
	v_add_f32_e32 v210, v210, v146
	v_sub_f32_e32 v146, v146, v215
	v_add_f32_e32 v209, v209, v146
	s_waitcnt lgkmcnt(6)
	v_exp_f32_e64 v213, -|v208|
	v_exp_f32_e64 v214, -|v207|
	v_exp_f32_e64 v215, -|v206|
	v_max_f32_e32 v216, 0, v208
	v_max_f32_e32 v217, 0, v207
	v_max_f32_e32 v218, 0, v206
	v_add_f32_e32 v213, 1.0, v213
	v_add_f32_e32 v214, 1.0, v214
	v_add_f32_e32 v215, 1.0, v215
	v_log_f32_e32 v213, v213
	v_log_f32_e32 v214, v214
	v_log_f32_e32 v215, v215
	v_add_f32_e32 v213, v216, v213
	v_add_f32_e32 v214, v217, v214
	v_add_f32_e32 v215, v218, v215
	v_sub_f32_e32 v146, v146, v213
	v_add_f32_e32 v208, v208, v146
	v_sub_f32_e32 v146, v146, v214
	v_add_f32_e32 v207, v207, v146
	v_sub_f32_e32 v146, v146, v215
	v_add_f32_e32 v206, v206, v146
	s_waitcnt lgkmcnt(5)
	v_exp_f32_e64 v213, -|v205|
	v_exp_f32_e64 v214, -|v204|
	v_exp_f32_e64 v215, -|v203|
	v_max_f32_e32 v216, 0, v205
	v_max_f32_e32 v217, 0, v204
	v_max_f32_e32 v218, 0, v203
	v_add_f32_e32 v213, 1.0, v213
	v_add_f32_e32 v214, 1.0, v214
	v_add_f32_e32 v215, 1.0, v215
	v_log_f32_e32 v213, v213
	v_log_f32_e32 v214, v214
	v_log_f32_e32 v215, v215
	v_add_f32_e32 v213, v216, v213
	v_add_f32_e32 v214, v217, v214
	v_add_f32_e32 v215, v218, v215
	v_sub_f32_e32 v146, v146, v213
	v_add_f32_e32 v205, v205, v146
	v_sub_f32_e32 v146, v146, v214
	v_add_f32_e32 v204, v204, v146
	v_sub_f32_e32 v146, v146, v215
	v_add_f32_e32 v203, v203, v146
	v_exp_f32_e64 v213, -|v202|
	v_exp_f32_e64 v214, -|v201|
	v_exp_f32_e64 v215, -|v200|
	v_max_f32_e32 v216, 0, v202
	v_max_f32_e32 v217, 0, v201
	v_max_f32_e32 v218, 0, v200
	v_add_f32_e32 v213, 1.0, v213
	v_add_f32_e32 v214, 1.0, v214
	v_add_f32_e32 v215, 1.0, v215
	v_log_f32_e32 v213, v213
	v_log_f32_e32 v214, v214
	v_log_f32_e32 v215, v215
	v_add_f32_e32 v213, v216, v213
	v_add_f32_e32 v214, v217, v214
	v_add_f32_e32 v215, v218, v215
	v_sub_f32_e32 v146, v146, v213
	v_add_f32_e32 v202, v202, v146
	v_sub_f32_e32 v146, v146, v214
	v_add_f32_e32 v201, v201, v146
	v_sub_f32_e32 v146, v146, v215
	v_add_f32_e32 v200, v200, v146
	s_waitcnt lgkmcnt(4)
	v_exp_f32_e64 v213, -|v199|
	v_exp_f32_e64 v214, -|v198|
	v_exp_f32_e64 v215, -|v197|
	v_max_f32_e32 v216, 0, v199
	v_max_f32_e32 v217, 0, v198
	v_max_f32_e32 v218, 0, v197
	v_add_f32_e32 v213, 1.0, v213
	v_add_f32_e32 v214, 1.0, v214
	v_add_f32_e32 v215, 1.0, v215
	v_log_f32_e32 v213, v213
	v_log_f32_e32 v214, v214
	v_log_f32_e32 v215, v215
	v_add_f32_e32 v213, v216, v213
	v_add_f32_e32 v214, v217, v214
	v_add_f32_e32 v215, v218, v215
	v_sub_f32_e32 v146, v146, v213
	v_add_f32_e32 v199, v199, v146
	v_sub_f32_e32 v146, v146, v214
	v_add_f32_e32 v198, v198, v146
	v_sub_f32_e32 v146, v146, v215
	v_add_f32_e32 v197, v197, v146
	s_waitcnt lgkmcnt(3)
; template <int DH, int MODE>
; __device__ void attn_item(const Params& p, int layer, int b, int blk, int head, char* smem) {
;     ...
; #pragma unroll 2
;         for (int c = 7; c >= 0; --c) {
;           float4 v = s4[c];
;           float e[4] = {v.x, v.y, v.z, v.w};
; #pragma unroll
;           for (int k = 3; k >= 0; --k) {
;             float z = e[k];
;             bool valid = (kpb + c * 4 + k) < qpos;
;             float sp = fmaxf(z, 0.f) + __builtin_amdgcn_logf(1.f + __builtin_amdgcn_exp2f(-fabsf(z)));
;             run += valid ? -sp : 0.f;
;             e[k] = z + run;
;           }
;           s4[c] = make_float4(e[0], e[1], e[2], e[3]);
;         }
;         float other = __shfl_xor(run, 1);
;         float offs = m_run + (half == 0 ? other : 0.f);
; #pragma unroll 2
;         for (int s8 = 0; s8 < 4; ++s8) {
;           float4 va = s4[2 * s8], vb = s4[2 * s8 + 1];
;           float e[8] = {va.x, va.y, va.z, va.w, vb.x, vb.y, vb.z, vb.w};
;           float pv[8];
; #pragma unroll
;           for (int k = 0; k < 8; ++k) {
;             bool valid = (kpb + s8 * 8 + k) < qpos;
;             pv[k] = valid ? __builtin_amdgcn_exp2f(e[k] + offs) : 0.f;
	v_exp_f32_e64 v213, -|v196|
	v_exp_f32_e64 v214, -|v195|
	v_exp_f32_e64 v215, -|v194|
	v_max_f32_e32 v216, 0, v196
	v_max_f32_e32 v217, 0, v195
	v_max_f32_e32 v218, 0, v194
	v_add_f32_e32 v213, 1.0, v213
	v_add_f32_e32 v214, 1.0, v214
	v_add_f32_e32 v215, 1.0, v215
	v_log_f32_e32 v213, v213
	v_log_f32_e32 v214, v214
	v_log_f32_e32 v215, v215
	v_add_f32_e32 v213, v216, v213
	v_add_f32_e32 v214, v217, v214
	v_add_f32_e32 v215, v218, v215
	v_sub_f32_e32 v146, v146, v213
	v_add_f32_e32 v196, v196, v146
	v_sub_f32_e32 v146, v146, v214
	v_add_f32_e32 v195, v195, v146
	v_sub_f32_e32 v146, v146, v215
	v_add_f32_e32 v194, v194, v146
	s_waitcnt lgkmcnt(2)
	v_exp_f32_e64 v213, -|v193|
	v_exp_f32_e64 v214, -|v192|
	v_exp_f32_e64 v215, -|v191|
	v_max_f32_e32 v216, 0, v193
	v_max_f32_e32 v217, 0, v192
	v_max_f32_e32 v218, 0, v191
	v_add_f32_e32 v213, 1.0, v213
	v_add_f32_e32 v214, 1.0, v214
	v_add_f32_e32 v215, 1.0, v215
	v_log_f32_e32 v213, v213
	v_log_f32_e32 v214, v214
	v_log_f32_e32 v215, v215
	v_add_f32_e32 v213, v216, v213
	v_add_f32_e32 v214, v217, v214
	v_add_f32_e32 v215, v218, v215
	v_sub_f32_e32 v146, v146, v213
	v_add_f32_e32 v193, v193, v146
	v_sub_f32_e32 v146, v146, v214
	v_add_f32_e32 v192, v192, v146
	v_sub_f32_e32 v146, v146, v215
	v_add_f32_e32 v191, v191, v146
	v_exp_f32_e64 v213, -|v190|
	v_exp_f32_e64 v214, -|v189|
	v_exp_f32_e64 v215, -|v188|
	v_max_f32_e32 v216, 0, v190
	v_max_f32_e32 v217, 0, v189
	v_max_f32_e32 v218, 0, v188
	v_add_f32_e32 v213, 1.0, v213
	v_add_f32_e32 v214, 1.0, v214
	v_add_f32_e32 v215, 1.0, v215
	v_log_f32_e32 v213, v213
	v_log_f32_e32 v214, v214
	v_log_f32_e32 v215, v215
	v_add_f32_e32 v213, v216, v213
	v_add_f32_e32 v214, v217, v214
	v_add_f32_e32 v215, v218, v215
	v_sub_f32_e32 v146, v146, v213
	v_add_f32_e32 v190, v190, v146
	v_sub_f32_e32 v146, v146, v214
	v_add_f32_e32 v189, v189, v146
	v_sub_f32_e32 v146, v146, v215
	v_add_f32_e32 v188, v188, v146
	s_waitcnt lgkmcnt(1)
	v_exp_f32_e64 v213, -|v187|
	v_exp_f32_e64 v214, -|v186|
	v_exp_f32_e64 v215, -|v185|
	v_max_f32_e32 v216, 0, v187
	v_max_f32_e32 v217, 0, v186
	v_max_f32_e32 v218, 0, v185
	v_add_f32_e32 v213, 1.0, v213
	v_add_f32_e32 v214, 1.0, v214
	v_add_f32_e32 v215, 1.0, v215
	v_log_f32_e32 v213, v213
	v_log_f32_e32 v214, v214
	v_log_f32_e32 v215, v215
	v_add_f32_e32 v213, v216, v213
	v_add_f32_e32 v214, v217, v214
	v_add_f32_e32 v215, v218, v215
	v_sub_f32_e32 v146, v146, v213
	v_add_f32_e32 v187, v187, v146
	v_sub_f32_e32 v146, v146, v214
	v_add_f32_e32 v186, v186, v146
	v_sub_f32_e32 v146, v146, v215
	v_add_f32_e32 v185, v185, v146
	s_waitcnt lgkmcnt(0)
	v_exp_f32_e64 v213, -|v184|
	v_exp_f32_e64 v214, -|v183|
	v_exp_f32_e64 v215, -|v182|
	v_max_f32_e32 v216, 0, v184
	v_max_f32_e32 v217, 0, v183
	v_max_f32_e32 v218, 0, v182
	v_add_f32_e32 v213, 1.0, v213
	v_add_f32_e32 v214, 1.0, v214
	v_add_f32_e32 v215, 1.0, v215
	v_log_f32_e32 v213, v213
	v_log_f32_e32 v214, v214
	v_log_f32_e32 v215, v215
	v_add_f32_e32 v213, v216, v213
	v_add_f32_e32 v214, v217, v214
	v_add_f32_e32 v215, v218, v215
	v_sub_f32_e32 v146, v146, v213
	v_add_f32_e32 v184, v184, v146
	v_sub_f32_e32 v146, v146, v214
	v_add_f32_e32 v183, v183, v146
	v_sub_f32_e32 v146, v146, v215
	v_add_f32_e32 v182, v182, v146
	v_exp_f32_e64 v213, -|v181|
	v_exp_f32_e64 v214, -|v180|
	v_max_f32_e32 v216, 0, v181
	v_max_f32_e32 v217, 0, v180
	v_add_f32_e32 v213, 1.0, v213
	v_add_f32_e32 v214, 1.0, v214
	v_log_f32_e32 v213, v213
	v_log_f32_e32 v214, v214
	s_nop 0
	v_add_f32_e32 v213, v216, v213
	v_add_f32_e32 v214, v217, v214
	v_sub_f32_e32 v146, v146, v213
	v_add_f32_e32 v181, v181, v146
	v_sub_f32_e32 v146, v146, v214
	v_add_f32_e32 v180, v180, v146
.Lsb_p1done_3:
	ds_write_b128 v167, v[180:183]
	ds_write_b128 v167, v[184:187] offset:16
	ds_write_b128 v167, v[188:191] offset:32
	ds_write_b128 v167, v[192:195] offset:48
	ds_write_b128 v167, v[196:199] offset:64
	ds_write_b128 v167, v[200:203] offset:80
	ds_write_b128 v167, v[204:207] offset:96
	ds_write_b128 v167, v[208:211] offset:112
	ds_bpermute_b32 v147, v163, v146
	s_mov_b32 s85, 0
	v_mov_b32_e32 v175, v168
	v_mov_b32_e32 v177, v167
	s_waitcnt lgkmcnt(0)
	v_cndmask_b32_e64 v148, 0, v147, s[6:7]
	v_add_f32_e32 v176, v174, v148
	ds_read_b128 v[180:183], v177
	ds_read_b128 v[184:187], v177 offset:16
	ds_read_b128 v[188:191], v177 offset:32
	ds_read_b128 v[192:195], v177 offset:48
	ds_read_b128 v[196:199], v177 offset:64
	ds_read_b128 v[200:203], v177 offset:80
	ds_read_b128 v[204:207], v177 offset:96
	ds_read_b128 v[208:211], v177 offset:112
	v_sub_u32_e32 v212, v144, v173
	v_add_u32_e32 v212, 0xffffc040, v212
	v_cmp_lt_i32_e32 vcc, 31, v212
	s_cmp_eq_u64 vcc, exec
	s_cbranch_scc1 .Lsb_p2fast_3
; __device__ __forceinline__ unsigned pack2(float a, float b) { return (unsigned)f2bf(a) | ((unsigned)f2bf(b) << 16); }
; template <int DH, int MODE>
; __device__ void attn_item(const Params& p, int layer, int b, int blk, int head, char* smem) {
;     ...
; #pragma unroll 2
;         for (int s8 = 0; s8 < 4; ++s8) {
;           float4 va = s4[2 * s8], vb = s4[2 * s8 + 1];
;           float e[8] = {va.x, va.y, va.z, va.w, vb.x, vb.y, vb.z, vb.w};
;           float pv[8];
; #pragma unroll
;           for (int k = 0; k < 8; ++k) {
;             bool valid = (kpb + s8 * 8 + k) < qpos;
;             pv[k] = valid ? __builtin_amdgcn_exp2f(e[k] + offs) : 0.f;
;           }
;           uint4 ov;
;           ov.x = pack2(pv[0], pv[1]); ov.y = pack2(pv[2], pv[3]);
;           ov.z = pack2(pv[4], pv[5]); ov.w = pack2(pv[6], pv[7]);
;           *reinterpret_cast<uint4*>(prow + s8 * 16) = ov;
;         }
	s_waitcnt lgkmcnt(7)
	v_add_f32_e32 v180, v176, v180
	v_add_f32_e32 v181, v176, v181
	v_add_f32_e32 v182, v176, v182
	v_exp_f32_e32 v180, v180
	v_exp_f32_e32 v181, v181
	v_exp_f32_e32 v182, v182
	v_cmp_lt_i32_e32 vcc, 0, v212
	v_cmp_lt_i32_e64 s[92:93], 1, v212
	v_cmp_lt_i32_e64 s[94:95], 2, v212
	v_cndmask_b32_e32 v180, 0, v180, vcc
	v_cndmask_b32_e64 v181, 0, v181, s[92:93]
	v_cndmask_b32_e64 v182, 0, v182, s[94:95]
	s_waitcnt lgkmcnt(6)
	v_add_f32_e32 v183, v176, v183
	v_add_f32_e32 v184, v176, v184
	v_add_f32_e32 v185, v176, v185
	v_exp_f32_e32 v183, v183
	v_exp_f32_e32 v184, v184
	v_exp_f32_e32 v185, v185
	v_cmp_lt_i32_e32 vcc, 3, v212
	v_cmp_lt_i32_e64 s[92:93], 4, v212
	v_cmp_lt_i32_e64 s[94:95], 5, v212
	v_cndmask_b32_e32 v183, 0, v183, vcc
	v_cndmask_b32_e64 v184, 0, v184, s[92:93]
	v_cndmask_b32_e64 v185, 0, v185, s[94:95]
	s_waitcnt lgkmcnt(5)
	v_add_f32_e32 v186, v176, v186
	v_add_f32_e32 v187, v176, v187
	v_add_f32_e32 v188, v176, v188
	v_exp_f32_e32 v186, v186
	v_exp_f32_e32 v187, v187
	v_exp_f32_e32 v188, v188
	v_cmp_lt_i32_e32 vcc, 6, v212
	v_cmp_lt_i32_e64 s[92:93], 7, v212
	v_cmp_lt_i32_e64 s[94:95], 8, v212
	v_cndmask_b32_e32 v186, 0, v186, vcc
	v_cndmask_b32_e64 v187, 0, v187, s[92:93]
	v_cndmask_b32_e64 v188, 0, v188, s[94:95]
	v_add_f32_e32 v189, v176, v189
	v_add_f32_e32 v190, v176, v190
	v_add_f32_e32 v191, v176, v191
	v_exp_f32_e32 v189, v189
	v_exp_f32_e32 v190, v190
	v_exp_f32_e32 v191, v191
	v_cmp_lt_i32_e32 vcc, 9, v212
	v_cmp_lt_i32_e64 s[92:93], 10, v212
	v_cmp_lt_i32_e64 s[94:95], 11, v212
	v_cndmask_b32_e32 v189, 0, v189, vcc
	v_cndmask_b32_e64 v190, 0, v190, s[92:93]
	v_cndmask_b32_e64 v191, 0, v191, s[94:95]
	s_waitcnt lgkmcnt(4)
	v_add_f32_e32 v192, v176, v192
	v_add_f32_e32 v193, v176, v193
	v_add_f32_e32 v194, v176, v194
	v_exp_f32_e32 v192, v192
	v_exp_f32_e32 v193, v193
	v_exp_f32_e32 v194, v194
	v_cmp_lt_i32_e32 vcc, 12, v212
	v_cmp_lt_i32_e64 s[92:93], 13, v212
	v_cmp_lt_i32_e64 s[94:95], 14, v212
	v_cndmask_b32_e32 v192, 0, v192, vcc
	v_cndmask_b32_e64 v193, 0, v193, s[92:93]
	v_cndmask_b32_e64 v194, 0, v194, s[94:95]
	s_waitcnt lgkmcnt(3)
	v_add_f32_e32 v195, v176, v195
	v_add_f32_e32 v196, v176, v196
	v_add_f32_e32 v197, v176, v197
	v_exp_f32_e32 v195, v195
	v_exp_f32_e32 v196, v196
	v_exp_f32_e32 v197, v197
	v_cmp_lt_i32_e32 vcc, 15, v212
	v_cmp_lt_i32_e64 s[92:93], 16, v212
	v_cmp_lt_i32_e64 s[94:95], 17, v212
	v_cndmask_b32_e32 v195, 0, v195, vcc
	v_cndmask_b32_e64 v196, 0, v196, s[92:93]
	v_cndmask_b32_e64 v197, 0, v197, s[94:95]
	s_waitcnt lgkmcnt(2)
	v_add_f32_e32 v198, v176, v198
	v_add_f32_e32 v199, v176, v199
	v_add_f32_e32 v200, v176, v200
	v_exp_f32_e32 v198, v198
	v_exp_f32_e32 v199, v199
	v_exp_f32_e32 v200, v200
	v_cmp_lt_i32_e32 vcc, 18, v212
	v_cmp_lt_i32_e64 s[92:93], 19, v212
	v_cmp_lt_i32_e64 s[94:95], 20, v212
	v_cndmask_b32_e32 v198, 0, v198, vcc
	v_cndmask_b32_e64 v199, 0, v199, s[92:93]
	v_cndmask_b32_e64 v200, 0, v200, s[94:95]
	v_add_f32_e32 v201, v176, v201
	v_add_f32_e32 v202, v176, v202
	v_add_f32_e32 v203, v176, v203
	v_exp_f32_e32 v201, v201
	v_exp_f32_e32 v202, v202
	v_exp_f32_e32 v203, v203
	v_cmp_lt_i32_e32 vcc, 21, v212
	v_cmp_lt_i32_e64 s[92:93], 22, v212
	v_cmp_lt_i32_e64 s[94:95], 23, v212
	v_cndmask_b32_e32 v201, 0, v201, vcc
	v_cndmask_b32_e64 v202, 0, v202, s[92:93]
	v_cndmask_b32_e64 v203, 0, v203, s[94:95]
	s_waitcnt lgkmcnt(1)
	v_add_f32_e32 v204, v176, v204
	v_add_f32_e32 v205, v176, v205
	v_add_f32_e32 v206, v176, v206
	v_exp_f32_e32 v204, v204
	v_exp_f32_e32 v205, v205
	v_exp_f32_e32 v206, v206
	v_cmp_lt_i32_e32 vcc, 24, v212
	v_cmp_lt_i32_e64 s[92:93], 25, v212
	v_cmp_lt_i32_e64 s[94:95], 26, v212
	v_cndmask_b32_e32 v204, 0, v204, vcc
	v_cndmask_b32_e64 v205, 0, v205, s[92:93]
	v_cndmask_b32_e64 v206, 0, v206, s[94:95]
	s_waitcnt lgkmcnt(0)
	v_add_f32_e32 v207, v176, v207
	v_add_f32_e32 v208, v176, v208
	v_add_f32_e32 v209, v176, v209
	v_exp_f32_e32 v207, v207
	v_exp_f32_e32 v208, v208
	v_exp_f32_e32 v209, v209
	v_cmp_lt_i32_e32 vcc, 27, v212
	v_cmp_lt_i32_e64 s[92:93], 28, v212
	v_cmp_lt_i32_e64 s[94:95], 29, v212
	v_cndmask_b32_e32 v207, 0, v207, vcc
	v_cndmask_b32_e64 v208, 0, v208, s[92:93]
	v_cndmask_b32_e64 v209, 0, v209, s[94:95]
	v_add_f32_e32 v210, v176, v210
	v_add_f32_e32 v211, v176, v211
	v_exp_f32_e32 v210, v210
	v_exp_f32_e32 v211, v211
	v_cmp_lt_i32_e32 vcc, 30, v212
	v_cmp_lt_i32_e64 s[92:93], 31, v212
	s_nop 0
	v_cndmask_b32_e32 v210, 0, v210, vcc
	v_cndmask_b32_e64 v211, 0, v211, s[92:93]
	v_cvt_pk_bf16_f32 v148, v180, v181
	v_cvt_pk_bf16_f32 v149, v182, v183
	v_cvt_pk_bf16_f32 v150, v184, v185
	v_cvt_pk_bf16_f32 v151, v186, v187
	ds_write_b128 v175, v[148:151]
	s_nop 0
	v_cvt_pk_bf16_f32 v148, v188, v189
	v_cvt_pk_bf16_f32 v149, v190, v191
	v_cvt_pk_bf16_f32 v150, v192, v193
	v_cvt_pk_bf16_f32 v151, v194, v195
	ds_write_b128 v175, v[148:151] offset:16
	s_nop 0
	v_cvt_pk_bf16_f32 v148, v196, v197
	v_cvt_pk_bf16_f32 v149, v198, v199
	v_cvt_pk_bf16_f32 v150, v200, v201
	v_cvt_pk_bf16_f32 v151, v202, v203
	ds_write_b128 v175, v[148:151] offset:32
	s_nop 0
	v_cvt_pk_bf16_f32 v148, v204, v205
	v_cvt_pk_bf16_f32 v149, v206, v207
	v_cvt_pk_bf16_f32 v150, v208, v209
	v_cvt_pk_bf16_f32 v151, v210, v211
	ds_write_b128 v175, v[148:151] offset:48
	s_branch .LBB0_213
; __device__ __forceinline__ unsigned pack2(float a, float b) { return (unsigned)f2bf(a) | ((unsigned)f2bf(b) << 16); }
; template <int DH, int MODE>
; __device__ void attn_item(const Params& p, int layer, int b, int blk, int head, char* smem) {
;     ...
; #pragma unroll 2
;         for (int s8 = 0; s8 < 4; ++s8) {
;           float4 va = s4[2 * s8], vb = s4[2 * s8 + 1];
;           float e[8] = {va.x, va.y, va.z, va.w, vb.x, vb.y, vb.z, vb.w};
;           float pv[8];
; #pragma unroll
;           for (int k = 0; k < 8; ++k) {
;             bool valid = (kpb + s8 * 8 + k) < qpos;
;             pv[k] = valid ? __builtin_amdgcn_exp2f(e[k] + offs) : 0.f;
;           }
;           uint4 ov;
;           ov.x = pack2(pv[0], pv[1]); ov.y = pack2(pv[2], pv[3]);
;           ov.z = pack2(pv[4], pv[5]); ov.w = pack2(pv[6], pv[7]);
;           *reinterpret_cast<uint4*>(prow + s8 * 16) = ov;
;         }
.Lsb_p2fast_3:
	s_waitcnt lgkmcnt(7)
	v_add_f32_e32 v180, v176, v180
	v_add_f32_e32 v181, v176, v181
	v_add_f32_e32 v182, v176, v182
	v_add_f32_e32 v183, v176, v183
	v_exp_f32_e32 v180, v180
	v_exp_f32_e32 v181, v181
	v_exp_f32_e32 v182, v182
	v_exp_f32_e32 v183, v183
	s_waitcnt lgkmcnt(6)
	v_add_f32_e32 v184, v176, v184
	v_add_f32_e32 v185, v176, v185
	v_add_f32_e32 v186, v176, v186
	v_add_f32_e32 v187, v176, v187
	v_exp_f32_e32 v184, v184
	v_exp_f32_e32 v185, v185
	v_exp_f32_e32 v186, v186
	v_exp_f32_e32 v187, v187
	s_waitcnt lgkmcnt(5)
	v_add_f32_e32 v188, v176, v188
	v_add_f32_e32 v189, v176, v189
	v_add_f32_e32 v190, v176, v190
	v_add_f32_e32 v191, v176, v191
	v_exp_f32_e32 v188, v188
	v_exp_f32_e32 v189, v189
	v_exp_f32_e32 v190, v190
	v_exp_f32_e32 v191, v191
	s_waitcnt lgkmcnt(4)
	v_add_f32_e32 v192, v176, v192
	v_add_f32_e32 v193, v176, v193
	v_add_f32_e32 v194, v176, v194
	v_add_f32_e32 v195, v176, v195
	v_exp_f32_e32 v192, v192
	v_exp_f32_e32 v193, v193
	v_exp_f32_e32 v194, v194
	v_exp_f32_e32 v195, v195
	s_waitcnt lgkmcnt(3)
	v_add_f32_e32 v196, v176, v196
	v_add_f32_e32 v197, v176, v197
	v_add_f32_e32 v198, v176, v198
	v_add_f32_e32 v199, v176, v199
	v_exp_f32_e32 v196, v196
	v_exp_f32_e32 v197, v197
	v_exp_f32_e32 v198, v198
	v_exp_f32_e32 v199, v199
	s_waitcnt lgkmcnt(2)
	v_add_f32_e32 v200, v176, v200
	v_add_f32_e32 v201, v176, v201
	v_add_f32_e32 v202, v176, v202
	v_add_f32_e32 v203, v176, v203
	v_exp_f32_e32 v200, v200
	v_exp_f32_e32 v201, v201
	v_exp_f32_e32 v202, v202
	v_exp_f32_e32 v203, v203
	s_waitcnt lgkmcnt(1)
	v_add_f32_e32 v204, v176, v204
	v_add_f32_e32 v205, v176, v205
	v_add_f32_e32 v206, v176, v206
	v_add_f32_e32 v207, v176, v207
	v_exp_f32_e32 v204, v204
	v_exp_f32_e32 v205, v205
	v_exp_f32_e32 v206, v206
	v_exp_f32_e32 v207, v207
	s_waitcnt lgkmcnt(0)
	v_add_f32_e32 v208, v176, v208
	v_add_f32_e32 v209, v176, v209
	v_add_f32_e32 v210, v176, v210
	v_add_f32_e32 v211, v176, v211
	v_exp_f32_e32 v208, v208
	v_exp_f32_e32 v209, v209
	v_exp_f32_e32 v210, v210
	v_exp_f32_e32 v211, v211
	s_nop 0
	v_cvt_pk_bf16_f32 v148, v180, v181
	v_cvt_pk_bf16_f32 v149, v182, v183
	v_cvt_pk_bf16_f32 v150, v184, v185
	v_cvt_pk_bf16_f32 v151, v186, v187
	ds_write_b128 v175, v[148:151]
	s_nop 0
	v_cvt_pk_bf16_f32 v148, v188, v189
	v_cvt_pk_bf16_f32 v149, v190, v191
	v_cvt_pk_bf16_f32 v150, v192, v193
	v_cvt_pk_bf16_f32 v151, v194, v195
	ds_write_b128 v175, v[148:151] offset:16
	s_nop 0
	v_cvt_pk_bf16_f32 v148, v196, v197
	v_cvt_pk_bf16_f32 v149, v198, v199
	v_cvt_pk_bf16_f32 v150, v200, v201
	v_cvt_pk_bf16_f32 v151, v202, v203
	ds_write_b128 v175, v[148:151] offset:32
	s_nop 0
	v_cvt_pk_bf16_f32 v148, v204, v205
	v_cvt_pk_bf16_f32 v149, v206, v207
	v_cvt_pk_bf16_f32 v150, v208, v209
	v_cvt_pk_bf16_f32 v151, v210, v211
	ds_write_b128 v175, v[148:151] offset:48
	s_branch .LBB0_213

; template <int DH, int MODE>
; __device__ void attn_item(const Params& p, int layer, int b, int blk, int head, char* smem) {
;     ...
;     V_SCATTER_(vr0, 0);
;     V_SCATTER_(vr1, 1);
;     if (KCH > 2) {
;       V_SCATTER_(vr2, 2);
;       V_SCATTER_(vr3, 3);
;     }
;     KV_LOAD_(it + 1);
;     if (!wskip) {
;       float4* s4 = reinterpret_cast<float4*>(Sf + row * SSTR + half * 32);
;       char* prow = Pb + half * 8192 + row * 64;
;       if (MODE == 0) {
;         const int kjb = kj0 + half * 32;
;         float tmax = -1e30f;
; #pragma unroll
;         for (int c = 0; c < 8; ++c) {
;           float4 v = s4[c];
;           float e[4] = {v.x, v.y, v.z, v.w};
; #pragma unroll
;           for (int k = 0; k < 4; ++k) {
;             int kj = kjb + c * 4 + k;
;             bool valid = (kj > row) && (kj <= row + 128);
;             tmax = valid ? fmaxf(tmax, e[k]) : tmax;
;           }
;         }
;         tmax = fmaxf(tmax, __shfl_xor(tmax, 1));
.LBB0_487:
	s_or_b64 exec, exec, s[14:15]
	s_add_i32 s89, s89, 1
	s_min_i32 s14, s89, s87
	s_add_i32 s14, s14, s86
	s_lshl_b32 s14, s14, 6
	s_add_i32 s14, s14, s88
	s_ashr_i32 s15, s14, 31
	s_add_u32 s14, s14, s84
	s_addc_u32 s15, s15, 0
	s_waitcnt lgkmcnt(0)
	s_barrier
	ds_write_b16 v96, v48
	ds_write_b16_d16_hi v96, v48 offset:64
	ds_write_b16 v96, v49 offset:128
	ds_write_b16_d16_hi v96, v49 offset:192
	ds_write_b16 v96, v50 offset:256
	ds_write_b16_d16_hi v96, v50 offset:320
	ds_write_b16 v96, v51 offset:384
	ds_write_b16_d16_hi v96, v51 offset:448
	s_waitcnt vmcnt(0)
	ds_write_b16 v96, v52 offset:2048
	ds_write_b16_d16_hi v96, v52 offset:2112
	ds_write_b16 v96, v53 offset:2176
	ds_write_b16_d16_hi v96, v53 offset:2240
	ds_write_b16 v96, v54 offset:2304
	ds_write_b16_d16_hi v96, v54 offset:2368
	ds_write_b16 v96, v55 offset:2432
	ds_write_b16_d16_hi v96, v55 offset:2496
	v_lshl_add_u64 v[48:49], s[14:15], 0, v[66:67]
	v_mad_u64_u32 v[52:53], s[20:21], v48, s63, v[76:77]
	v_or_b32_e32 v48, s14, v72
	v_mad_i32_i24 v53, v49, s63, v53
	v_mad_u64_u32 v[54:55], s[20:21], v48, s63, v[78:79]
	v_add_co_u32_e32 v48, vcc, 0x4c000, v52
	v_mad_i32_i24 v55, s15, v160, v55
	s_nop 0
	v_addc_co_u32_e32 v49, vcc, 0, v53, vcc
	global_load_dwordx4 v[60:63], v[48:49], off
	s_nop 0
	global_load_dwordx4 v[48:51], v[54:55], off
	global_load_dwordx4 v[56:59], v[52:53], off
	s_nop 0
	global_load_dwordx4 v[52:55], v[54:55], off offset:64
	s_and_saveexec_b64 s[54:55], s[52:53]
	s_cbranch_execz .LBB0_509
	v_or_b32_e32 v101, s16, v89
	s_movk_i32 s91, 0x80
	ds_read_b128 v[164:167], v90 offset:16384
	ds_read_b128 v[168:171], v90 offset:16400
	ds_read_b128 v[172:175], v90 offset:16416
	ds_read_b128 v[176:179], v90 offset:16432
	ds_read_b128 v[180:183], v90 offset:16448
	ds_read_b128 v[184:187], v90 offset:16464
	ds_read_b128 v[188:191], v90 offset:16480
	ds_read_b128 v[192:195], v90 offset:16496
	v_sub_u32_e32 v102, v80, v101
	v_mov_b32_e32 v83, 0xf149f2ca
	v_add_u32_e32 v103, -31, v102
	v_cmp_gt_u32_e32 vcc, 0x61, v103
	s_cmp_eq_u64 vcc, exec
	s_cbranch_scc1 .Lswa_tfast_2
	v_mov_b32_e32 v196, v102
	v_add_u32_e32 v197, -1, v102
	v_add_u32_e32 v198, -2, v102
	v_cmp_gt_u32_e32 vcc, s91, v196
	v_cmp_gt_u32_e64 s[92:93], s91, v197
	v_cmp_gt_u32_e64 s[94:95], s91, v198
	s_waitcnt lgkmcnt(7)
	v_cndmask_b32_e32 v164, v83, v164, vcc
	v_cndmask_b32_e64 v165, v83, v165, s[92:93]
	v_cndmask_b32_e64 v166, v83, v166, s[94:95]
	v_add_u32_e32 v196, -3, v102
	v_add_u32_e32 v197, -4, v102
	v_add_u32_e32 v198, -5, v102
	v_cmp_gt_u32_e32 vcc, s91, v196
	v_cmp_gt_u32_e64 s[92:93], s91, v197
	v_cmp_gt_u32_e64 s[94:95], s91, v198
	s_waitcnt lgkmcnt(6)
	v_cndmask_b32_e32 v167, v83, v167, vcc
	v_cndmask_b32_e64 v168, v83, v168, s[92:93]
	v_cndmask_b32_e64 v169, v83, v169, s[94:95]
	v_add_u32_e32 v196, -6, v102
	v_add_u32_e32 v197, -7, v102
	v_add_u32_e32 v198, -8, v102
	v_cmp_gt_u32_e32 vcc, s91, v196
	v_cmp_gt_u32_e64 s[92:93], s91, v197
	v_cmp_gt_u32_e64 s[94:95], s91, v198
	s_waitcnt lgkmcnt(5)
	v_cndmask_b32_e32 v170, v83, v170, vcc
	v_cndmask_b32_e64 v171, v83, v171, s[92:93]
	v_cndmask_b32_e64 v172, v83, v172, s[94:95]
	v_add_u32_e32 v196, -9, v102
	v_add_u32_e32 v197, -10, v102
	v_add_u32_e32 v198, -11, v102
	v_cmp_gt_u32_e32 vcc, s91, v196
	v_cmp_gt_u32_e64 s[92:93], s91, v197
	v_cmp_gt_u32_e64 s[94:95], s91, v198
	v_cndmask_b32_e32 v173, v83, v173, vcc
	v_cndmask_b32_e64 v174, v83, v174, s[92:93]
	v_cndmask_b32_e64 v175, v83, v175, s[94:95]
	v_add_u32_e32 v196, -12, v102
	v_add_u32_e32 v197, -13, v102
	v_add_u32_e32 v198, -14, v102
	v_cmp_gt_u32_e32 vcc, s91, v196
	v_cmp_gt_u32_e64 s[92:93], s91, v197
	v_cmp_gt_u32_e64 s[94:95], s91, v198
	s_waitcnt lgkmcnt(4)
	v_cndmask_b32_e32 v176, v83, v176, vcc
	v_cndmask_b32_e64 v177, v83, v177, s[92:93]
	v_cndmask_b32_e64 v178, v83, v178, s[94:95]
	v_add_u32_e32 v196, -15, v102
	v_add_u32_e32 v197, -16, v102
	v_add_u32_e32 v198, 0xffffffef, v102
	v_cmp_gt_u32_e32 vcc, s91, v196
	v_cmp_gt_u32_e64 s[92:93], s91, v197
	v_cmp_gt_u32_e64 s[94:95], s91, v198
	s_waitcnt lgkmcnt(3)
	v_cndmask_b32_e32 v179, v83, v179, vcc
	v_cndmask_b32_e64 v180, v83, v180, s[92:93]
	v_cndmask_b32_e64 v181, v83, v181, s[94:95]
	v_add_u32_e32 v196, 0xffffffee, v102
	v_add_u32_e32 v197, 0xffffffed, v102
	v_add_u32_e32 v198, 0xffffffec, v102
	v_cmp_gt_u32_e32 vcc, s91, v196
	v_cmp_gt_u32_e64 s[92:93], s91, v197
	v_cmp_gt_u32_e64 s[94:95], s91, v198
	s_waitcnt lgkmcnt(2)
	v_cndmask_b32_e32 v182, v83, v182, vcc
	v_cndmask_b32_e64 v183, v83, v183, s[92:93]
	v_cndmask_b32_e64 v184, v83, v184, s[94:95]
	v_add_u32_e32 v196, 0xffffffeb, v102
	v_add_u32_e32 v197, 0xffffffea, v102
	v_add_u32_e32 v198, 0xffffffe9, v102
	v_cmp_gt_u32_e32 vcc, s91, v196
	v_cmp_gt_u32_e64 s[92:93], s91, v197
	v_cmp_gt_u32_e64 s[94:95], s91, v198
	v_cndmask_b32_e32 v185, v83, v185, vcc
	v_cndmask_b32_e64 v186, v83, v186, s[92:93]
	v_cndmask_b32_e64 v187, v83, v187, s[94:95]
	v_add_u32_e32 v196, 0xffffffe8, v102
	v_add_u32_e32 v197, 0xffffffe7, v102
	v_add_u32_e32 v198, 0xffffffe6, v102
	v_cmp_gt_u32_e32 vcc, s91, v196
	v_cmp_gt_u32_e64 s[92:93], s91, v197
	v_cmp_gt_u32_e64 s[94:95], s91, v198
	s_waitcnt lgkmcnt(1)
	v_cndmask_b32_e32 v188, v83, v188, vcc
	v_cndmask_b32_e64 v189, v83, v189, s[92:93]
	v_cndmask_b32_e64 v190, v83, v190, s[94:95]
	v_add_u32_e32 v196, 0xffffffe5, v102
	v_add_u32_e32 v197, 0xffffffe4, v102
	v_add_u32_e32 v198, 0xffffffe3, v102
	v_cmp_gt_u32_e32 vcc, s91, v196
	v_cmp_gt_u32_e64 s[92:93], s91, v197
	v_cmp_gt_u32_e64 s[94:95], s91, v198
	s_waitcnt lgkmcnt(0)
	v_cndmask_b32_e32 v191, v83, v191, vcc
	v_cndmask_b32_e64 v192, v83, v192, s[92:93]
	v_cndmask_b32_e64 v193, v83, v193, s[94:95]
	v_add_u32_e32 v196, 0xffffffe2, v102
	v_add_u32_e32 v197, 0xffffffe1, v102
	v_cmp_gt_u32_e32 vcc, s91, v196
	v_cmp_gt_u32_e64 s[92:93], s91, v197
	s_nop 0
	v_cndmask_b32_e32 v194, v83, v194, vcc
	v_cndmask_b32_e64 v195, v83, v195, s[92:93]
	v_max3_f32 v164, v164, v165, v166
	v_max3_f32 v167, v167, v168, v169
	v_max3_f32 v170, v170, v171, v172
	v_max3_f32 v173, v173, v174, v175
	v_max3_f32 v176, v176, v177, v178
	v_max3_f32 v179, v179, v180, v181
	v_max3_f32 v182, v182, v183, v184
	v_max3_f32 v185, v185, v186, v187
	v_max3_f32 v188, v188, v189, v190
	v_max3_f32 v191, v191, v192, v193
	v_max_f32_e32 v194, v194, v195
	v_max3_f32 v164, v164, v167, v170
	v_max3_f32 v173, v173, v176, v179
	v_max3_f32 v182, v182, v185, v188
	v_max_f32_e32 v191, v191, v194
	v_max3_f32 v164, v164, v173, v182
	v_max_f32_e32 v164, v164, v191
	v_mov_b32_e32 v82, v164
	s_branch .Lswa_tdone_2

; template <int DH, int MODE>
; __device__ void attn_item(const Params& p, int layer, int b, int blk, int head, char* smem) {
;     ...
;         tmax = fmaxf(tmax, __shfl_xor(tmax, 1));
;         float m_new = fmaxf(m_run, tmax);
;         float alpha = __builtin_amdgcn_exp2f(m_run - m_new);
;         float psum = 0.f;
; #pragma unroll 2
;         for (int s8 = 0; s8 < 4; ++s8) {
;           float4 va = s4[2 * s8], vb = s4[2 * s8 + 1];
;           float e[8] = {va.x, va.y, va.z, va.w, vb.x, vb.y, vb.z, vb.w};
;           float pv[8];
; #pragma unroll
;           for (int k = 0; k < 8; ++k) {
;             int kj = kjb + s8 * 8 + k;
;             bool valid = (kj > row) && (kj <= row + 128);
;             float pe = valid ? __builtin_amdgcn_exp2f(e[k] - m_new) : 0.f;
;             pv[k] = pe;
;             psum += pe;
;           }
.Lswa_tdone_2:
	v_cmp_lt_i32_e32 vcc, v157, v158
	s_mov_b32 s90, 0
	v_mov_b32_e32 v103, 0
	v_cndmask_b32_e32 v83, v156, v157, vcc
	v_lshlrev_b32_e32 v83, 2, v83
	ds_bpermute_b32 v101, v83, v82
	v_mov_b32_e32 v102, v91
	s_waitcnt lgkmcnt(0)
	v_max3_f32 v82, v87, v82, v101
	v_mov_b32_e32 v101, v93
	ds_read_b128 v[164:167], v102
	ds_read_b128 v[168:171], v102 offset:16
	ds_read_b128 v[172:175], v102 offset:32
	ds_read_b128 v[176:179], v102 offset:48
	ds_read_b128 v[180:183], v102 offset:64
	ds_read_b128 v[184:187], v102 offset:80
	ds_read_b128 v[188:191], v102 offset:96
	ds_read_b128 v[192:195], v102 offset:112
	s_movk_i32 s91, 0x80
	v_sub_u32_e32 v112, v80, v92
	v_add_u32_e32 v113, -31, v112
	v_cmp_gt_u32_e32 vcc, 0x61, v113
	s_cmp_eq_u64 vcc, exec
	s_cbranch_scc1 .Lswa_pfast_2
	s_waitcnt lgkmcnt(7)
	v_sub_f32_e32 v164, v164, v82
	v_sub_f32_e32 v165, v165, v82
	v_sub_f32_e32 v166, v166, v82
	v_exp_f32_e32 v164, v164
	v_exp_f32_e32 v165, v165
	v_exp_f32_e32 v166, v166
	v_mov_b32_e32 v196, v112
	v_add_u32_e32 v197, -1, v112
	v_add_u32_e32 v198, -2, v112
	v_cmp_gt_u32_e32 vcc, s91, v196
	v_cmp_gt_u32_e64 s[92:93], s91, v197
	v_cmp_gt_u32_e64 s[94:95], s91, v198
	v_cndmask_b32_e32 v164, 0, v164, vcc
	v_cndmask_b32_e64 v165, 0, v165, s[92:93]
	v_cndmask_b32_e64 v166, 0, v166, s[94:95]
	v_add_f32_e32 v103, v103, v164
	v_add_f32_e32 v103, v103, v165
	v_add_f32_e32 v103, v103, v166
	s_waitcnt lgkmcnt(6)
	v_sub_f32_e32 v167, v167, v82
	v_sub_f32_e32 v168, v168, v82
	v_sub_f32_e32 v169, v169, v82
	v_exp_f32_e32 v167, v167
	v_exp_f32_e32 v168, v168
	v_exp_f32_e32 v169, v169
	v_add_u32_e32 v196, -3, v112
	v_add_u32_e32 v197, -4, v112
	v_add_u32_e32 v198, -5, v112
	v_cmp_gt_u32_e32 vcc, s91, v196
	v_cmp_gt_u32_e64 s[92:93], s91, v197
	v_cmp_gt_u32_e64 s[94:95], s91, v198
	v_cndmask_b32_e32 v167, 0, v167, vcc
	v_cndmask_b32_e64 v168, 0, v168, s[92:93]
	v_cndmask_b32_e64 v169, 0, v169, s[94:95]
	v_add_f32_e32 v103, v103, v167
	v_add_f32_e32 v103, v103, v168
	v_add_f32_e32 v103, v103, v169
	s_waitcnt lgkmcnt(5)
	v_sub_f32_e32 v170, v170, v82
	v_sub_f32_e32 v171, v171, v82
	v_sub_f32_e32 v172, v172, v82
	v_exp_f32_e32 v170, v170
	v_exp_f32_e32 v171, v171
	v_exp_f32_e32 v172, v172
	v_add_u32_e32 v196, -6, v112
	v_add_u32_e32 v197, -7, v112
	v_add_u32_e32 v198, -8, v112
	v_cmp_gt_u32_e32 vcc, s91, v196
	v_cmp_gt_u32_e64 s[92:93], s91, v197
	v_cmp_gt_u32_e64 s[94:95], s91, v198
	v_cndmask_b32_e32 v170, 0, v170, vcc
	v_cndmask_b32_e64 v171, 0, v171, s[92:93]
	v_cndmask_b32_e64 v172, 0, v172, s[94:95]
	v_add_f32_e32 v103, v103, v170
	v_add_f32_e32 v103, v103, v171
	v_add_f32_e32 v103, v103, v172
	v_sub_f32_e32 v173, v173, v82
	v_sub_f32_e32 v174, v174, v82
	v_sub_f32_e32 v175, v175, v82
	v_exp_f32_e32 v173, v173
	v_exp_f32_e32 v174, v174
	v_exp_f32_e32 v175, v175
	v_add_u32_e32 v196, -9, v112
	v_add_u32_e32 v197, -10, v112
	v_add_u32_e32 v198, -11, v112
	v_cmp_gt_u32_e32 vcc, s91, v196
	v_cmp_gt_u32_e64 s[92:93], s91, v197
	v_cmp_gt_u32_e64 s[94:95], s91, v198
	v_cndmask_b32_e32 v173, 0, v173, vcc
	v_cndmask_b32_e64 v174, 0, v174, s[92:93]
	v_cndmask_b32_e64 v175, 0, v175, s[94:95]
	v_add_f32_e32 v103, v103, v173
	v_add_f32_e32 v103, v103, v174
	v_add_f32_e32 v103, v103, v175
	s_waitcnt lgkmcnt(4)
	v_sub_f32_e32 v176, v176, v82
	v_sub_f32_e32 v177, v177, v82
	v_sub_f32_e32 v178, v178, v82
	v_exp_f32_e32 v176, v176
	v_exp_f32_e32 v177, v177
	v_exp_f32_e32 v178, v178
	v_add_u32_e32 v196, -12, v112
	v_add_u32_e32 v197, -13, v112
	v_add_u32_e32 v198, -14, v112
	v_cmp_gt_u32_e32 vcc, s91, v196
	v_cmp_gt_u32_e64 s[92:93], s91, v197
	v_cmp_gt_u32_e64 s[94:95], s91, v198
	v_cndmask_b32_e32 v176, 0, v176, vcc
	v_cndmask_b32_e64 v177, 0, v177, s[92:93]
	v_cndmask_b32_e64 v178, 0, v178, s[94:95]
	v_add_f32_e32 v103, v103, v176
	v_add_f32_e32 v103, v103, v177
	v_add_f32_e32 v103, v103, v178
	s_waitcnt lgkmcnt(3)
; __device__ __forceinline__ unsigned pack2(float a, float b) { return (unsigned)f2bf(a) | ((unsigned)f2bf(b) << 16); }
; template <int DH, int MODE>
; __device__ void attn_item(const Params& p, int layer, int b, int blk, int head, char* smem) {
;     ...
; #pragma unroll 2
;         for (int s8 = 0; s8 < 4; ++s8) {
;           float4 va = s4[2 * s8], vb = s4[2 * s8 + 1];
;           float e[8] = {va.x, va.y, va.z, va.w, vb.x, vb.y, vb.z, vb.w};
;           float pv[8];
; #pragma unroll
;           for (int k = 0; k < 8; ++k) {
;             int kj = kjb + s8 * 8 + k;
;             bool valid = (kj > row) && (kj <= row + 128);
;             float pe = valid ? __builtin_amdgcn_exp2f(e[k] - m_new) : 0.f;
;             pv[k] = pe;
;             psum += pe;
;           }
;           uint4 ov;
;           ov.x = pack2(pv[0], pv[1]); ov.y = pack2(pv[2], pv[3]);
;           ov.z = pack2(pv[4], pv[5]); ov.w = pack2(pv[6], pv[7]);
;           *reinterpret_cast<uint4*>(prow + s8 * 16) = ov;
	v_sub_f32_e32 v179, v179, v82
	v_sub_f32_e32 v180, v180, v82
	v_sub_f32_e32 v181, v181, v82
	v_exp_f32_e32 v179, v179
	v_exp_f32_e32 v180, v180
	v_exp_f32_e32 v181, v181
	v_add_u32_e32 v196, -15, v112
	v_add_u32_e32 v197, -16, v112
	v_add_u32_e32 v198, 0xffffffef, v112
	v_cmp_gt_u32_e32 vcc, s91, v196
	v_cmp_gt_u32_e64 s[92:93], s91, v197
	v_cmp_gt_u32_e64 s[94:95], s91, v198
	v_cndmask_b32_e32 v179, 0, v179, vcc
	v_cndmask_b32_e64 v180, 0, v180, s[92:93]
	v_cndmask_b32_e64 v181, 0, v181, s[94:95]
	v_add_f32_e32 v103, v103, v179
	v_add_f32_e32 v103, v103, v180
	v_add_f32_e32 v103, v103, v181
	s_waitcnt lgkmcnt(2)
	v_sub_f32_e32 v182, v182, v82
	v_sub_f32_e32 v183, v183, v82
	v_sub_f32_e32 v184, v184, v82
	v_exp_f32_e32 v182, v182
	v_exp_f32_e32 v183, v183
	v_exp_f32_e32 v184, v184
	v_add_u32_e32 v196, 0xffffffee, v112
	v_add_u32_e32 v197, 0xffffffed, v112
	v_add_u32_e32 v198, 0xffffffec, v112
	v_cmp_gt_u32_e32 vcc, s91, v196
	v_cmp_gt_u32_e64 s[92:93], s91, v197
	v_cmp_gt_u32_e64 s[94:95], s91, v198
	v_cndmask_b32_e32 v182, 0, v182, vcc
	v_cndmask_b32_e64 v183, 0, v183, s[92:93]
	v_cndmask_b32_e64 v184, 0, v184, s[94:95]
	v_add_f32_e32 v103, v103, v182
	v_add_f32_e32 v103, v103, v183
	v_add_f32_e32 v103, v103, v184
	v_sub_f32_e32 v185, v185, v82
	v_sub_f32_e32 v186, v186, v82
	v_sub_f32_e32 v187, v187, v82
	v_exp_f32_e32 v185, v185
	v_exp_f32_e32 v186, v186
	v_exp_f32_e32 v187, v187
	v_add_u32_e32 v196, 0xffffffeb, v112
	v_add_u32_e32 v197, 0xffffffea, v112
	v_add_u32_e32 v198, 0xffffffe9, v112
	v_cmp_gt_u32_e32 vcc, s91, v196
	v_cmp_gt_u32_e64 s[92:93], s91, v197
	v_cmp_gt_u32_e64 s[94:95], s91, v198
	v_cndmask_b32_e32 v185, 0, v185, vcc
	v_cndmask_b32_e64 v186, 0, v186, s[92:93]
	v_cndmask_b32_e64 v187, 0, v187, s[94:95]
	v_add_f32_e32 v103, v103, v185
	v_add_f32_e32 v103, v103, v186
	v_add_f32_e32 v103, v103, v187
	s_waitcnt lgkmcnt(1)
	v_sub_f32_e32 v188, v188, v82
	v_sub_f32_e32 v189, v189, v82
	v_sub_f32_e32 v190, v190, v82
	v_exp_f32_e32 v188, v188
	v_exp_f32_e32 v189, v189
	v_exp_f32_e32 v190, v190
	v_add_u32_e32 v196, 0xffffffe8, v112
	v_add_u32_e32 v197, 0xffffffe7, v112
	v_add_u32_e32 v198, 0xffffffe6, v112
	v_cmp_gt_u32_e32 vcc, s91, v196
	v_cmp_gt_u32_e64 s[92:93], s91, v197
	v_cmp_gt_u32_e64 s[94:95], s91, v198
	v_cndmask_b32_e32 v188, 0, v188, vcc
	v_cndmask_b32_e64 v189, 0, v189, s[92:93]
	v_cndmask_b32_e64 v190, 0, v190, s[94:95]
	v_add_f32_e32 v103, v103, v188
	v_add_f32_e32 v103, v103, v189
	v_add_f32_e32 v103, v103, v190
	s_waitcnt lgkmcnt(0)
	v_sub_f32_e32 v191, v191, v82
	v_sub_f32_e32 v192, v192, v82
	v_sub_f32_e32 v193, v193, v82
	v_exp_f32_e32 v191, v191
	v_exp_f32_e32 v192, v192
	v_exp_f32_e32 v193, v193
	v_add_u32_e32 v196, 0xffffffe5, v112
	v_add_u32_e32 v197, 0xffffffe4, v112
	v_add_u32_e32 v198, 0xffffffe3, v112
	v_cmp_gt_u32_e32 vcc, s91, v196
	v_cmp_gt_u32_e64 s[92:93], s91, v197
	v_cmp_gt_u32_e64 s[94:95], s91, v198
	v_cndmask_b32_e32 v191, 0, v191, vcc
	v_cndmask_b32_e64 v192, 0, v192, s[92:93]
	v_cndmask_b32_e64 v193, 0, v193, s[94:95]
	v_add_f32_e32 v103, v103, v191
	v_add_f32_e32 v103, v103, v192
	v_add_f32_e32 v103, v103, v193
	v_sub_f32_e32 v194, v194, v82
	v_sub_f32_e32 v195, v195, v82
	v_exp_f32_e32 v194, v194
	v_exp_f32_e32 v195, v195
	v_add_u32_e32 v196, 0xffffffe2, v112
	v_add_u32_e32 v197, 0xffffffe1, v112
	v_cmp_gt_u32_e32 vcc, s91, v196
	v_cmp_gt_u32_e64 s[92:93], s91, v197
	s_nop 0
	v_cndmask_b32_e32 v194, 0, v194, vcc
	v_cndmask_b32_e64 v195, 0, v195, s[92:93]
	v_add_f32_e32 v103, v103, v194
	v_add_f32_e32 v103, v103, v195
	v_cvt_pk_bf16_f32 v104, v164, v165
	v_cvt_pk_bf16_f32 v105, v166, v167
	v_cvt_pk_bf16_f32 v106, v168, v169
	v_cvt_pk_bf16_f32 v107, v170, v171
	ds_write_b128 v101, v[104:107]
	s_nop 0
	v_cvt_pk_bf16_f32 v104, v172, v173
	v_cvt_pk_bf16_f32 v105, v174, v175
	v_cvt_pk_bf16_f32 v106, v176, v177
	v_cvt_pk_bf16_f32 v107, v178, v179
	ds_write_b128 v101, v[104:107] offset:16
	s_nop 0
	v_cvt_pk_bf16_f32 v104, v180, v181
	v_cvt_pk_bf16_f32 v105, v182, v183
	v_cvt_pk_bf16_f32 v106, v184, v185
	v_cvt_pk_bf16_f32 v107, v186, v187
	ds_write_b128 v101, v[104:107] offset:32
	s_nop 0
	v_cvt_pk_bf16_f32 v104, v188, v189
	v_cvt_pk_bf16_f32 v105, v190, v191
	v_cvt_pk_bf16_f32 v106, v192, v193
	v_cvt_pk_bf16_f32 v107, v194, v195
	ds_write_b128 v101, v[104:107] offset:48
	s_branch .Lswa_pdone_2

; __device__ __forceinline__ unsigned pack2(float a, float b) { return (unsigned)f2bf(a) | ((unsigned)f2bf(b) << 16); }
; template <int DH, int MODE>
; __device__ void attn_item(const Params& p, int layer, int b, int blk, int head, char* smem) {
;     ...
;         float alpha = __builtin_amdgcn_exp2f(m_run - m_new);
;         float psum = 0.f;
; #pragma unroll 2
;         for (int s8 = 0; s8 < 4; ++s8) {
;           float4 va = s4[2 * s8], vb = s4[2 * s8 + 1];
;           float e[8] = {va.x, va.y, va.z, va.w, vb.x, vb.y, vb.z, vb.w};
;           float pv[8];
; #pragma unroll
;           for (int k = 0; k < 8; ++k) {
;             int kj = kjb + s8 * 8 + k;
;             bool valid = (kj > row) && (kj <= row + 128);
;             float pe = valid ? __builtin_amdgcn_exp2f(e[k] - m_new) : 0.f;
;             pv[k] = pe;
;             psum += pe;
;           }
;           uint4 ov;
;           ov.x = pack2(pv[0], pv[1]); ov.y = pack2(pv[2], pv[3]);
;           ov.z = pack2(pv[4], pv[5]); ov.w = pack2(pv[6], pv[7]);
;           *reinterpret_cast<uint4*>(prow + s8 * 16) = ov;
;         }
;         psum += __shfl_xor(psum, 1);
;         l_run = l_run * alpha + psum;
;         m_run = m_new;
;         if (half == 0) alpha_s[row] = alpha;
.Lswa_pdone_2:
	v_sub_f32_e32 v101, v87, v82
	ds_bpermute_b32 v87, v83, v103
	v_exp_f32_e32 v83, v101
	s_and_saveexec_b64 s[14:15], s[12:13]
	ds_write_b32 v97, v83 offset:8192
	s_or_b64 exec, exec, s[14:15]
	s_waitcnt lgkmcnt(0)
	v_add_f32_e32 v101, v103, v87
	v_fmac_f32_e32 v101, v88, v83
	v_mov_b32_e32 v87, v82
	v_mov_b32_e32 v88, v101

; template <int DH, int MODE>
; __device__ void attn_item(const Params& p, int layer, int b, int blk, int head, char* smem) {
;     ...
;         const int qpos = blk * 128 + row;
;         const int kpb = ktok + half * 32;
;         float run = 0.f;
; #pragma unroll 2
;         for (int c = 7; c >= 0; --c) {
;           float4 v = s4[c];
;           float e[4] = {v.x, v.y, v.z, v.w};
; #pragma unroll
;           for (int k = 3; k >= 0; --k) {
;             float z = e[k];
;             bool valid = (kpb + c * 4 + k) < qpos;
;             float sp = fmaxf(z, 0.f) + __builtin_amdgcn_logf(1.f + __builtin_amdgcn_exp2f(-fabsf(z)));
;             run += valid ? -sp : 0.f;
;             e[k] = z + run;
;           }
;           s4[c] = make_float4(e[0], e[1], e[2], e[3]);
;         }
.LBB0_524:
	s_or_b64 exec, exec, s[52:53]
	s_add_i32 s36, s87, 1
	s_min_i32 s52, s36, s85
	s_sub_i32 s52, s85, s52
	s_lshl_b32 s52, s52, 6
	s_ashr_i32 s53, s52, 31
	s_add_u32 s52, s52, s84
	s_addc_u32 s53, s53, 0
	s_waitcnt lgkmcnt(0)
	s_barrier
	ds_write_b16 v171, v96
	ds_write_b16_d16_hi v171, v96 offset:64
	ds_write_b16 v171, v97 offset:128
	ds_write_b16_d16_hi v171, v97 offset:192
	ds_write_b16 v171, v98 offset:256
	ds_write_b16_d16_hi v171, v98 offset:320
	ds_write_b16 v171, v99 offset:384
	ds_write_b16_d16_hi v171, v99 offset:448
	ds_write_b16 v171, v100 offset:2048
	ds_write_b16_d16_hi v171, v100 offset:2112
	ds_write_b16 v171, v101 offset:2176
	ds_write_b16_d16_hi v171, v101 offset:2240
	ds_write_b16 v171, v102 offset:2304
	ds_write_b16_d16_hi v171, v102 offset:2368
	ds_write_b16 v171, v103 offset:2432
	ds_write_b16_d16_hi v171, v103 offset:2496
	s_waitcnt vmcnt(1)
	ds_write_b16 v171, v108 offset:4096
	ds_write_b16_d16_hi v171, v108 offset:4160
	ds_write_b16 v171, v109 offset:4224
	ds_write_b16_d16_hi v171, v109 offset:4288
	ds_write_b16 v171, v110 offset:4352
	ds_write_b16_d16_hi v171, v110 offset:4416
	ds_write_b16 v171, v111 offset:4480
	ds_write_b16_d16_hi v171, v111 offset:4544
	s_waitcnt vmcnt(0)
	ds_write_b16 v171, v104 offset:6144
	ds_write_b16_d16_hi v171, v104 offset:6208
	ds_write_b16 v171, v105 offset:6272
	ds_write_b16_d16_hi v171, v105 offset:6336
	ds_write_b16 v171, v106 offset:6400
	ds_write_b16_d16_hi v171, v106 offset:6464
	ds_write_b16 v171, v107 offset:6528
	ds_write_b16_d16_hi v171, v107 offset:6592
	v_lshl_add_u64 v[96:97], s[52:53], 0, v[134:135]
	v_mad_u64_u32 v[104:105], s[54:55], v96, s63, v[140:141]
	v_or_b32_e32 v96, s52, v132
	v_mad_i32_i24 v105, v97, s63, v105
	v_mad_u64_u32 v[106:107], s[54:55], v96, s63, v[142:143]
	v_add_co_u32_e32 v96, vcc, s71, v104
	v_mad_i32_i24 v107, s53, v160, v107
	s_nop 0
	v_addc_co_u32_e32 v97, vcc, 0, v105, vcc
	v_add_co_u32_e32 v98, vcc, 0x4c000, v104
	s_nop 1
	v_addc_co_u32_e32 v99, vcc, 0, v105, vcc
	v_add_co_u32_e32 v100, vcc, 0x72000, v104
	global_load_dwordx4 v[120:123], v[96:97], off
	global_load_dwordx4 v[116:119], v[98:99], off
	v_addc_co_u32_e32 v101, vcc, 0, v105, vcc
	global_load_dwordx4 v[96:99], v[106:107], off
	global_load_dwordx4 v[124:127], v[100:101], off
	s_nop 0
	global_load_dwordx4 v[100:103], v[106:107], off offset:64
	global_load_dwordx4 v[108:111], v[106:107], off offset:128
	global_load_dwordx4 v[112:115], v[104:105], off
	s_nop 0
	global_load_dwordx4 v[104:107], v[106:107], off offset:192
	s_and_saveexec_b64 s[52:53], s[16:17]
	s_cbranch_execz .LBB0_535
	v_mov_b32_e32 v146, 0
	s_mov_b32 s54, 0
	v_mov_b32_e32 v148, v166
	ds_read_b128 v[208:211], v167 offset:112
	ds_read_b128 v[204:207], v167 offset:96
	ds_read_b128 v[200:203], v167 offset:80
	ds_read_b128 v[196:199], v167 offset:64
	ds_read_b128 v[192:195], v167 offset:48
	ds_read_b128 v[188:191], v167 offset:32
	ds_read_b128 v[184:187], v167 offset:16
	ds_read_b128 v[180:183], v167
	v_sub_u32_e32 v212, v144, v173
	v_add_u32_e32 v212, 0xffffc040, v212
	v_cmp_lt_i32_e32 vcc, 31, v212
	s_cmp_eq_u64 vcc, exec
	s_cbranch_scc1 .Lsb_p1fast_2
	s_waitcnt lgkmcnt(7)
	v_exp_f32_e64 v213, -|v211|
	v_exp_f32_e64 v214, -|v210|
	v_exp_f32_e64 v215, -|v209|
	v_max_f32_e32 v216, 0, v211
	v_max_f32_e32 v217, 0, v210
	v_max_f32_e32 v218, 0, v209
	v_add_f32_e32 v213, 1.0, v213
	v_add_f32_e32 v214, 1.0, v214
	v_add_f32_e32 v215, 1.0, v215
	v_log_f32_e32 v213, v213
	v_log_f32_e32 v214, v214
	v_log_f32_e32 v215, v215
	v_cmp_lt_i32_e32 vcc, 31, v212
	v_cmp_lt_i32_e64 s[92:93], 30, v212
	v_cmp_lt_i32_e64 s[94:95], 29, v212
	v_add_f32_e32 v213, v216, v213
	v_add_f32_e32 v214, v217, v214
	v_add_f32_e32 v215, v218, v215
	v_cndmask_b32_e64 v213, 0, -v213, vcc
	v_cndmask_b32_e64 v214, 0, -v214, s[92:93]
	v_cndmask_b32_e64 v215, 0, -v215, s[94:95]
	v_add_f32_e32 v146, v146, v213
	v_add_f32_e32 v211, v211, v146
	v_add_f32_e32 v146, v146, v214
	v_add_f32_e32 v210, v210, v146
	v_add_f32_e32 v146, v146, v215
	v_add_f32_e32 v209, v209, v146
	s_waitcnt lgkmcnt(6)
	v_exp_f32_e64 v213, -|v208|
	v_exp_f32_e64 v214, -|v207|
	v_exp_f32_e64 v215, -|v206|
	v_max_f32_e32 v216, 0, v208
	v_max_f32_e32 v217, 0, v207
	v_max_f32_e32 v218, 0, v206
	v_add_f32_e32 v213, 1.0, v213
	v_add_f32_e32 v214, 1.0, v214
	v_add_f32_e32 v215, 1.0, v215
	v_log_f32_e32 v213, v213
	v_log_f32_e32 v214, v214
	v_log_f32_e32 v215, v215
	v_cmp_lt_i32_e32 vcc, 28, v212
	v_cmp_lt_i32_e64 s[92:93], 27, v212
	v_cmp_lt_i32_e64 s[94:95], 26, v212
	v_add_f32_e32 v213, v216, v213
	v_add_f32_e32 v214, v217, v214
	v_add_f32_e32 v215, v218, v215
	v_cndmask_b32_e64 v213, 0, -v213, vcc
	v_cndmask_b32_e64 v214, 0, -v214, s[92:93]
	v_cndmask_b32_e64 v215, 0, -v215, s[94:95]
	v_add_f32_e32 v146, v146, v213
	v_add_f32_e32 v208, v208, v146
	v_add_f32_e32 v146, v146, v214
	v_add_f32_e32 v207, v207, v146
	v_add_f32_e32 v146, v146, v215
	v_add_f32_e32 v206, v206, v146
	s_waitcnt lgkmcnt(5)
; template <int DH, int MODE>
; __device__ void attn_item(const Params& p, int layer, int b, int blk, int head, char* smem) {
;     ...
;         for (int c = 7; c >= 0; --c) {
;           float4 v = s4[c];
;           float e[4] = {v.x, v.y, v.z, v.w};
; #pragma unroll
;           for (int k = 3; k >= 0; --k) {
;             float z = e[k];
;             bool valid = (kpb + c * 4 + k) < qpos;
;             float sp = fmaxf(z, 0.f) + __builtin_amdgcn_logf(1.f + __builtin_amdgcn_exp2f(-fabsf(z)));
;             run += valid ? -sp : 0.f;
;             e[k] = z + run;
;           }
;           s4[c] = make_float4(e[0], e[1], e[2], e[3]);
;         }
	v_exp_f32_e64 v213, -|v205|
	v_exp_f32_e64 v214, -|v204|
	v_exp_f32_e64 v215, -|v203|
	v_max_f32_e32 v216, 0, v205
	v_max_f32_e32 v217, 0, v204
	v_max_f32_e32 v218, 0, v203
	v_add_f32_e32 v213, 1.0, v213
	v_add_f32_e32 v214, 1.0, v214
	v_add_f32_e32 v215, 1.0, v215
	v_log_f32_e32 v213, v213
	v_log_f32_e32 v214, v214
	v_log_f32_e32 v215, v215
	v_cmp_lt_i32_e32 vcc, 25, v212
	v_cmp_lt_i32_e64 s[92:93], 24, v212
	v_cmp_lt_i32_e64 s[94:95], 23, v212
	v_add_f32_e32 v213, v216, v213
	v_add_f32_e32 v214, v217, v214
	v_add_f32_e32 v215, v218, v215
	v_cndmask_b32_e64 v213, 0, -v213, vcc
	v_cndmask_b32_e64 v214, 0, -v214, s[92:93]
	v_cndmask_b32_e64 v215, 0, -v215, s[94:95]
	v_add_f32_e32 v146, v146, v213
	v_add_f32_e32 v205, v205, v146
	v_add_f32_e32 v146, v146, v214
	v_add_f32_e32 v204, v204, v146
	v_add_f32_e32 v146, v146, v215
	v_add_f32_e32 v203, v203, v146
	v_exp_f32_e64 v213, -|v202|
	v_exp_f32_e64 v214, -|v201|
	v_exp_f32_e64 v215, -|v200|
	v_max_f32_e32 v216, 0, v202
	v_max_f32_e32 v217, 0, v201
	v_max_f32_e32 v218, 0, v200
	v_add_f32_e32 v213, 1.0, v213
	v_add_f32_e32 v214, 1.0, v214
	v_add_f32_e32 v215, 1.0, v215
	v_log_f32_e32 v213, v213
	v_log_f32_e32 v214, v214
	v_log_f32_e32 v215, v215
	v_cmp_lt_i32_e32 vcc, 22, v212
	v_cmp_lt_i32_e64 s[92:93], 21, v212
	v_cmp_lt_i32_e64 s[94:95], 20, v212
	v_add_f32_e32 v213, v216, v213
	v_add_f32_e32 v214, v217, v214
	v_add_f32_e32 v215, v218, v215
	v_cndmask_b32_e64 v213, 0, -v213, vcc
	v_cndmask_b32_e64 v214, 0, -v214, s[92:93]
	v_cndmask_b32_e64 v215, 0, -v215, s[94:95]
	v_add_f32_e32 v146, v146, v213
	v_add_f32_e32 v202, v202, v146
	v_add_f32_e32 v146, v146, v214
	v_add_f32_e32 v201, v201, v146
	v_add_f32_e32 v146, v146, v215
	v_add_f32_e32 v200, v200, v146
	s_waitcnt lgkmcnt(4)
	v_exp_f32_e64 v213, -|v199|
	v_exp_f32_e64 v214, -|v198|
	v_exp_f32_e64 v215, -|v197|
	v_max_f32_e32 v216, 0, v199
	v_max_f32_e32 v217, 0, v198
	v_max_f32_e32 v218, 0, v197
	v_add_f32_e32 v213, 1.0, v213
	v_add_f32_e32 v214, 1.0, v214
	v_add_f32_e32 v215, 1.0, v215
	v_log_f32_e32 v213, v213
	v_log_f32_e32 v214, v214
	v_log_f32_e32 v215, v215
	v_cmp_lt_i32_e32 vcc, 19, v212
	v_cmp_lt_i32_e64 s[92:93], 18, v212
	v_cmp_lt_i32_e64 s[94:95], 17, v212
	v_add_f32_e32 v213, v216, v213
	v_add_f32_e32 v214, v217, v214
	v_add_f32_e32 v215, v218, v215
	v_cndmask_b32_e64 v213, 0, -v213, vcc
	v_cndmask_b32_e64 v214, 0, -v214, s[92:93]
	v_cndmask_b32_e64 v215, 0, -v215, s[94:95]
	v_add_f32_e32 v146, v146, v213
	v_add_f32_e32 v199, v199, v146
	v_add_f32_e32 v146, v146, v214
	v_add_f32_e32 v198, v198, v146
	v_add_f32_e32 v146, v146, v215
	v_add_f32_e32 v197, v197, v146
	s_waitcnt lgkmcnt(3)
	v_exp_f32_e64 v213, -|v196|
	v_exp_f32_e64 v214, -|v195|
	v_exp_f32_e64 v215, -|v194|
	v_max_f32_e32 v216, 0, v196
	v_max_f32_e32 v217, 0, v195
	v_max_f32_e32 v218, 0, v194
	v_add_f32_e32 v213, 1.0, v213
	v_add_f32_e32 v214, 1.0, v214
	v_add_f32_e32 v215, 1.0, v215
	v_log_f32_e32 v213, v213
	v_log_f32_e32 v214, v214
	v_log_f32_e32 v215, v215
	v_cmp_lt_i32_e32 vcc, 16, v212
	v_cmp_lt_i32_e64 s[92:93], 15, v212
	v_cmp_lt_i32_e64 s[94:95], 14, v212
	v_add_f32_e32 v213, v216, v213
	v_add_f32_e32 v214, v217, v214
	v_add_f32_e32 v215, v218, v215
	v_cndmask_b32_e64 v213, 0, -v213, vcc
	v_cndmask_b32_e64 v214, 0, -v214, s[92:93]
	v_cndmask_b32_e64 v215, 0, -v215, s[94:95]
	v_add_f32_e32 v146, v146, v213
	v_add_f32_e32 v196, v196, v146
	v_add_f32_e32 v146, v146, v214
	v_add_f32_e32 v195, v195, v146
	v_add_f32_e32 v146, v146, v215
	v_add_f32_e32 v194, v194, v146
	s_waitcnt lgkmcnt(2)
; template <int DH, int MODE>
; __device__ void attn_item(const Params& p, int layer, int b, int blk, int head, char* smem) {
;     ...
;         for (int c = 7; c >= 0; --c) {
;           float4 v = s4[c];
;           float e[4] = {v.x, v.y, v.z, v.w};
; #pragma unroll
;           for (int k = 3; k >= 0; --k) {
;             float z = e[k];
;             bool valid = (kpb + c * 4 + k) < qpos;
;             float sp = fmaxf(z, 0.f) + __builtin_amdgcn_logf(1.f + __builtin_amdgcn_exp2f(-fabsf(z)));
;             run += valid ? -sp : 0.f;
;             e[k] = z + run;
;           }
;           s4[c] = make_float4(e[0], e[1], e[2], e[3]);
;         }
	v_exp_f32_e64 v213, -|v193|
	v_exp_f32_e64 v214, -|v192|
	v_exp_f32_e64 v215, -|v191|
	v_max_f32_e32 v216, 0, v193
	v_max_f32_e32 v217, 0, v192
	v_max_f32_e32 v218, 0, v191
	v_add_f32_e32 v213, 1.0, v213
	v_add_f32_e32 v214, 1.0, v214
	v_add_f32_e32 v215, 1.0, v215
	v_log_f32_e32 v213, v213
	v_log_f32_e32 v214, v214
	v_log_f32_e32 v215, v215
	v_cmp_lt_i32_e32 vcc, 13, v212
	v_cmp_lt_i32_e64 s[92:93], 12, v212
	v_cmp_lt_i32_e64 s[94:95], 11, v212
	v_add_f32_e32 v213, v216, v213
	v_add_f32_e32 v214, v217, v214
	v_add_f32_e32 v215, v218, v215
	v_cndmask_b32_e64 v213, 0, -v213, vcc
	v_cndmask_b32_e64 v214, 0, -v214, s[92:93]
	v_cndmask_b32_e64 v215, 0, -v215, s[94:95]
	v_add_f32_e32 v146, v146, v213
	v_add_f32_e32 v193, v193, v146
	v_add_f32_e32 v146, v146, v214
	v_add_f32_e32 v192, v192, v146
	v_add_f32_e32 v146, v146, v215
	v_add_f32_e32 v191, v191, v146
	v_exp_f32_e64 v213, -|v190|
	v_exp_f32_e64 v214, -|v189|
	v_exp_f32_e64 v215, -|v188|
	v_max_f32_e32 v216, 0, v190
	v_max_f32_e32 v217, 0, v189
	v_max_f32_e32 v218, 0, v188
	v_add_f32_e32 v213, 1.0, v213
	v_add_f32_e32 v214, 1.0, v214
	v_add_f32_e32 v215, 1.0, v215
	v_log_f32_e32 v213, v213
	v_log_f32_e32 v214, v214
	v_log_f32_e32 v215, v215
	v_cmp_lt_i32_e32 vcc, 10, v212
	v_cmp_lt_i32_e64 s[92:93], 9, v212
	v_cmp_lt_i32_e64 s[94:95], 8, v212
	v_add_f32_e32 v213, v216, v213
	v_add_f32_e32 v214, v217, v214
	v_add_f32_e32 v215, v218, v215
	v_cndmask_b32_e64 v213, 0, -v213, vcc
	v_cndmask_b32_e64 v214, 0, -v214, s[92:93]
	v_cndmask_b32_e64 v215, 0, -v215, s[94:95]
	v_add_f32_e32 v146, v146, v213
	v_add_f32_e32 v190, v190, v146
	v_add_f32_e32 v146, v146, v214
	v_add_f32_e32 v189, v189, v146
	v_add_f32_e32 v146, v146, v215
	v_add_f32_e32 v188, v188, v146
	s_waitcnt lgkmcnt(1)
	v_exp_f32_e64 v213, -|v187|
	v_exp_f32_e64 v214, -|v186|
	v_exp_f32_e64 v215, -|v185|
	v_max_f32_e32 v216, 0, v187
	v_max_f32_e32 v217, 0, v186
	v_max_f32_e32 v218, 0, v185
	v_add_f32_e32 v213, 1.0, v213
	v_add_f32_e32 v214, 1.0, v214
	v_add_f32_e32 v215, 1.0, v215
	v_log_f32_e32 v213, v213
	v_log_f32_e32 v214, v214
	v_log_f32_e32 v215, v215
	v_cmp_lt_i32_e32 vcc, 7, v212
	v_cmp_lt_i32_e64 s[92:93], 6, v212
	v_cmp_lt_i32_e64 s[94:95], 5, v212
	v_add_f32_e32 v213, v216, v213
	v_add_f32_e32 v214, v217, v214
	v_add_f32_e32 v215, v218, v215
	v_cndmask_b32_e64 v213, 0, -v213, vcc
	v_cndmask_b32_e64 v214, 0, -v214, s[92:93]
	v_cndmask_b32_e64 v215, 0, -v215, s[94:95]
	v_add_f32_e32 v146, v146, v213
	v_add_f32_e32 v187, v187, v146
	v_add_f32_e32 v146, v146, v214
	v_add_f32_e32 v186, v186, v146
	v_add_f32_e32 v146, v146, v215
	v_add_f32_e32 v185, v185, v146
	s_waitcnt lgkmcnt(0)
	v_exp_f32_e64 v213, -|v184|
	v_exp_f32_e64 v214, -|v183|
	v_exp_f32_e64 v215, -|v182|
	v_max_f32_e32 v216, 0, v184
	v_max_f32_e32 v217, 0, v183
	v_max_f32_e32 v218, 0, v182
	v_add_f32_e32 v213, 1.0, v213
	v_add_f32_e32 v214, 1.0, v214
	v_add_f32_e32 v215, 1.0, v215
	v_log_f32_e32 v213, v213
	v_log_f32_e32 v214, v214
	v_log_f32_e32 v215, v215
	v_cmp_lt_i32_e32 vcc, 4, v212
	v_cmp_lt_i32_e64 s[92:93], 3, v212
	v_cmp_lt_i32_e64 s[94:95], 2, v212
	v_add_f32_e32 v213, v216, v213
	v_add_f32_e32 v214, v217, v214
	v_add_f32_e32 v215, v218, v215
	v_cndmask_b32_e64 v213, 0, -v213, vcc
	v_cndmask_b32_e64 v214, 0, -v214, s[92:93]
	v_cndmask_b32_e64 v215, 0, -v215, s[94:95]
	v_add_f32_e32 v146, v146, v213
	v_add_f32_e32 v184, v184, v146
	v_add_f32_e32 v146, v146, v214
	v_add_f32_e32 v183, v183, v146
	v_add_f32_e32 v146, v146, v215
	v_add_f32_e32 v182, v182, v146
	v_exp_f32_e64 v213, -|v181|
	v_exp_f32_e64 v214, -|v180|
	v_max_f32_e32 v216, 0, v181
	v_max_f32_e32 v217, 0, v180
	v_add_f32_e32 v213, 1.0, v213
	v_add_f32_e32 v214, 1.0, v214
	v_log_f32_e32 v213, v213
	v_log_f32_e32 v214, v214
	v_cmp_lt_i32_e32 vcc, 1, v212
	v_cmp_lt_i32_e64 s[92:93], 0, v212
	s_nop 0
	v_add_f32_e32 v213, v216, v213
	v_add_f32_e32 v214, v217, v214
	v_cndmask_b32_e64 v213, 0, -v213, vcc
	v_cndmask_b32_e64 v214, 0, -v214, s[92:93]
	v_add_f32_e32 v146, v146, v213
	v_add_f32_e32 v181, v181, v146
	v_add_f32_e32 v146, v146, v214
	v_add_f32_e32 v180, v180, v146
	s_branch .Lsb_p1done_2

; __device__ __forceinline__ unsigned pack2(float a, float b) { return (unsigned)f2bf(a) | ((unsigned)f2bf(b) << 16); }
; template <int DH, int MODE>
; __device__ void attn_item(const Params& p, int layer, int b, int blk, int head, char* smem) {
;     ...
;           s4[c] = make_float4(e[0], e[1], e[2], e[3]);
;         }
;         float other = __shfl_xor(run, 1);
;         float offs = m_run + (half == 0 ? other : 0.f);
; #pragma unroll 2
;         for (int s8 = 0; s8 < 4; ++s8) {
;           float4 va = s4[2 * s8], vb = s4[2 * s8 + 1];
;           float e[8] = {va.x, va.y, va.z, va.w, vb.x, vb.y, vb.z, vb.w};
;           float pv[8];
; #pragma unroll
;           for (int k = 0; k < 8; ++k) {
;             bool valid = (kpb + s8 * 8 + k) < qpos;
;             pv[k] = valid ? __builtin_amdgcn_exp2f(e[k] + offs) : 0.f;
;           }
;           uint4 ov;
;           ov.x = pack2(pv[0], pv[1]); ov.y = pack2(pv[2], pv[3]);
;           ov.z = pack2(pv[4], pv[5]); ov.w = pack2(pv[6], pv[7]);
;           *reinterpret_cast<uint4*>(prow + s8 * 16) = ov;
;         }
.Lsb_p1done_2:
	ds_write_b128 v167, v[180:183]
	ds_write_b128 v167, v[184:187] offset:16
	ds_write_b128 v167, v[188:191] offset:32
	ds_write_b128 v167, v[192:195] offset:48
	ds_write_b128 v167, v[196:199] offset:64
	ds_write_b128 v167, v[200:203] offset:80
	ds_write_b128 v167, v[204:207] offset:96
	ds_write_b128 v167, v[208:211] offset:112
	ds_bpermute_b32 v147, v163, v146
	s_mov_b32 s88, 0
	v_mov_b32_e32 v175, v168
	v_mov_b32_e32 v177, v167
	s_waitcnt lgkmcnt(0)
	v_cndmask_b32_e64 v148, 0, v147, s[14:15]
	v_add_f32_e32 v176, v174, v148
	ds_read_b128 v[180:183], v177
	ds_read_b128 v[184:187], v177 offset:16
	ds_read_b128 v[188:191], v177 offset:32
	ds_read_b128 v[192:195], v177 offset:48
	ds_read_b128 v[196:199], v177 offset:64
	ds_read_b128 v[200:203], v177 offset:80
	ds_read_b128 v[204:207], v177 offset:96
	ds_read_b128 v[208:211], v177 offset:112
	v_sub_u32_e32 v212, v144, v173
	v_add_u32_e32 v212, 0xffffc040, v212
	v_cmp_lt_i32_e32 vcc, 31, v212
	s_cmp_eq_u64 vcc, exec
	s_cbranch_scc1 .Lsb_p2fast_2
	s_waitcnt lgkmcnt(7)
	v_add_f32_e32 v180, v176, v180
	v_add_f32_e32 v181, v176, v181
	v_add_f32_e32 v182, v176, v182
	v_exp_f32_e32 v180, v180
	v_exp_f32_e32 v181, v181
	v_exp_f32_e32 v182, v182
	v_cmp_lt_i32_e32 vcc, 0, v212
	v_cmp_lt_i32_e64 s[92:93], 1, v212
	v_cmp_lt_i32_e64 s[94:95], 2, v212
	v_cndmask_b32_e32 v180, 0, v180, vcc
	v_cndmask_b32_e64 v181, 0, v181, s[92:93]
	v_cndmask_b32_e64 v182, 0, v182, s[94:95]
	s_waitcnt lgkmcnt(6)
	v_add_f32_e32 v183, v176, v183
	v_add_f32_e32 v184, v176, v184
	v_add_f32_e32 v185, v176, v185
	v_exp_f32_e32 v183, v183
	v_exp_f32_e32 v184, v184
	v_exp_f32_e32 v185, v185
	v_cmp_lt_i32_e32 vcc, 3, v212
	v_cmp_lt_i32_e64 s[92:93], 4, v212
	v_cmp_lt_i32_e64 s[94:95], 5, v212
	v_cndmask_b32_e32 v183, 0, v183, vcc
	v_cndmask_b32_e64 v184, 0, v184, s[92:93]
	v_cndmask_b32_e64 v185, 0, v185, s[94:95]
	s_waitcnt lgkmcnt(5)
	v_add_f32_e32 v186, v176, v186
	v_add_f32_e32 v187, v176, v187
	v_add_f32_e32 v188, v176, v188
	v_exp_f32_e32 v186, v186
	v_exp_f32_e32 v187, v187
	v_exp_f32_e32 v188, v188
	v_cmp_lt_i32_e32 vcc, 6, v212
	v_cmp_lt_i32_e64 s[92:93], 7, v212
	v_cmp_lt_i32_e64 s[94:95], 8, v212
	v_cndmask_b32_e32 v186, 0, v186, vcc
	v_cndmask_b32_e64 v187, 0, v187, s[92:93]
	v_cndmask_b32_e64 v188, 0, v188, s[94:95]
	v_add_f32_e32 v189, v176, v189
	v_add_f32_e32 v190, v176, v190
	v_add_f32_e32 v191, v176, v191
	v_exp_f32_e32 v189, v189
	v_exp_f32_e32 v190, v190
	v_exp_f32_e32 v191, v191
	v_cmp_lt_i32_e32 vcc, 9, v212
	v_cmp_lt_i32_e64 s[92:93], 10, v212
	v_cmp_lt_i32_e64 s[94:95], 11, v212
	v_cndmask_b32_e32 v189, 0, v189, vcc
	v_cndmask_b32_e64 v190, 0, v190, s[92:93]
	v_cndmask_b32_e64 v191, 0, v191, s[94:95]
	s_waitcnt lgkmcnt(4)
	v_add_f32_e32 v192, v176, v192
	v_add_f32_e32 v193, v176, v193
	v_add_f32_e32 v194, v176, v194
	v_exp_f32_e32 v192, v192
	v_exp_f32_e32 v193, v193
	v_exp_f32_e32 v194, v194
	v_cmp_lt_i32_e32 vcc, 12, v212
	v_cmp_lt_i32_e64 s[92:93], 13, v212
	v_cmp_lt_i32_e64 s[94:95], 14, v212
	v_cndmask_b32_e32 v192, 0, v192, vcc
	v_cndmask_b32_e64 v193, 0, v193, s[92:93]
	v_cndmask_b32_e64 v194, 0, v194, s[94:95]
	s_waitcnt lgkmcnt(3)
	v_add_f32_e32 v195, v176, v195
	v_add_f32_e32 v196, v176, v196
	v_add_f32_e32 v197, v176, v197
	v_exp_f32_e32 v195, v195
	v_exp_f32_e32 v196, v196
	v_exp_f32_e32 v197, v197
	v_cmp_lt_i32_e32 vcc, 15, v212
	v_cmp_lt_i32_e64 s[92:93], 16, v212
	v_cmp_lt_i32_e64 s[94:95], 17, v212
	v_cndmask_b32_e32 v195, 0, v195, vcc
	v_cndmask_b32_e64 v196, 0, v196, s[92:93]
	v_cndmask_b32_e64 v197, 0, v197, s[94:95]
	s_waitcnt lgkmcnt(2)
	v_add_f32_e32 v198, v176, v198
	v_add_f32_e32 v199, v176, v199
	v_add_f32_e32 v200, v176, v200
	v_exp_f32_e32 v198, v198
	v_exp_f32_e32 v199, v199
	v_exp_f32_e32 v200, v200
	v_cmp_lt_i32_e32 vcc, 18, v212
	v_cmp_lt_i32_e64 s[92:93], 19, v212
	v_cmp_lt_i32_e64 s[94:95], 20, v212
	v_cndmask_b32_e32 v198, 0, v198, vcc
	v_cndmask_b32_e64 v199, 0, v199, s[92:93]
	v_cndmask_b32_e64 v200, 0, v200, s[94:95]
	v_add_f32_e32 v201, v176, v201
	v_add_f32_e32 v202, v176, v202
	v_add_f32_e32 v203, v176, v203
	v_exp_f32_e32 v201, v201
	v_exp_f32_e32 v202, v202
	v_exp_f32_e32 v203, v203
	v_cmp_lt_i32_e32 vcc, 21, v212
	v_cmp_lt_i32_e64 s[92:93], 22, v212
	v_cmp_lt_i32_e64 s[94:95], 23, v212
	v_cndmask_b32_e32 v201, 0, v201, vcc
	v_cndmask_b32_e64 v202, 0, v202, s[92:93]
	v_cndmask_b32_e64 v203, 0, v203, s[94:95]
	s_waitcnt lgkmcnt(1)
	v_add_f32_e32 v204, v176, v204
	v_add_f32_e32 v205, v176, v205
	v_add_f32_e32 v206, v176, v206
	v_exp_f32_e32 v204, v204
	v_exp_f32_e32 v205, v205
	v_exp_f32_e32 v206, v206
	v_cmp_lt_i32_e32 vcc, 24, v212
	v_cmp_lt_i32_e64 s[92:93], 25, v212
	v_cmp_lt_i32_e64 s[94:95], 26, v212
	v_cndmask_b32_e32 v204, 0, v204, vcc
	v_cndmask_b32_e64 v205, 0, v205, s[92:93]
	v_cndmask_b32_e64 v206, 0, v206, s[94:95]
	s_waitcnt lgkmcnt(0)
	v_add_f32_e32 v207, v176, v207
	v_add_f32_e32 v208, v176, v208
	v_add_f32_e32 v209, v176, v209
	v_exp_f32_e32 v207, v207
	v_exp_f32_e32 v208, v208
	v_exp_f32_e32 v209, v209
	v_cmp_lt_i32_e32 vcc, 27, v212
	v_cmp_lt_i32_e64 s[92:93], 28, v212
	v_cmp_lt_i32_e64 s[94:95], 29, v212
	v_cndmask_b32_e32 v207, 0, v207, vcc
	v_cndmask_b32_e64 v208, 0, v208, s[92:93]
	v_cndmask_b32_e64 v209, 0, v209, s[94:95]
	v_add_f32_e32 v210, v176, v210
	v_add_f32_e32 v211, v176, v211
	v_exp_f32_e32 v210, v210
	v_exp_f32_e32 v211, v211
	v_cmp_lt_i32_e32 vcc, 30, v212
	v_cmp_lt_i32_e64 s[92:93], 31, v212
	s_nop 0
	v_cndmask_b32_e32 v210, 0, v210, vcc
	v_cndmask_b32_e64 v211, 0, v211, s[92:93]
	v_cvt_pk_bf16_f32 v148, v180, v181
	v_cvt_pk_bf16_f32 v149, v182, v183
	v_cvt_pk_bf16_f32 v150, v184, v185
	v_cvt_pk_bf16_f32 v151, v186, v187
	ds_write_b128 v175, v[148:151]
	s_nop 0
	v_cvt_pk_bf16_f32 v148, v188, v189
	v_cvt_pk_bf16_f32 v149, v190, v191
	v_cvt_pk_bf16_f32 v150, v192, v193
	v_cvt_pk_bf16_f32 v151, v194, v195
	ds_write_b128 v175, v[148:151] offset:16
	s_nop 0
	v_cvt_pk_bf16_f32 v148, v196, v197
	v_cvt_pk_bf16_f32 v149, v198, v199
	v_cvt_pk_bf16_f32 v150, v200, v201
	v_cvt_pk_bf16_f32 v151, v202, v203
	ds_write_b128 v175, v[148:151] offset:32
	s_nop 0
	v_cvt_pk_bf16_f32 v148, v204, v205
	v_cvt_pk_bf16_f32 v149, v206, v207
	v_cvt_pk_bf16_f32 v150, v208, v209
	v_cvt_pk_bf16_f32 v151, v210, v211
	ds_write_b128 v175, v[148:151] offset:48
	s_branch .LBB0_534

; template <int DH, int MODE>
; __device__ void attn_item(const Params& p, int layer, int b, int blk, int head, char* smem) {
;     ...
;         const int kjb = kj0 + half * 32;
;         float tmax = -1e30f;
; #pragma unroll
;         for (int c = 0; c < 8; ++c) {
;           float4 v = s4[c];
;           float e[4] = {v.x, v.y, v.z, v.w};
; #pragma unroll
;           for (int k = 0; k < 4; ++k) {
;             int kj = kjb + c * 4 + k;
;             bool valid = (kj > row) && (kj <= row + 128);
;             tmax = valid ? fmaxf(tmax, e[k]) : tmax;
;           }
;         }
.LBB0_808:
	s_or_b64 exec, exec, s[14:15]
	s_add_i32 s89, s89, 1
	s_min_i32 s14, s89, s87
	s_add_i32 s14, s14, s86
	s_lshl_b32 s14, s14, 6
	s_add_i32 s14, s14, s88
	s_ashr_i32 s15, s14, 31
	s_add_u32 s14, s14, s84
	s_addc_u32 s15, s15, 0
	s_waitcnt lgkmcnt(0)
	s_barrier
	ds_write_b16 v96, v48
	ds_write_b16_d16_hi v96, v48 offset:64
	ds_write_b16 v96, v49 offset:128
	ds_write_b16_d16_hi v96, v49 offset:192
	ds_write_b16 v96, v50 offset:256
	ds_write_b16_d16_hi v96, v50 offset:320
	ds_write_b16 v96, v51 offset:384
	ds_write_b16_d16_hi v96, v51 offset:448
	s_waitcnt vmcnt(0)
	ds_write_b16 v96, v52 offset:2048
	ds_write_b16_d16_hi v96, v52 offset:2112
	ds_write_b16 v96, v53 offset:2176
	ds_write_b16_d16_hi v96, v53 offset:2240
	ds_write_b16 v96, v54 offset:2304
	ds_write_b16_d16_hi v96, v54 offset:2368
	ds_write_b16 v96, v55 offset:2432
	ds_write_b16_d16_hi v96, v55 offset:2496
	v_lshl_add_u64 v[48:49], s[14:15], 0, v[66:67]
	v_mad_u64_u32 v[52:53], s[20:21], v48, s45, v[76:77]
	v_or_b32_e32 v48, s14, v72
	v_mad_i32_i24 v53, v49, s45, v53
	v_mad_u64_u32 v[54:55], s[20:21], v48, s45, v[78:79]
	v_add_co_u32_e32 v48, vcc, 0x4c000, v52
	v_mad_i32_i24 v55, s15, v160, v55
	s_nop 0
	v_addc_co_u32_e32 v49, vcc, 0, v53, vcc
	global_load_dwordx4 v[60:63], v[48:49], off
	s_nop 0
	global_load_dwordx4 v[48:51], v[54:55], off
	global_load_dwordx4 v[56:59], v[52:53], off
	s_nop 0
	global_load_dwordx4 v[52:55], v[54:55], off offset:64
	s_and_saveexec_b64 s[52:53], s[50:51]
	s_cbranch_execz .LBB0_830
	v_or_b32_e32 v101, s16, v89
	s_movk_i32 s91, 0x80
	ds_read_b128 v[164:167], v90 offset:16384
	ds_read_b128 v[168:171], v90 offset:16400
	ds_read_b128 v[172:175], v90 offset:16416
	ds_read_b128 v[176:179], v90 offset:16432
	ds_read_b128 v[180:183], v90 offset:16448
	ds_read_b128 v[184:187], v90 offset:16464
	ds_read_b128 v[188:191], v90 offset:16480
	ds_read_b128 v[192:195], v90 offset:16496
	v_sub_u32_e32 v102, v80, v101
	v_mov_b32_e32 v83, 0xf149f2ca
	v_add_u32_e32 v103, -31, v102
	v_cmp_gt_u32_e32 vcc, 0x61, v103
	s_cmp_eq_u64 vcc, exec
	s_cbranch_scc1 .Lswa_tfast_1
	v_mov_b32_e32 v196, v102
	v_add_u32_e32 v197, -1, v102
	v_add_u32_e32 v198, -2, v102
	v_cmp_gt_u32_e32 vcc, s91, v196
	v_cmp_gt_u32_e64 s[92:93], s91, v197
	v_cmp_gt_u32_e64 s[94:95], s91, v198
	s_waitcnt lgkmcnt(7)
	v_cndmask_b32_e32 v164, v83, v164, vcc
	v_cndmask_b32_e64 v165, v83, v165, s[92:93]
	v_cndmask_b32_e64 v166, v83, v166, s[94:95]
	v_add_u32_e32 v196, -3, v102
	v_add_u32_e32 v197, -4, v102
	v_add_u32_e32 v198, -5, v102
	v_cmp_gt_u32_e32 vcc, s91, v196
	v_cmp_gt_u32_e64 s[92:93], s91, v197
	v_cmp_gt_u32_e64 s[94:95], s91, v198
	s_waitcnt lgkmcnt(6)
	v_cndmask_b32_e32 v167, v83, v167, vcc
	v_cndmask_b32_e64 v168, v83, v168, s[92:93]
	v_cndmask_b32_e64 v169, v83, v169, s[94:95]
	v_add_u32_e32 v196, -6, v102
	v_add_u32_e32 v197, -7, v102
	v_add_u32_e32 v198, -8, v102
	v_cmp_gt_u32_e32 vcc, s91, v196
	v_cmp_gt_u32_e64 s[92:93], s91, v197
	v_cmp_gt_u32_e64 s[94:95], s91, v198
	s_waitcnt lgkmcnt(5)
	v_cndmask_b32_e32 v170, v83, v170, vcc
	v_cndmask_b32_e64 v171, v83, v171, s[92:93]
	v_cndmask_b32_e64 v172, v83, v172, s[94:95]
	v_add_u32_e32 v196, -9, v102
	v_add_u32_e32 v197, -10, v102
	v_add_u32_e32 v198, -11, v102
	v_cmp_gt_u32_e32 vcc, s91, v196
	v_cmp_gt_u32_e64 s[92:93], s91, v197
	v_cmp_gt_u32_e64 s[94:95], s91, v198
	v_cndmask_b32_e32 v173, v83, v173, vcc
	v_cndmask_b32_e64 v174, v83, v174, s[92:93]
	v_cndmask_b32_e64 v175, v83, v175, s[94:95]
	v_add_u32_e32 v196, -12, v102
	v_add_u32_e32 v197, -13, v102
	v_add_u32_e32 v198, -14, v102
	v_cmp_gt_u32_e32 vcc, s91, v196
	v_cmp_gt_u32_e64 s[92:93], s91, v197
	v_cmp_gt_u32_e64 s[94:95], s91, v198
	s_waitcnt lgkmcnt(4)
	v_cndmask_b32_e32 v176, v83, v176, vcc
	v_cndmask_b32_e64 v177, v83, v177, s[92:93]
	v_cndmask_b32_e64 v178, v83, v178, s[94:95]
	v_add_u32_e32 v196, -15, v102
	v_add_u32_e32 v197, -16, v102
	v_add_u32_e32 v198, 0xffffffef, v102
	v_cmp_gt_u32_e32 vcc, s91, v196
	v_cmp_gt_u32_e64 s[92:93], s91, v197
	v_cmp_gt_u32_e64 s[94:95], s91, v198
	s_waitcnt lgkmcnt(3)
	v_cndmask_b32_e32 v179, v83, v179, vcc
	v_cndmask_b32_e64 v180, v83, v180, s[92:93]
	v_cndmask_b32_e64 v181, v83, v181, s[94:95]
	v_add_u32_e32 v196, 0xffffffee, v102
	v_add_u32_e32 v197, 0xffffffed, v102
	v_add_u32_e32 v198, 0xffffffec, v102
	v_cmp_gt_u32_e32 vcc, s91, v196
	v_cmp_gt_u32_e64 s[92:93], s91, v197
	v_cmp_gt_u32_e64 s[94:95], s91, v198
	s_waitcnt lgkmcnt(2)
	v_cndmask_b32_e32 v182, v83, v182, vcc
	v_cndmask_b32_e64 v183, v83, v183, s[92:93]
	v_cndmask_b32_e64 v184, v83, v184, s[94:95]
	v_add_u32_e32 v196, 0xffffffeb, v102
	v_add_u32_e32 v197, 0xffffffea, v102
	v_add_u32_e32 v198, 0xffffffe9, v102
	v_cmp_gt_u32_e32 vcc, s91, v196
	v_cmp_gt_u32_e64 s[92:93], s91, v197
	v_cmp_gt_u32_e64 s[94:95], s91, v198
	v_cndmask_b32_e32 v185, v83, v185, vcc
	v_cndmask_b32_e64 v186, v83, v186, s[92:93]
	v_cndmask_b32_e64 v187, v83, v187, s[94:95]
	v_add_u32_e32 v196, 0xffffffe8, v102
	v_add_u32_e32 v197, 0xffffffe7, v102
	v_add_u32_e32 v198, 0xffffffe6, v102
	v_cmp_gt_u32_e32 vcc, s91, v196
	v_cmp_gt_u32_e64 s[92:93], s91, v197
	v_cmp_gt_u32_e64 s[94:95], s91, v198
	s_waitcnt lgkmcnt(1)
	v_cndmask_b32_e32 v188, v83, v188, vcc
	v_cndmask_b32_e64 v189, v83, v189, s[92:93]
	v_cndmask_b32_e64 v190, v83, v190, s[94:95]
	v_add_u32_e32 v196, 0xffffffe5, v102
	v_add_u32_e32 v197, 0xffffffe4, v102
	v_add_u32_e32 v198, 0xffffffe3, v102
	v_cmp_gt_u32_e32 vcc, s91, v196
	v_cmp_gt_u32_e64 s[92:93], s91, v197
	v_cmp_gt_u32_e64 s[94:95], s91, v198
	s_waitcnt lgkmcnt(0)
	v_cndmask_b32_e32 v191, v83, v191, vcc
	v_cndmask_b32_e64 v192, v83, v192, s[92:93]
	v_cndmask_b32_e64 v193, v83, v193, s[94:95]
	v_add_u32_e32 v196, 0xffffffe2, v102
	v_add_u32_e32 v197, 0xffffffe1, v102
	v_cmp_gt_u32_e32 vcc, s91, v196
	v_cmp_gt_u32_e64 s[92:93], s91, v197
	s_nop 0
	v_cndmask_b32_e32 v194, v83, v194, vcc
	v_cndmask_b32_e64 v195, v83, v195, s[92:93]
	v_max3_f32 v164, v164, v165, v166
	v_max3_f32 v167, v167, v168, v169
	v_max3_f32 v170, v170, v171, v172
	v_max3_f32 v173, v173, v174, v175
	v_max3_f32 v176, v176, v177, v178
	v_max3_f32 v179, v179, v180, v181
	v_max3_f32 v182, v182, v183, v184
	v_max3_f32 v185, v185, v186, v187
	v_max3_f32 v188, v188, v189, v190
	v_max3_f32 v191, v191, v192, v193
	v_max_f32_e32 v194, v194, v195
	v_max3_f32 v164, v164, v167, v170
	v_max3_f32 v173, v173, v176, v179
	v_max3_f32 v182, v182, v185, v188
	v_max_f32_e32 v191, v191, v194
	v_max3_f32 v164, v164, v173, v182
	v_max_f32_e32 v164, v164, v191
	v_mov_b32_e32 v82, v164
	s_branch .Lswa_tdone_1

; template <int DH, int MODE>
; __device__ void attn_item(const Params& p, int layer, int b, int blk, int head, char* smem) {
;     ...
;         const int qpos = blk * 128 + row;
;         const int kpb = ktok + half * 32;
;         float run = 0.f;
; #pragma unroll 2
;         for (int c = 7; c >= 0; --c) {
;           float4 v = s4[c];
;           float e[4] = {v.x, v.y, v.z, v.w};
; #pragma unroll
;           for (int k = 3; k >= 0; --k) {
;             float z = e[k];
;             bool valid = (kpb + c * 4 + k) < qpos;
;             float sp = fmaxf(z, 0.f) + __builtin_amdgcn_logf(1.f + __builtin_amdgcn_exp2f(-fabsf(z)));
;             run += valid ? -sp : 0.f;
;             e[k] = z + run;
;           }
;           s4[c] = make_float4(e[0], e[1], e[2], e[3]);
;         }
.LBB0_845:
	s_or_b64 exec, exec, s[50:51]
	s_add_i32 s36, s87, 1
	s_min_i32 s50, s36, s85
	s_sub_i32 s50, s85, s50
	s_lshl_b32 s50, s50, 6
	s_ashr_i32 s51, s50, 31
	s_add_u32 s50, s50, s84
	s_addc_u32 s51, s51, 0
	s_waitcnt lgkmcnt(0)
	s_barrier
	ds_write_b16 v171, v96
	ds_write_b16_d16_hi v171, v96 offset:64
	ds_write_b16 v171, v97 offset:128
	ds_write_b16_d16_hi v171, v97 offset:192
	ds_write_b16 v171, v98 offset:256
	ds_write_b16_d16_hi v171, v98 offset:320
	ds_write_b16 v171, v99 offset:384
	ds_write_b16_d16_hi v171, v99 offset:448
	ds_write_b16 v171, v100 offset:2048
	ds_write_b16_d16_hi v171, v100 offset:2112
	ds_write_b16 v171, v101 offset:2176
	ds_write_b16_d16_hi v171, v101 offset:2240
	ds_write_b16 v171, v102 offset:2304
	ds_write_b16_d16_hi v171, v102 offset:2368
	ds_write_b16 v171, v103 offset:2432
	ds_write_b16_d16_hi v171, v103 offset:2496
	s_waitcnt vmcnt(1)
	ds_write_b16 v171, v108 offset:4096
	ds_write_b16_d16_hi v171, v108 offset:4160
	ds_write_b16 v171, v109 offset:4224
	ds_write_b16_d16_hi v171, v109 offset:4288
	ds_write_b16 v171, v110 offset:4352
	ds_write_b16_d16_hi v171, v110 offset:4416
	ds_write_b16 v171, v111 offset:4480
	ds_write_b16_d16_hi v171, v111 offset:4544
	s_waitcnt vmcnt(0)
	ds_write_b16 v171, v104 offset:6144
	ds_write_b16_d16_hi v171, v104 offset:6208
	ds_write_b16 v171, v105 offset:6272
	ds_write_b16_d16_hi v171, v105 offset:6336
	ds_write_b16 v171, v106 offset:6400
	ds_write_b16_d16_hi v171, v106 offset:6464
	ds_write_b16 v171, v107 offset:6528
	ds_write_b16_d16_hi v171, v107 offset:6592
	v_lshl_add_u64 v[96:97], s[50:51], 0, v[134:135]
	v_mad_u64_u32 v[104:105], s[52:53], v96, s45, v[140:141]
	v_or_b32_e32 v96, s50, v132
	v_mad_i32_i24 v105, v97, s45, v105
	v_mad_u64_u32 v[106:107], s[52:53], v96, s45, v[142:143]
	v_add_co_u32_e32 v96, vcc, s71, v104
	v_mad_i32_i24 v107, s51, v160, v107
	s_nop 0
	v_addc_co_u32_e32 v97, vcc, 0, v105, vcc
	v_add_co_u32_e32 v98, vcc, 0x4c000, v104
	s_nop 1
	v_addc_co_u32_e32 v99, vcc, 0, v105, vcc
	v_add_co_u32_e32 v100, vcc, 0x72000, v104
	global_load_dwordx4 v[120:123], v[96:97], off
	global_load_dwordx4 v[116:119], v[98:99], off
	v_addc_co_u32_e32 v101, vcc, 0, v105, vcc
	global_load_dwordx4 v[96:99], v[106:107], off
	global_load_dwordx4 v[124:127], v[100:101], off
	s_nop 0
	global_load_dwordx4 v[100:103], v[106:107], off offset:64
	global_load_dwordx4 v[108:111], v[106:107], off offset:128
	global_load_dwordx4 v[112:115], v[104:105], off
	s_nop 0
	global_load_dwordx4 v[104:107], v[106:107], off offset:192
	s_and_saveexec_b64 s[50:51], s[16:17]
	s_cbranch_execz .LBB0_856
	v_mov_b32_e32 v146, 0
	s_mov_b32 s52, 0
	v_mov_b32_e32 v148, v166
	ds_read_b128 v[208:211], v167 offset:112
	ds_read_b128 v[204:207], v167 offset:96
	ds_read_b128 v[200:203], v167 offset:80
	ds_read_b128 v[196:199], v167 offset:64
	ds_read_b128 v[192:195], v167 offset:48
	ds_read_b128 v[188:191], v167 offset:32
	ds_read_b128 v[184:187], v167 offset:16
	ds_read_b128 v[180:183], v167
	v_sub_u32_e32 v212, v144, v173
	v_add_u32_e32 v212, 0xffffc040, v212
	v_cmp_lt_i32_e32 vcc, 31, v212
	s_cmp_eq_u64 vcc, exec
	s_cbranch_scc1 .Lsb_p1fast_1
	s_waitcnt lgkmcnt(7)
	v_exp_f32_e64 v213, -|v211|
	v_exp_f32_e64 v214, -|v210|
	v_exp_f32_e64 v215, -|v209|
	v_max_f32_e32 v216, 0, v211
	v_max_f32_e32 v217, 0, v210
	v_max_f32_e32 v218, 0, v209
	v_add_f32_e32 v213, 1.0, v213
	v_add_f32_e32 v214, 1.0, v214
	v_add_f32_e32 v215, 1.0, v215
	v_log_f32_e32 v213, v213
	v_log_f32_e32 v214, v214
	v_log_f32_e32 v215, v215
	v_cmp_lt_i32_e32 vcc, 31, v212
	v_cmp_lt_i32_e64 s[92:93], 30, v212
	v_cmp_lt_i32_e64 s[94:95], 29, v212
	v_add_f32_e32 v213, v216, v213
	v_add_f32_e32 v214, v217, v214
	v_add_f32_e32 v215, v218, v215
	v_cndmask_b32_e64 v213, 0, -v213, vcc
	v_cndmask_b32_e64 v214, 0, -v214, s[92:93]
	v_cndmask_b32_e64 v215, 0, -v215, s[94:95]
	v_add_f32_e32 v146, v146, v213
	v_add_f32_e32 v211, v211, v146
	v_add_f32_e32 v146, v146, v214
	v_add_f32_e32 v210, v210, v146
	v_add_f32_e32 v146, v146, v215
	v_add_f32_e32 v209, v209, v146
	s_waitcnt lgkmcnt(6)
	v_exp_f32_e64 v213, -|v208|
	v_exp_f32_e64 v214, -|v207|
	v_exp_f32_e64 v215, -|v206|
	v_max_f32_e32 v216, 0, v208
	v_max_f32_e32 v217, 0, v207
	v_max_f32_e32 v218, 0, v206
	v_add_f32_e32 v213, 1.0, v213
	v_add_f32_e32 v214, 1.0, v214
	v_add_f32_e32 v215, 1.0, v215
	v_log_f32_e32 v213, v213
	v_log_f32_e32 v214, v214
	v_log_f32_e32 v215, v215
	v_cmp_lt_i32_e32 vcc, 28, v212
	v_cmp_lt_i32_e64 s[92:93], 27, v212
	v_cmp_lt_i32_e64 s[94:95], 26, v212
	v_add_f32_e32 v213, v216, v213
	v_add_f32_e32 v214, v217, v214
	v_add_f32_e32 v215, v218, v215
	v_cndmask_b32_e64 v213, 0, -v213, vcc
	v_cndmask_b32_e64 v214, 0, -v214, s[92:93]
	v_cndmask_b32_e64 v215, 0, -v215, s[94:95]
	v_add_f32_e32 v146, v146, v213
	v_add_f32_e32 v208, v208, v146
	v_add_f32_e32 v146, v146, v214
	v_add_f32_e32 v207, v207, v146
	v_add_f32_e32 v146, v146, v215
	v_add_f32_e32 v206, v206, v146
	s_waitcnt lgkmcnt(5)
; template <int DH, int MODE>
; __device__ void attn_item(const Params& p, int layer, int b, int blk, int head, char* smem) {
;     ...
;         for (int c = 7; c >= 0; --c) {
;           float4 v = s4[c];
;           float e[4] = {v.x, v.y, v.z, v.w};
; #pragma unroll
;           for (int k = 3; k >= 0; --k) {
;             float z = e[k];
;             bool valid = (kpb + c * 4 + k) < qpos;
;             float sp = fmaxf(z, 0.f) + __builtin_amdgcn_logf(1.f + __builtin_amdgcn_exp2f(-fabsf(z)));
;             run += valid ? -sp : 0.f;
;             e[k] = z + run;
;           }
;           s4[c] = make_float4(e[0], e[1], e[2], e[3]);
;         }
	v_exp_f32_e64 v213, -|v205|
	v_exp_f32_e64 v214, -|v204|
	v_exp_f32_e64 v215, -|v203|
	v_max_f32_e32 v216, 0, v205
	v_max_f32_e32 v217, 0, v204
	v_max_f32_e32 v218, 0, v203
	v_add_f32_e32 v213, 1.0, v213
	v_add_f32_e32 v214, 1.0, v214
	v_add_f32_e32 v215, 1.0, v215
	v_log_f32_e32 v213, v213
	v_log_f32_e32 v214, v214
	v_log_f32_e32 v215, v215
	v_cmp_lt_i32_e32 vcc, 25, v212
	v_cmp_lt_i32_e64 s[92:93], 24, v212
	v_cmp_lt_i32_e64 s[94:95], 23, v212
	v_add_f32_e32 v213, v216, v213
	v_add_f32_e32 v214, v217, v214
	v_add_f32_e32 v215, v218, v215
	v_cndmask_b32_e64 v213, 0, -v213, vcc
	v_cndmask_b32_e64 v214, 0, -v214, s[92:93]
	v_cndmask_b32_e64 v215, 0, -v215, s[94:95]
	v_add_f32_e32 v146, v146, v213
	v_add_f32_e32 v205, v205, v146
	v_add_f32_e32 v146, v146, v214
	v_add_f32_e32 v204, v204, v146
	v_add_f32_e32 v146, v146, v215
	v_add_f32_e32 v203, v203, v146
	v_exp_f32_e64 v213, -|v202|
	v_exp_f32_e64 v214, -|v201|
	v_exp_f32_e64 v215, -|v200|
	v_max_f32_e32 v216, 0, v202
	v_max_f32_e32 v217, 0, v201
	v_max_f32_e32 v218, 0, v200
	v_add_f32_e32 v213, 1.0, v213
	v_add_f32_e32 v214, 1.0, v214
	v_add_f32_e32 v215, 1.0, v215
	v_log_f32_e32 v213, v213
	v_log_f32_e32 v214, v214
	v_log_f32_e32 v215, v215
	v_cmp_lt_i32_e32 vcc, 22, v212
	v_cmp_lt_i32_e64 s[92:93], 21, v212
	v_cmp_lt_i32_e64 s[94:95], 20, v212
	v_add_f32_e32 v213, v216, v213
	v_add_f32_e32 v214, v217, v214
	v_add_f32_e32 v215, v218, v215
	v_cndmask_b32_e64 v213, 0, -v213, vcc
	v_cndmask_b32_e64 v214, 0, -v214, s[92:93]
	v_cndmask_b32_e64 v215, 0, -v215, s[94:95]
	v_add_f32_e32 v146, v146, v213
	v_add_f32_e32 v202, v202, v146
	v_add_f32_e32 v146, v146, v214
	v_add_f32_e32 v201, v201, v146
	v_add_f32_e32 v146, v146, v215
	v_add_f32_e32 v200, v200, v146
	s_waitcnt lgkmcnt(4)
	v_exp_f32_e64 v213, -|v199|
	v_exp_f32_e64 v214, -|v198|
	v_exp_f32_e64 v215, -|v197|
	v_max_f32_e32 v216, 0, v199
	v_max_f32_e32 v217, 0, v198
	v_max_f32_e32 v218, 0, v197
	v_add_f32_e32 v213, 1.0, v213
	v_add_f32_e32 v214, 1.0, v214
	v_add_f32_e32 v215, 1.0, v215
	v_log_f32_e32 v213, v213
	v_log_f32_e32 v214, v214
	v_log_f32_e32 v215, v215
	v_cmp_lt_i32_e32 vcc, 19, v212
	v_cmp_lt_i32_e64 s[92:93], 18, v212
	v_cmp_lt_i32_e64 s[94:95], 17, v212
	v_add_f32_e32 v213, v216, v213
	v_add_f32_e32 v214, v217, v214
	v_add_f32_e32 v215, v218, v215
	v_cndmask_b32_e64 v213, 0, -v213, vcc
	v_cndmask_b32_e64 v214, 0, -v214, s[92:93]
	v_cndmask_b32_e64 v215, 0, -v215, s[94:95]
	v_add_f32_e32 v146, v146, v213
	v_add_f32_e32 v199, v199, v146
	v_add_f32_e32 v146, v146, v214
	v_add_f32_e32 v198, v198, v146
	v_add_f32_e32 v146, v146, v215
	v_add_f32_e32 v197, v197, v146
	s_waitcnt lgkmcnt(3)
	v_exp_f32_e64 v213, -|v196|
	v_exp_f32_e64 v214, -|v195|
	v_exp_f32_e64 v215, -|v194|
	v_max_f32_e32 v216, 0, v196
	v_max_f32_e32 v217, 0, v195
	v_max_f32_e32 v218, 0, v194
	v_add_f32_e32 v213, 1.0, v213
	v_add_f32_e32 v214, 1.0, v214
	v_add_f32_e32 v215, 1.0, v215
	v_log_f32_e32 v213, v213
	v_log_f32_e32 v214, v214
	v_log_f32_e32 v215, v215
	v_cmp_lt_i32_e32 vcc, 16, v212
	v_cmp_lt_i32_e64 s[92:93], 15, v212
	v_cmp_lt_i32_e64 s[94:95], 14, v212
	v_add_f32_e32 v213, v216, v213
	v_add_f32_e32 v214, v217, v214
	v_add_f32_e32 v215, v218, v215
	v_cndmask_b32_e64 v213, 0, -v213, vcc
	v_cndmask_b32_e64 v214, 0, -v214, s[92:93]
	v_cndmask_b32_e64 v215, 0, -v215, s[94:95]
	v_add_f32_e32 v146, v146, v213
	v_add_f32_e32 v196, v196, v146
	v_add_f32_e32 v146, v146, v214
	v_add_f32_e32 v195, v195, v146
	v_add_f32_e32 v146, v146, v215
	v_add_f32_e32 v194, v194, v146
	s_waitcnt lgkmcnt(2)
; template <int DH, int MODE>
; __device__ void attn_item(const Params& p, int layer, int b, int blk, int head, char* smem) {
;     ...
;         for (int c = 7; c >= 0; --c) {
;           float4 v = s4[c];
;           float e[4] = {v.x, v.y, v.z, v.w};
; #pragma unroll
;           for (int k = 3; k >= 0; --k) {
;             float z = e[k];
;             bool valid = (kpb + c * 4 + k) < qpos;
;             float sp = fmaxf(z, 0.f) + __builtin_amdgcn_logf(1.f + __builtin_amdgcn_exp2f(-fabsf(z)));
;             run += valid ? -sp : 0.f;
;             e[k] = z + run;
;           }
;           s4[c] = make_float4(e[0], e[1], e[2], e[3]);
;         }
	v_exp_f32_e64 v213, -|v193|
	v_exp_f32_e64 v214, -|v192|
	v_exp_f32_e64 v215, -|v191|
	v_max_f32_e32 v216, 0, v193
	v_max_f32_e32 v217, 0, v192
	v_max_f32_e32 v218, 0, v191
	v_add_f32_e32 v213, 1.0, v213
	v_add_f32_e32 v214, 1.0, v214
	v_add_f32_e32 v215, 1.0, v215
	v_log_f32_e32 v213, v213
	v_log_f32_e32 v214, v214
	v_log_f32_e32 v215, v215
	v_cmp_lt_i32_e32 vcc, 13, v212
	v_cmp_lt_i32_e64 s[92:93], 12, v212
	v_cmp_lt_i32_e64 s[94:95], 11, v212
	v_add_f32_e32 v213, v216, v213
	v_add_f32_e32 v214, v217, v214
	v_add_f32_e32 v215, v218, v215
	v_cndmask_b32_e64 v213, 0, -v213, vcc
	v_cndmask_b32_e64 v214, 0, -v214, s[92:93]
	v_cndmask_b32_e64 v215, 0, -v215, s[94:95]
	v_add_f32_e32 v146, v146, v213
	v_add_f32_e32 v193, v193, v146
	v_add_f32_e32 v146, v146, v214
	v_add_f32_e32 v192, v192, v146
	v_add_f32_e32 v146, v146, v215
	v_add_f32_e32 v191, v191, v146
	v_exp_f32_e64 v213, -|v190|
	v_exp_f32_e64 v214, -|v189|
	v_exp_f32_e64 v215, -|v188|
	v_max_f32_e32 v216, 0, v190
	v_max_f32_e32 v217, 0, v189
	v_max_f32_e32 v218, 0, v188
	v_add_f32_e32 v213, 1.0, v213
	v_add_f32_e32 v214, 1.0, v214
	v_add_f32_e32 v215, 1.0, v215
	v_log_f32_e32 v213, v213
	v_log_f32_e32 v214, v214
	v_log_f32_e32 v215, v215
	v_cmp_lt_i32_e32 vcc, 10, v212
	v_cmp_lt_i32_e64 s[92:93], 9, v212
	v_cmp_lt_i32_e64 s[94:95], 8, v212
	v_add_f32_e32 v213, v216, v213
	v_add_f32_e32 v214, v217, v214
	v_add_f32_e32 v215, v218, v215
	v_cndmask_b32_e64 v213, 0, -v213, vcc
	v_cndmask_b32_e64 v214, 0, -v214, s[92:93]
	v_cndmask_b32_e64 v215, 0, -v215, s[94:95]
	v_add_f32_e32 v146, v146, v213
	v_add_f32_e32 v190, v190, v146
	v_add_f32_e32 v146, v146, v214
	v_add_f32_e32 v189, v189, v146
	v_add_f32_e32 v146, v146, v215
	v_add_f32_e32 v188, v188, v146
	s_waitcnt lgkmcnt(1)
	v_exp_f32_e64 v213, -|v187|
	v_exp_f32_e64 v214, -|v186|
	v_exp_f32_e64 v215, -|v185|
	v_max_f32_e32 v216, 0, v187
	v_max_f32_e32 v217, 0, v186
	v_max_f32_e32 v218, 0, v185
	v_add_f32_e32 v213, 1.0, v213
	v_add_f32_e32 v214, 1.0, v214
	v_add_f32_e32 v215, 1.0, v215
	v_log_f32_e32 v213, v213
	v_log_f32_e32 v214, v214
	v_log_f32_e32 v215, v215
	v_cmp_lt_i32_e32 vcc, 7, v212
	v_cmp_lt_i32_e64 s[92:93], 6, v212
	v_cmp_lt_i32_e64 s[94:95], 5, v212
	v_add_f32_e32 v213, v216, v213
	v_add_f32_e32 v214, v217, v214
	v_add_f32_e32 v215, v218, v215
	v_cndmask_b32_e64 v213, 0, -v213, vcc
	v_cndmask_b32_e64 v214, 0, -v214, s[92:93]
	v_cndmask_b32_e64 v215, 0, -v215, s[94:95]
	v_add_f32_e32 v146, v146, v213
	v_add_f32_e32 v187, v187, v146
	v_add_f32_e32 v146, v146, v214
	v_add_f32_e32 v186, v186, v146
	v_add_f32_e32 v146, v146, v215
	v_add_f32_e32 v185, v185, v146
	s_waitcnt lgkmcnt(0)
	v_exp_f32_e64 v213, -|v184|
	v_exp_f32_e64 v214, -|v183|
	v_exp_f32_e64 v215, -|v182|
	v_max_f32_e32 v216, 0, v184
	v_max_f32_e32 v217, 0, v183
	v_max_f32_e32 v218, 0, v182
	v_add_f32_e32 v213, 1.0, v213
	v_add_f32_e32 v214, 1.0, v214
	v_add_f32_e32 v215, 1.0, v215
	v_log_f32_e32 v213, v213
	v_log_f32_e32 v214, v214
	v_log_f32_e32 v215, v215
	v_cmp_lt_i32_e32 vcc, 4, v212
	v_cmp_lt_i32_e64 s[92:93], 3, v212
	v_cmp_lt_i32_e64 s[94:95], 2, v212
	v_add_f32_e32 v213, v216, v213
	v_add_f32_e32 v214, v217, v214
	v_add_f32_e32 v215, v218, v215
	v_cndmask_b32_e64 v213, 0, -v213, vcc
	v_cndmask_b32_e64 v214, 0, -v214, s[92:93]
	v_cndmask_b32_e64 v215, 0, -v215, s[94:95]
	v_add_f32_e32 v146, v146, v213
	v_add_f32_e32 v184, v184, v146
	v_add_f32_e32 v146, v146, v214
	v_add_f32_e32 v183, v183, v146
	v_add_f32_e32 v146, v146, v215
	v_add_f32_e32 v182, v182, v146
	v_exp_f32_e64 v213, -|v181|
	v_exp_f32_e64 v214, -|v180|
	v_max_f32_e32 v216, 0, v181
	v_max_f32_e32 v217, 0, v180
	v_add_f32_e32 v213, 1.0, v213
	v_add_f32_e32 v214, 1.0, v214
	v_log_f32_e32 v213, v213
	v_log_f32_e32 v214, v214
	v_cmp_lt_i32_e32 vcc, 1, v212
	v_cmp_lt_i32_e64 s[92:93], 0, v212
	s_nop 0
	v_add_f32_e32 v213, v216, v213
	v_add_f32_e32 v214, v217, v214
	v_cndmask_b32_e64 v213, 0, -v213, vcc
	v_cndmask_b32_e64 v214, 0, -v214, s[92:93]
	v_add_f32_e32 v146, v146, v213
	v_add_f32_e32 v181, v181, v146
	v_add_f32_e32 v146, v146, v214
	v_add_f32_e32 v180, v180, v146
	s_branch .Lsb_p1done_1

; template <int DH, int MODE>
; __device__ void attn_item(const Params& p, int layer, int b, int blk, int head, char* smem) {
;     ...
;         const int kjb = kj0 + half * 32;
;         float tmax = -1e30f;
; #pragma unroll
;         for (int c = 0; c < 8; ++c) {
;           float4 v = s4[c];
;           float e[4] = {v.x, v.y, v.z, v.w};
; #pragma unroll
;           for (int k = 0; k < 4; ++k) {
;             int kj = kjb + c * 4 + k;
;             bool valid = (kj > row) && (kj <= row + 128);
;             tmax = valid ? fmaxf(tmax, e[k]) : tmax;
;           }
;         }
.LBB0_1129:
	s_or_b64 exec, exec, s[8:9]
	s_add_i32 s82, s82, 1
	s_min_i32 s8, s82, s80
	s_add_i32 s8, s8, s79
	s_lshl_b32 s8, s8, 6
	s_add_i32 s8, s8, s81
	s_ashr_i32 s9, s8, 31
	s_add_u32 s8, s8, s77
	s_addc_u32 s9, s9, 0
	s_waitcnt lgkmcnt(0)
	s_barrier
	ds_write_b16 v96, v48
	ds_write_b16_d16_hi v96, v48 offset:64
	ds_write_b16 v96, v49 offset:128
	ds_write_b16_d16_hi v96, v49 offset:192
	ds_write_b16 v96, v50 offset:256
	ds_write_b16_d16_hi v96, v50 offset:320
	ds_write_b16 v96, v51 offset:384
	ds_write_b16_d16_hi v96, v51 offset:448
	s_waitcnt vmcnt(0)
	ds_write_b16 v96, v52 offset:2048
	ds_write_b16_d16_hi v96, v52 offset:2112
	ds_write_b16 v96, v53 offset:2176
	ds_write_b16_d16_hi v96, v53 offset:2240
	ds_write_b16 v96, v54 offset:2304
	ds_write_b16_d16_hi v96, v54 offset:2368
	ds_write_b16 v96, v55 offset:2432
	ds_write_b16_d16_hi v96, v55 offset:2496
	v_lshl_add_u64 v[48:49], s[8:9], 0, v[66:67]
	v_mad_u64_u32 v[52:53], s[12:13], v48, s39, v[76:77]
	v_or_b32_e32 v48, s8, v72
	v_mad_i32_i24 v53, v49, s39, v53
	v_mad_u64_u32 v[54:55], s[12:13], v48, s39, v[78:79]
	v_add_co_u32_e32 v48, vcc, 0x4c000, v52
	v_mad_i32_i24 v55, s9, v160, v55
	s_nop 0
	v_addc_co_u32_e32 v49, vcc, 0, v53, vcc
	global_load_dwordx4 v[60:63], v[48:49], off
	s_nop 0
	global_load_dwordx4 v[48:51], v[54:55], off
	global_load_dwordx4 v[56:59], v[52:53], off
	s_nop 0
	global_load_dwordx4 v[52:55], v[54:55], off offset:64
	s_and_saveexec_b64 s[46:47], s[44:45]
	s_cbranch_execz .LBB0_1151
	v_or_b32_e32 v101, s10, v89
	s_movk_i32 s91, 0x80
	ds_read_b128 v[164:167], v90 offset:16384
	ds_read_b128 v[168:171], v90 offset:16400
	ds_read_b128 v[172:175], v90 offset:16416
	ds_read_b128 v[176:179], v90 offset:16432
	ds_read_b128 v[180:183], v90 offset:16448
	ds_read_b128 v[184:187], v90 offset:16464
	ds_read_b128 v[188:191], v90 offset:16480
	ds_read_b128 v[192:195], v90 offset:16496
	v_sub_u32_e32 v102, v80, v101
	v_mov_b32_e32 v83, 0xf149f2ca
	v_add_u32_e32 v103, -31, v102
	v_cmp_gt_u32_e32 vcc, 0x61, v103
	s_cmp_eq_u64 vcc, exec
	s_cbranch_scc1 .Lswa_tfast_0
	v_mov_b32_e32 v196, v102
	v_add_u32_e32 v197, -1, v102
	v_add_u32_e32 v198, -2, v102
	v_cmp_gt_u32_e32 vcc, s91, v196
	v_cmp_gt_u32_e64 s[92:93], s91, v197
	v_cmp_gt_u32_e64 s[94:95], s91, v198
	s_waitcnt lgkmcnt(7)
	v_cndmask_b32_e32 v164, v83, v164, vcc
	v_cndmask_b32_e64 v165, v83, v165, s[92:93]
	v_cndmask_b32_e64 v166, v83, v166, s[94:95]
	v_add_u32_e32 v196, -3, v102
	v_add_u32_e32 v197, -4, v102
	v_add_u32_e32 v198, -5, v102
	v_cmp_gt_u32_e32 vcc, s91, v196
	v_cmp_gt_u32_e64 s[92:93], s91, v197
	v_cmp_gt_u32_e64 s[94:95], s91, v198
	s_waitcnt lgkmcnt(6)
	v_cndmask_b32_e32 v167, v83, v167, vcc
	v_cndmask_b32_e64 v168, v83, v168, s[92:93]
	v_cndmask_b32_e64 v169, v83, v169, s[94:95]
	v_add_u32_e32 v196, -6, v102
	v_add_u32_e32 v197, -7, v102
	v_add_u32_e32 v198, -8, v102
	v_cmp_gt_u32_e32 vcc, s91, v196
	v_cmp_gt_u32_e64 s[92:93], s91, v197
	v_cmp_gt_u32_e64 s[94:95], s91, v198
	s_waitcnt lgkmcnt(5)
	v_cndmask_b32_e32 v170, v83, v170, vcc
	v_cndmask_b32_e64 v171, v83, v171, s[92:93]
	v_cndmask_b32_e64 v172, v83, v172, s[94:95]
	v_add_u32_e32 v196, -9, v102
	v_add_u32_e32 v197, -10, v102
	v_add_u32_e32 v198, -11, v102
	v_cmp_gt_u32_e32 vcc, s91, v196
	v_cmp_gt_u32_e64 s[92:93], s91, v197
	v_cmp_gt_u32_e64 s[94:95], s91, v198
	v_cndmask_b32_e32 v173, v83, v173, vcc
	v_cndmask_b32_e64 v174, v83, v174, s[92:93]
	v_cndmask_b32_e64 v175, v83, v175, s[94:95]
	v_add_u32_e32 v196, -12, v102
	v_add_u32_e32 v197, -13, v102
	v_add_u32_e32 v198, -14, v102
	v_cmp_gt_u32_e32 vcc, s91, v196
	v_cmp_gt_u32_e64 s[92:93], s91, v197
	v_cmp_gt_u32_e64 s[94:95], s91, v198
	s_waitcnt lgkmcnt(4)
	v_cndmask_b32_e32 v176, v83, v176, vcc
	v_cndmask_b32_e64 v177, v83, v177, s[92:93]
	v_cndmask_b32_e64 v178, v83, v178, s[94:95]
	v_add_u32_e32 v196, -15, v102
	v_add_u32_e32 v197, -16, v102
	v_add_u32_e32 v198, 0xffffffef, v102
	v_cmp_gt_u32_e32 vcc, s91, v196
	v_cmp_gt_u32_e64 s[92:93], s91, v197
	v_cmp_gt_u32_e64 s[94:95], s91, v198
	s_waitcnt lgkmcnt(3)
	v_cndmask_b32_e32 v179, v83, v179, vcc
	v_cndmask_b32_e64 v180, v83, v180, s[92:93]
	v_cndmask_b32_e64 v181, v83, v181, s[94:95]
	v_add_u32_e32 v196, 0xffffffee, v102
	v_add_u32_e32 v197, 0xffffffed, v102
	v_add_u32_e32 v198, 0xffffffec, v102
	v_cmp_gt_u32_e32 vcc, s91, v196
	v_cmp_gt_u32_e64 s[92:93], s91, v197
	v_cmp_gt_u32_e64 s[94:95], s91, v198
	s_waitcnt lgkmcnt(2)
	v_cndmask_b32_e32 v182, v83, v182, vcc
	v_cndmask_b32_e64 v183, v83, v183, s[92:93]
	v_cndmask_b32_e64 v184, v83, v184, s[94:95]
	v_add_u32_e32 v196, 0xffffffeb, v102
	v_add_u32_e32 v197, 0xffffffea, v102
	v_add_u32_e32 v198, 0xffffffe9, v102
	v_cmp_gt_u32_e32 vcc, s91, v196
	v_cmp_gt_u32_e64 s[92:93], s91, v197
	v_cmp_gt_u32_e64 s[94:95], s91, v198
	v_cndmask_b32_e32 v185, v83, v185, vcc
	v_cndmask_b32_e64 v186, v83, v186, s[92:93]
	v_cndmask_b32_e64 v187, v83, v187, s[94:95]
	v_add_u32_e32 v196, 0xffffffe8, v102
	v_add_u32_e32 v197, 0xffffffe7, v102
	v_add_u32_e32 v198, 0xffffffe6, v102
	v_cmp_gt_u32_e32 vcc, s91, v196
	v_cmp_gt_u32_e64 s[92:93], s91, v197
	v_cmp_gt_u32_e64 s[94:95], s91, v198
	s_waitcnt lgkmcnt(1)
	v_cndmask_b32_e32 v188, v83, v188, vcc
	v_cndmask_b32_e64 v189, v83, v189, s[92:93]
	v_cndmask_b32_e64 v190, v83, v190, s[94:95]
	v_add_u32_e32 v196, 0xffffffe5, v102
	v_add_u32_e32 v197, 0xffffffe4, v102
	v_add_u32_e32 v198, 0xffffffe3, v102
	v_cmp_gt_u32_e32 vcc, s91, v196
	v_cmp_gt_u32_e64 s[92:93], s91, v197
	v_cmp_gt_u32_e64 s[94:95], s91, v198
	s_waitcnt lgkmcnt(0)
	v_cndmask_b32_e32 v191, v83, v191, vcc
	v_cndmask_b32_e64 v192, v83, v192, s[92:93]
	v_cndmask_b32_e64 v193, v83, v193, s[94:95]
	v_add_u32_e32 v196, 0xffffffe2, v102
	v_add_u32_e32 v197, 0xffffffe1, v102
	v_cmp_gt_u32_e32 vcc, s91, v196
	v_cmp_gt_u32_e64 s[92:93], s91, v197
	s_nop 0
	v_cndmask_b32_e32 v194, v83, v194, vcc
	v_cndmask_b32_e64 v195, v83, v195, s[92:93]
	v_max3_f32 v164, v164, v165, v166
	v_max3_f32 v167, v167, v168, v169
	v_max3_f32 v170, v170, v171, v172
	v_max3_f32 v173, v173, v174, v175
	v_max3_f32 v176, v176, v177, v178
	v_max3_f32 v179, v179, v180, v181
	v_max3_f32 v182, v182, v183, v184
	v_max3_f32 v185, v185, v186, v187
	v_max3_f32 v188, v188, v189, v190
	v_max3_f32 v191, v191, v192, v193
	v_max_f32_e32 v194, v194, v195
	v_max3_f32 v164, v164, v167, v170
	v_max3_f32 v173, v173, v176, v179
	v_max3_f32 v182, v182, v185, v188
	v_max_f32_e32 v191, v191, v194
	v_max3_f32 v164, v164, v173, v182
	v_max_f32_e32 v164, v164, v191
	v_mov_b32_e32 v82, v164
	s_branch .Lswa_tdone_0

; template <int DH, int MODE>
; __device__ void attn_item(const Params& p, int layer, int b, int blk, int head, char* smem) {
;     ...
;         tmax = fmaxf(tmax, __shfl_xor(tmax, 1));
;         float m_new = fmaxf(m_run, tmax);
;         float alpha = __builtin_amdgcn_exp2f(m_run - m_new);
;         float psum = 0.f;
; #pragma unroll 2
;         for (int s8 = 0; s8 < 4; ++s8) {
;           float4 va = s4[2 * s8], vb = s4[2 * s8 + 1];
;           float e[8] = {va.x, va.y, va.z, va.w, vb.x, vb.y, vb.z, vb.w};
;           float pv[8];
; #pragma unroll
;           for (int k = 0; k < 8; ++k) {
;             int kj = kjb + s8 * 8 + k;
;             bool valid = (kj > row) && (kj <= row + 128);
;             float pe = valid ? __builtin_amdgcn_exp2f(e[k] - m_new) : 0.f;
;             pv[k] = pe;
;             psum += pe;
;           }
.Lswa_tdone_0:
	v_cmp_lt_i32_e32 vcc, v157, v158
	s_mov_b32 s83, 0
	v_mov_b32_e32 v103, 0
	v_cndmask_b32_e32 v83, v156, v157, vcc
	v_lshlrev_b32_e32 v83, 2, v83
	ds_bpermute_b32 v101, v83, v82
	v_mov_b32_e32 v102, v91
	s_waitcnt lgkmcnt(0)
	v_max3_f32 v82, v87, v82, v101
	v_mov_b32_e32 v101, v93
	ds_read_b128 v[164:167], v102
	ds_read_b128 v[168:171], v102 offset:16
	ds_read_b128 v[172:175], v102 offset:32
	ds_read_b128 v[176:179], v102 offset:48
	ds_read_b128 v[180:183], v102 offset:64
	ds_read_b128 v[184:187], v102 offset:80
	ds_read_b128 v[188:191], v102 offset:96
	ds_read_b128 v[192:195], v102 offset:112
	s_movk_i32 s91, 0x80
	v_sub_u32_e32 v112, v80, v92
	v_add_u32_e32 v113, -31, v112
	v_cmp_gt_u32_e32 vcc, 0x61, v113
	s_cmp_eq_u64 vcc, exec
	s_cbranch_scc1 .Lswa_pfast_0
	s_waitcnt lgkmcnt(7)
	v_sub_f32_e32 v164, v164, v82
	v_sub_f32_e32 v165, v165, v82
	v_sub_f32_e32 v166, v166, v82
	v_exp_f32_e32 v164, v164
	v_exp_f32_e32 v165, v165
	v_exp_f32_e32 v166, v166
	v_mov_b32_e32 v196, v112
	v_add_u32_e32 v197, -1, v112
	v_add_u32_e32 v198, -2, v112
	v_cmp_gt_u32_e32 vcc, s91, v196
	v_cmp_gt_u32_e64 s[92:93], s91, v197
	v_cmp_gt_u32_e64 s[94:95], s91, v198
	v_cndmask_b32_e32 v164, 0, v164, vcc
	v_cndmask_b32_e64 v165, 0, v165, s[92:93]
	v_cndmask_b32_e64 v166, 0, v166, s[94:95]
	v_add_f32_e32 v103, v103, v164
	v_add_f32_e32 v103, v103, v165
	v_add_f32_e32 v103, v103, v166
	s_waitcnt lgkmcnt(6)
	v_sub_f32_e32 v167, v167, v82
	v_sub_f32_e32 v168, v168, v82
	v_sub_f32_e32 v169, v169, v82
	v_exp_f32_e32 v167, v167
	v_exp_f32_e32 v168, v168
	v_exp_f32_e32 v169, v169
	v_add_u32_e32 v196, -3, v112
	v_add_u32_e32 v197, -4, v112
	v_add_u32_e32 v198, -5, v112
	v_cmp_gt_u32_e32 vcc, s91, v196
	v_cmp_gt_u32_e64 s[92:93], s91, v197
	v_cmp_gt_u32_e64 s[94:95], s91, v198
	v_cndmask_b32_e32 v167, 0, v167, vcc
	v_cndmask_b32_e64 v168, 0, v168, s[92:93]
	v_cndmask_b32_e64 v169, 0, v169, s[94:95]
	v_add_f32_e32 v103, v103, v167
	v_add_f32_e32 v103, v103, v168
	v_add_f32_e32 v103, v103, v169
	s_waitcnt lgkmcnt(5)
	v_sub_f32_e32 v170, v170, v82
	v_sub_f32_e32 v171, v171, v82
	v_sub_f32_e32 v172, v172, v82
	v_exp_f32_e32 v170, v170
	v_exp_f32_e32 v171, v171
	v_exp_f32_e32 v172, v172
	v_add_u32_e32 v196, -6, v112
	v_add_u32_e32 v197, -7, v112
	v_add_u32_e32 v198, -8, v112
	v_cmp_gt_u32_e32 vcc, s91, v196
	v_cmp_gt_u32_e64 s[92:93], s91, v197
	v_cmp_gt_u32_e64 s[94:95], s91, v198
	v_cndmask_b32_e32 v170, 0, v170, vcc
	v_cndmask_b32_e64 v171, 0, v171, s[92:93]
	v_cndmask_b32_e64 v172, 0, v172, s[94:95]
	v_add_f32_e32 v103, v103, v170
	v_add_f32_e32 v103, v103, v171
	v_add_f32_e32 v103, v103, v172
	v_sub_f32_e32 v173, v173, v82
	v_sub_f32_e32 v174, v174, v82
	v_sub_f32_e32 v175, v175, v82
	v_exp_f32_e32 v173, v173
	v_exp_f32_e32 v174, v174
	v_exp_f32_e32 v175, v175
	v_add_u32_e32 v196, -9, v112
	v_add_u32_e32 v197, -10, v112
	v_add_u32_e32 v198, -11, v112
	v_cmp_gt_u32_e32 vcc, s91, v196
	v_cmp_gt_u32_e64 s[92:93], s91, v197
	v_cmp_gt_u32_e64 s[94:95], s91, v198
	v_cndmask_b32_e32 v173, 0, v173, vcc
	v_cndmask_b32_e64 v174, 0, v174, s[92:93]
	v_cndmask_b32_e64 v175, 0, v175, s[94:95]
	v_add_f32_e32 v103, v103, v173
	v_add_f32_e32 v103, v103, v174
	v_add_f32_e32 v103, v103, v175
	s_waitcnt lgkmcnt(4)
	v_sub_f32_e32 v176, v176, v82
	v_sub_f32_e32 v177, v177, v82
	v_sub_f32_e32 v178, v178, v82
	v_exp_f32_e32 v176, v176
	v_exp_f32_e32 v177, v177
	v_exp_f32_e32 v178, v178
	v_add_u32_e32 v196, -12, v112
	v_add_u32_e32 v197, -13, v112
	v_add_u32_e32 v198, -14, v112
	v_cmp_gt_u32_e32 vcc, s91, v196
	v_cmp_gt_u32_e64 s[92:93], s91, v197
	v_cmp_gt_u32_e64 s[94:95], s91, v198
	v_cndmask_b32_e32 v176, 0, v176, vcc
	v_cndmask_b32_e64 v177, 0, v177, s[92:93]
	v_cndmask_b32_e64 v178, 0, v178, s[94:95]
	v_add_f32_e32 v103, v103, v176
	v_add_f32_e32 v103, v103, v177
	v_add_f32_e32 v103, v103, v178
	s_waitcnt lgkmcnt(3)
; __device__ __forceinline__ unsigned pack2(float a, float b) { return (unsigned)f2bf(a) | ((unsigned)f2bf(b) << 16); }
; template <int DH, int MODE>
; __device__ void attn_item(const Params& p, int layer, int b, int blk, int head, char* smem) {
;     ...
; #pragma unroll 2
;         for (int s8 = 0; s8 < 4; ++s8) {
;           float4 va = s4[2 * s8], vb = s4[2 * s8 + 1];
;           float e[8] = {va.x, va.y, va.z, va.w, vb.x, vb.y, vb.z, vb.w};
;           float pv[8];
; #pragma unroll
;           for (int k = 0; k < 8; ++k) {
;             int kj = kjb + s8 * 8 + k;
;             bool valid = (kj > row) && (kj <= row + 128);
;             float pe = valid ? __builtin_amdgcn_exp2f(e[k] - m_new) : 0.f;
;             pv[k] = pe;
;             psum += pe;
;           }
;           uint4 ov;
;           ov.x = pack2(pv[0], pv[1]); ov.y = pack2(pv[2], pv[3]);
;           ov.z = pack2(pv[4], pv[5]); ov.w = pack2(pv[6], pv[7]);
;           *reinterpret_cast<uint4*>(prow + s8 * 16) = ov;
	v_sub_f32_e32 v179, v179, v82
	v_sub_f32_e32 v180, v180, v82
	v_sub_f32_e32 v181, v181, v82
	v_exp_f32_e32 v179, v179
	v_exp_f32_e32 v180, v180
	v_exp_f32_e32 v181, v181
	v_add_u32_e32 v196, -15, v112
	v_add_u32_e32 v197, -16, v112
	v_add_u32_e32 v198, 0xffffffef, v112
	v_cmp_gt_u32_e32 vcc, s91, v196
	v_cmp_gt_u32_e64 s[92:93], s91, v197
	v_cmp_gt_u32_e64 s[94:95], s91, v198
	v_cndmask_b32_e32 v179, 0, v179, vcc
	v_cndmask_b32_e64 v180, 0, v180, s[92:93]
	v_cndmask_b32_e64 v181, 0, v181, s[94:95]
	v_add_f32_e32 v103, v103, v179
	v_add_f32_e32 v103, v103, v180
	v_add_f32_e32 v103, v103, v181
	s_waitcnt lgkmcnt(2)
	v_sub_f32_e32 v182, v182, v82
	v_sub_f32_e32 v183, v183, v82
	v_sub_f32_e32 v184, v184, v82
	v_exp_f32_e32 v182, v182
	v_exp_f32_e32 v183, v183
	v_exp_f32_e32 v184, v184
	v_add_u32_e32 v196, 0xffffffee, v112
	v_add_u32_e32 v197, 0xffffffed, v112
	v_add_u32_e32 v198, 0xffffffec, v112
	v_cmp_gt_u32_e32 vcc, s91, v196
	v_cmp_gt_u32_e64 s[92:93], s91, v197
	v_cmp_gt_u32_e64 s[94:95], s91, v198
	v_cndmask_b32_e32 v182, 0, v182, vcc
	v_cndmask_b32_e64 v183, 0, v183, s[92:93]
	v_cndmask_b32_e64 v184, 0, v184, s[94:95]
	v_add_f32_e32 v103, v103, v182
	v_add_f32_e32 v103, v103, v183
	v_add_f32_e32 v103, v103, v184
	v_sub_f32_e32 v185, v185, v82
	v_sub_f32_e32 v186, v186, v82
	v_sub_f32_e32 v187, v187, v82
	v_exp_f32_e32 v185, v185
	v_exp_f32_e32 v186, v186
	v_exp_f32_e32 v187, v187
	v_add_u32_e32 v196, 0xffffffeb, v112
	v_add_u32_e32 v197, 0xffffffea, v112
	v_add_u32_e32 v198, 0xffffffe9, v112
	v_cmp_gt_u32_e32 vcc, s91, v196
	v_cmp_gt_u32_e64 s[92:93], s91, v197
	v_cmp_gt_u32_e64 s[94:95], s91, v198
	v_cndmask_b32_e32 v185, 0, v185, vcc
	v_cndmask_b32_e64 v186, 0, v186, s[92:93]
	v_cndmask_b32_e64 v187, 0, v187, s[94:95]
	v_add_f32_e32 v103, v103, v185
	v_add_f32_e32 v103, v103, v186
	v_add_f32_e32 v103, v103, v187
	s_waitcnt lgkmcnt(1)
	v_sub_f32_e32 v188, v188, v82
	v_sub_f32_e32 v189, v189, v82
	v_sub_f32_e32 v190, v190, v82
	v_exp_f32_e32 v188, v188
	v_exp_f32_e32 v189, v189
	v_exp_f32_e32 v190, v190
	v_add_u32_e32 v196, 0xffffffe8, v112
	v_add_u32_e32 v197, 0xffffffe7, v112
	v_add_u32_e32 v198, 0xffffffe6, v112
	v_cmp_gt_u32_e32 vcc, s91, v196
	v_cmp_gt_u32_e64 s[92:93], s91, v197
	v_cmp_gt_u32_e64 s[94:95], s91, v198
	v_cndmask_b32_e32 v188, 0, v188, vcc
	v_cndmask_b32_e64 v189, 0, v189, s[92:93]
	v_cndmask_b32_e64 v190, 0, v190, s[94:95]
	v_add_f32_e32 v103, v103, v188
	v_add_f32_e32 v103, v103, v189
	v_add_f32_e32 v103, v103, v190
	s_waitcnt lgkmcnt(0)
	v_sub_f32_e32 v191, v191, v82
	v_sub_f32_e32 v192, v192, v82
	v_sub_f32_e32 v193, v193, v82
	v_exp_f32_e32 v191, v191
	v_exp_f32_e32 v192, v192
	v_exp_f32_e32 v193, v193
	v_add_u32_e32 v196, 0xffffffe5, v112
	v_add_u32_e32 v197, 0xffffffe4, v112
	v_add_u32_e32 v198, 0xffffffe3, v112
	v_cmp_gt_u32_e32 vcc, s91, v196
	v_cmp_gt_u32_e64 s[92:93], s91, v197
	v_cmp_gt_u32_e64 s[94:95], s91, v198
	v_cndmask_b32_e32 v191, 0, v191, vcc
	v_cndmask_b32_e64 v192, 0, v192, s[92:93]
	v_cndmask_b32_e64 v193, 0, v193, s[94:95]
	v_add_f32_e32 v103, v103, v191
	v_add_f32_e32 v103, v103, v192
	v_add_f32_e32 v103, v103, v193
	v_sub_f32_e32 v194, v194, v82
	v_sub_f32_e32 v195, v195, v82
	v_exp_f32_e32 v194, v194
	v_exp_f32_e32 v195, v195
	v_add_u32_e32 v196, 0xffffffe2, v112
	v_add_u32_e32 v197, 0xffffffe1, v112
	v_cmp_gt_u32_e32 vcc, s91, v196
	v_cmp_gt_u32_e64 s[92:93], s91, v197
	s_nop 0
	v_cndmask_b32_e32 v194, 0, v194, vcc
	v_cndmask_b32_e64 v195, 0, v195, s[92:93]
	v_add_f32_e32 v103, v103, v194
	v_add_f32_e32 v103, v103, v195
	v_cvt_pk_bf16_f32 v104, v164, v165
	v_cvt_pk_bf16_f32 v105, v166, v167
	v_cvt_pk_bf16_f32 v106, v168, v169
	v_cvt_pk_bf16_f32 v107, v170, v171
	ds_write_b128 v101, v[104:107]
	s_nop 0
	v_cvt_pk_bf16_f32 v104, v172, v173
	v_cvt_pk_bf16_f32 v105, v174, v175
	v_cvt_pk_bf16_f32 v106, v176, v177
	v_cvt_pk_bf16_f32 v107, v178, v179
	ds_write_b128 v101, v[104:107] offset:16
	s_nop 0
	v_cvt_pk_bf16_f32 v104, v180, v181
	v_cvt_pk_bf16_f32 v105, v182, v183
	v_cvt_pk_bf16_f32 v106, v184, v185
	v_cvt_pk_bf16_f32 v107, v186, v187
	ds_write_b128 v101, v[104:107] offset:32
	s_nop 0
	v_cvt_pk_bf16_f32 v104, v188, v189
	v_cvt_pk_bf16_f32 v105, v190, v191
	v_cvt_pk_bf16_f32 v106, v192, v193
	v_cvt_pk_bf16_f32 v107, v194, v195
	ds_write_b128 v101, v[104:107] offset:48
	s_branch .Lswa_pdone_0

; __device__ __forceinline__ unsigned pack2(float a, float b) { return (unsigned)f2bf(a) | ((unsigned)f2bf(b) << 16); }
; template <int DH, int MODE>
; __device__ void attn_item(const Params& p, int layer, int b, int blk, int head, char* smem) {
;     ...
;         float alpha = __builtin_amdgcn_exp2f(m_run - m_new);
;         float psum = 0.f;
; #pragma unroll 2
;         for (int s8 = 0; s8 < 4; ++s8) {
;           float4 va = s4[2 * s8], vb = s4[2 * s8 + 1];
;           float e[8] = {va.x, va.y, va.z, va.w, vb.x, vb.y, vb.z, vb.w};
;           float pv[8];
; #pragma unroll
;           for (int k = 0; k < 8; ++k) {
;             int kj = kjb + s8 * 8 + k;
;             bool valid = (kj > row) && (kj <= row + 128);
;             float pe = valid ? __builtin_amdgcn_exp2f(e[k] - m_new) : 0.f;
;             pv[k] = pe;
;             psum += pe;
;           }
;           uint4 ov;
;           ov.x = pack2(pv[0], pv[1]); ov.y = pack2(pv[2], pv[3]);
;           ov.z = pack2(pv[4], pv[5]); ov.w = pack2(pv[6], pv[7]);
;           *reinterpret_cast<uint4*>(prow + s8 * 16) = ov;
;         }
;         psum += __shfl_xor(psum, 1);
;         l_run = l_run * alpha + psum;
;         m_run = m_new;
;         if (half == 0) alpha_s[row] = alpha;
.Lswa_pdone_0:
	v_sub_f32_e32 v101, v87, v82
	ds_bpermute_b32 v87, v83, v103
	v_exp_f32_e32 v83, v101
	s_and_saveexec_b64 s[8:9], s[6:7]
	ds_write_b32 v97, v83 offset:8192
	s_or_b64 exec, exec, s[8:9]
	s_waitcnt lgkmcnt(0)
	v_add_f32_e32 v101, v103, v87
	v_fmac_f32_e32 v101, v88, v83
	v_mov_b32_e32 v87, v82
	v_mov_b32_e32 v88, v101

; template <int DH, int MODE>
; __device__ void attn_item(const Params& p, int layer, int b, int blk, int head, char* smem) {
;     ...
;         const int qpos = blk * 128 + row;
;         const int kpb = ktok + half * 32;
;         float run = 0.f;
; #pragma unroll 2
;         for (int c = 7; c >= 0; --c) {
;           float4 v = s4[c];
;           float e[4] = {v.x, v.y, v.z, v.w};
; #pragma unroll
;           for (int k = 3; k >= 0; --k) {
;             float z = e[k];
;             bool valid = (kpb + c * 4 + k) < qpos;
;             float sp = fmaxf(z, 0.f) + __builtin_amdgcn_logf(1.f + __builtin_amdgcn_exp2f(-fabsf(z)));
;             run += valid ? -sp : 0.f;
;             e[k] = z + run;
;           }
;           s4[c] = make_float4(e[0], e[1], e[2], e[3]);
;         }
.LBB0_1166:
	s_or_b64 exec, exec, s[44:45]
	s_add_i32 s16, s80, 1
	s_min_i32 s44, s16, s78
	s_sub_i32 s44, s78, s44
	s_lshl_b32 s44, s44, 6
	s_ashr_i32 s45, s44, 31
	s_add_u32 s44, s44, s77
	s_addc_u32 s45, s45, 0
	s_waitcnt lgkmcnt(0)
	s_barrier
	ds_write_b16 v171, v96
	ds_write_b16_d16_hi v171, v96 offset:64
	ds_write_b16 v171, v97 offset:128
	ds_write_b16_d16_hi v171, v97 offset:192
	ds_write_b16 v171, v98 offset:256
	ds_write_b16_d16_hi v171, v98 offset:320
	ds_write_b16 v171, v99 offset:384
	ds_write_b16_d16_hi v171, v99 offset:448
	ds_write_b16 v171, v100 offset:2048
	ds_write_b16_d16_hi v171, v100 offset:2112
	ds_write_b16 v171, v101 offset:2176
	ds_write_b16_d16_hi v171, v101 offset:2240
	ds_write_b16 v171, v102 offset:2304
	ds_write_b16_d16_hi v171, v102 offset:2368
	ds_write_b16 v171, v103 offset:2432
	ds_write_b16_d16_hi v171, v103 offset:2496
	s_waitcnt vmcnt(1)
	ds_write_b16 v171, v108 offset:4096
	ds_write_b16_d16_hi v171, v108 offset:4160
	ds_write_b16 v171, v109 offset:4224
	ds_write_b16_d16_hi v171, v109 offset:4288
	ds_write_b16 v171, v110 offset:4352
	ds_write_b16_d16_hi v171, v110 offset:4416
	ds_write_b16 v171, v111 offset:4480
	ds_write_b16_d16_hi v171, v111 offset:4544
	s_waitcnt vmcnt(0)
	ds_write_b16 v171, v104 offset:6144
	ds_write_b16_d16_hi v171, v104 offset:6208
	ds_write_b16 v171, v105 offset:6272
	ds_write_b16_d16_hi v171, v105 offset:6336
	ds_write_b16 v171, v106 offset:6400
	ds_write_b16_d16_hi v171, v106 offset:6464
	ds_write_b16 v171, v107 offset:6528
	ds_write_b16_d16_hi v171, v107 offset:6592
	v_lshl_add_u64 v[96:97], s[44:45], 0, v[134:135]
	v_mad_u64_u32 v[104:105], s[46:47], v96, s39, v[140:141]
	v_or_b32_e32 v96, s44, v132
	v_mad_i32_i24 v105, v97, s39, v105
	v_mad_u64_u32 v[106:107], s[46:47], v96, s39, v[142:143]
	v_add_co_u32_e32 v96, vcc, s64, v104
	v_mad_i32_i24 v107, s45, v160, v107
	s_nop 0
	v_addc_co_u32_e32 v97, vcc, 0, v105, vcc
	v_add_co_u32_e32 v98, vcc, 0x4c000, v104
	s_nop 1
	v_addc_co_u32_e32 v99, vcc, 0, v105, vcc
	v_add_co_u32_e32 v100, vcc, 0x72000, v104
	global_load_dwordx4 v[120:123], v[96:97], off
	global_load_dwordx4 v[116:119], v[98:99], off
	v_addc_co_u32_e32 v101, vcc, 0, v105, vcc
	global_load_dwordx4 v[96:99], v[106:107], off
	global_load_dwordx4 v[124:127], v[100:101], off
	s_nop 0
	global_load_dwordx4 v[100:103], v[106:107], off offset:64
	global_load_dwordx4 v[108:111], v[106:107], off offset:128
	global_load_dwordx4 v[112:115], v[104:105], off
	s_nop 0
	global_load_dwordx4 v[104:107], v[106:107], off offset:192
	s_and_saveexec_b64 s[44:45], s[10:11]
	s_cbranch_execz .LBB0_1177
	v_mov_b32_e32 v146, 0
	s_mov_b32 s46, 0
	v_mov_b32_e32 v148, v166
	ds_read_b128 v[208:211], v167 offset:112
	ds_read_b128 v[204:207], v167 offset:96
	ds_read_b128 v[200:203], v167 offset:80
	ds_read_b128 v[196:199], v167 offset:64
	ds_read_b128 v[192:195], v167 offset:48
	ds_read_b128 v[188:191], v167 offset:32
	ds_read_b128 v[184:187], v167 offset:16
	ds_read_b128 v[180:183], v167
	v_sub_u32_e32 v212, v144, v173
	v_add_u32_e32 v212, 0xffffc040, v212
	v_cmp_lt_i32_e32 vcc, 31, v212
	s_cmp_eq_u64 vcc, exec
	s_cbranch_scc1 .Lsb_p1fast_0
	s_waitcnt lgkmcnt(7)
	v_exp_f32_e64 v213, -|v211|
	v_exp_f32_e64 v214, -|v210|
	v_exp_f32_e64 v215, -|v209|
	v_max_f32_e32 v216, 0, v211
	v_max_f32_e32 v217, 0, v210
	v_max_f32_e32 v218, 0, v209
	v_add_f32_e32 v213, 1.0, v213
	v_add_f32_e32 v214, 1.0, v214
	v_add_f32_e32 v215, 1.0, v215
	v_log_f32_e32 v213, v213
	v_log_f32_e32 v214, v214
	v_log_f32_e32 v215, v215
	v_cmp_lt_i32_e32 vcc, 31, v212
	v_cmp_lt_i32_e64 s[92:93], 30, v212
	v_cmp_lt_i32_e64 s[94:95], 29, v212
	v_add_f32_e32 v213, v216, v213
	v_add_f32_e32 v214, v217, v214
	v_add_f32_e32 v215, v218, v215
	v_cndmask_b32_e64 v213, 0, -v213, vcc
	v_cndmask_b32_e64 v214, 0, -v214, s[92:93]
	v_cndmask_b32_e64 v215, 0, -v215, s[94:95]
	v_add_f32_e32 v146, v146, v213
	v_add_f32_e32 v211, v211, v146
	v_add_f32_e32 v146, v146, v214
	v_add_f32_e32 v210, v210, v146
	v_add_f32_e32 v146, v146, v215
	v_add_f32_e32 v209, v209, v146
	s_waitcnt lgkmcnt(6)
	v_exp_f32_e64 v213, -|v208|
	v_exp_f32_e64 v214, -|v207|
	v_exp_f32_e64 v215, -|v206|
	v_max_f32_e32 v216, 0, v208
	v_max_f32_e32 v217, 0, v207
	v_max_f32_e32 v218, 0, v206
	v_add_f32_e32 v213, 1.0, v213
	v_add_f32_e32 v214, 1.0, v214
	v_add_f32_e32 v215, 1.0, v215
	v_log_f32_e32 v213, v213
	v_log_f32_e32 v214, v214
	v_log_f32_e32 v215, v215
	v_cmp_lt_i32_e32 vcc, 28, v212
	v_cmp_lt_i32_e64 s[92:93], 27, v212
	v_cmp_lt_i32_e64 s[94:95], 26, v212
	v_add_f32_e32 v213, v216, v213
	v_add_f32_e32 v214, v217, v214
	v_add_f32_e32 v215, v218, v215
	v_cndmask_b32_e64 v213, 0, -v213, vcc
	v_cndmask_b32_e64 v214, 0, -v214, s[92:93]
	v_cndmask_b32_e64 v215, 0, -v215, s[94:95]
	v_add_f32_e32 v146, v146, v213
	v_add_f32_e32 v208, v208, v146
	v_add_f32_e32 v146, v146, v214
	v_add_f32_e32 v207, v207, v146
	v_add_f32_e32 v146, v146, v215
	v_add_f32_e32 v206, v206, v146
	s_waitcnt lgkmcnt(5)
; template <int DH, int MODE>
; __device__ void attn_item(const Params& p, int layer, int b, int blk, int head, char* smem) {
;     ...
;         for (int c = 7; c >= 0; --c) {
;           float4 v = s4[c];
;           float e[4] = {v.x, v.y, v.z, v.w};
; #pragma unroll
;           for (int k = 3; k >= 0; --k) {
;             float z = e[k];
;             bool valid = (kpb + c * 4 + k) < qpos;
;             float sp = fmaxf(z, 0.f) + __builtin_amdgcn_logf(1.f + __builtin_amdgcn_exp2f(-fabsf(z)));
;             run += valid ? -sp : 0.f;
;             e[k] = z + run;
;           }
;           s4[c] = make_float4(e[0], e[1], e[2], e[3]);
;         }
	v_exp_f32_e64 v213, -|v205|
	v_exp_f32_e64 v214, -|v204|
	v_exp_f32_e64 v215, -|v203|
	v_max_f32_e32 v216, 0, v205
	v_max_f32_e32 v217, 0, v204
	v_max_f32_e32 v218, 0, v203
	v_add_f32_e32 v213, 1.0, v213
	v_add_f32_e32 v214, 1.0, v214
	v_add_f32_e32 v215, 1.0, v215
	v_log_f32_e32 v213, v213
	v_log_f32_e32 v214, v214
	v_log_f32_e32 v215, v215
	v_cmp_lt_i32_e32 vcc, 25, v212
	v_cmp_lt_i32_e64 s[92:93], 24, v212
	v_cmp_lt_i32_e64 s[94:95], 23, v212
	v_add_f32_e32 v213, v216, v213
	v_add_f32_e32 v214, v217, v214
	v_add_f32_e32 v215, v218, v215
	v_cndmask_b32_e64 v213, 0, -v213, vcc
	v_cndmask_b32_e64 v214, 0, -v214, s[92:93]
	v_cndmask_b32_e64 v215, 0, -v215, s[94:95]
	v_add_f32_e32 v146, v146, v213
	v_add_f32_e32 v205, v205, v146
	v_add_f32_e32 v146, v146, v214
	v_add_f32_e32 v204, v204, v146
	v_add_f32_e32 v146, v146, v215
	v_add_f32_e32 v203, v203, v146
	v_exp_f32_e64 v213, -|v202|
	v_exp_f32_e64 v214, -|v201|
	v_exp_f32_e64 v215, -|v200|
	v_max_f32_e32 v216, 0, v202
	v_max_f32_e32 v217, 0, v201
	v_max_f32_e32 v218, 0, v200
	v_add_f32_e32 v213, 1.0, v213
	v_add_f32_e32 v214, 1.0, v214
	v_add_f32_e32 v215, 1.0, v215
	v_log_f32_e32 v213, v213
	v_log_f32_e32 v214, v214
	v_log_f32_e32 v215, v215
	v_cmp_lt_i32_e32 vcc, 22, v212
	v_cmp_lt_i32_e64 s[92:93], 21, v212
	v_cmp_lt_i32_e64 s[94:95], 20, v212
	v_add_f32_e32 v213, v216, v213
	v_add_f32_e32 v214, v217, v214
	v_add_f32_e32 v215, v218, v215
	v_cndmask_b32_e64 v213, 0, -v213, vcc
	v_cndmask_b32_e64 v214, 0, -v214, s[92:93]
	v_cndmask_b32_e64 v215, 0, -v215, s[94:95]
	v_add_f32_e32 v146, v146, v213
	v_add_f32_e32 v202, v202, v146
	v_add_f32_e32 v146, v146, v214
	v_add_f32_e32 v201, v201, v146
	v_add_f32_e32 v146, v146, v215
	v_add_f32_e32 v200, v200, v146
	s_waitcnt lgkmcnt(4)
	v_exp_f32_e64 v213, -|v199|
	v_exp_f32_e64 v214, -|v198|
	v_exp_f32_e64 v215, -|v197|
	v_max_f32_e32 v216, 0, v199
	v_max_f32_e32 v217, 0, v198
	v_max_f32_e32 v218, 0, v197
	v_add_f32_e32 v213, 1.0, v213
	v_add_f32_e32 v214, 1.0, v214
	v_add_f32_e32 v215, 1.0, v215
	v_log_f32_e32 v213, v213
	v_log_f32_e32 v214, v214
	v_log_f32_e32 v215, v215
	v_cmp_lt_i32_e32 vcc, 19, v212
	v_cmp_lt_i32_e64 s[92:93], 18, v212
	v_cmp_lt_i32_e64 s[94:95], 17, v212
	v_add_f32_e32 v213, v216, v213
	v_add_f32_e32 v214, v217, v214
	v_add_f32_e32 v215, v218, v215
	v_cndmask_b32_e64 v213, 0, -v213, vcc
	v_cndmask_b32_e64 v214, 0, -v214, s[92:93]
	v_cndmask_b32_e64 v215, 0, -v215, s[94:95]
	v_add_f32_e32 v146, v146, v213
	v_add_f32_e32 v199, v199, v146
	v_add_f32_e32 v146, v146, v214
	v_add_f32_e32 v198, v198, v146
	v_add_f32_e32 v146, v146, v215
	v_add_f32_e32 v197, v197, v146
	s_waitcnt lgkmcnt(3)
	v_exp_f32_e64 v213, -|v196|
	v_exp_f32_e64 v214, -|v195|
	v_exp_f32_e64 v215, -|v194|
	v_max_f32_e32 v216, 0, v196
	v_max_f32_e32 v217, 0, v195
	v_max_f32_e32 v218, 0, v194
	v_add_f32_e32 v213, 1.0, v213
	v_add_f32_e32 v214, 1.0, v214
	v_add_f32_e32 v215, 1.0, v215
	v_log_f32_e32 v213, v213
	v_log_f32_e32 v214, v214
	v_log_f32_e32 v215, v215
	v_cmp_lt_i32_e32 vcc, 16, v212
	v_cmp_lt_i32_e64 s[92:93], 15, v212
	v_cmp_lt_i32_e64 s[94:95], 14, v212
	v_add_f32_e32 v213, v216, v213
	v_add_f32_e32 v214, v217, v214
	v_add_f32_e32 v215, v218, v215
	v_cndmask_b32_e64 v213, 0, -v213, vcc
	v_cndmask_b32_e64 v214, 0, -v214, s[92:93]
	v_cndmask_b32_e64 v215, 0, -v215, s[94:95]
	v_add_f32_e32 v146, v146, v213
	v_add_f32_e32 v196, v196, v146
	v_add_f32_e32 v146, v146, v214
	v_add_f32_e32 v195, v195, v146
	v_add_f32_e32 v146, v146, v215
	v_add_f32_e32 v194, v194, v146
	s_waitcnt lgkmcnt(2)
; template <int DH, int MODE>
; __device__ void attn_item(const Params& p, int layer, int b, int blk, int head, char* smem) {
;     ...
;         for (int c = 7; c >= 0; --c) {
;           float4 v = s4[c];
;           float e[4] = {v.x, v.y, v.z, v.w};
; #pragma unroll
;           for (int k = 3; k >= 0; --k) {
;             float z = e[k];
;             bool valid = (kpb + c * 4 + k) < qpos;
;             float sp = fmaxf(z, 0.f) + __builtin_amdgcn_logf(1.f + __builtin_amdgcn_exp2f(-fabsf(z)));
;             run += valid ? -sp : 0.f;
;             e[k] = z + run;
;           }
;           s4[c] = make_float4(e[0], e[1], e[2], e[3]);
;         }
	v_exp_f32_e64 v213, -|v193|
	v_exp_f32_e64 v214, -|v192|
	v_exp_f32_e64 v215, -|v191|
	v_max_f32_e32 v216, 0, v193
	v_max_f32_e32 v217, 0, v192
	v_max_f32_e32 v218, 0, v191
	v_add_f32_e32 v213, 1.0, v213
	v_add_f32_e32 v214, 1.0, v214
	v_add_f32_e32 v215, 1.0, v215
	v_log_f32_e32 v213, v213
	v_log_f32_e32 v214, v214
	v_log_f32_e32 v215, v215
	v_cmp_lt_i32_e32 vcc, 13, v212
	v_cmp_lt_i32_e64 s[92:93], 12, v212
	v_cmp_lt_i32_e64 s[94:95], 11, v212
	v_add_f32_e32 v213, v216, v213
	v_add_f32_e32 v214, v217, v214
	v_add_f32_e32 v215, v218, v215
	v_cndmask_b32_e64 v213, 0, -v213, vcc
	v_cndmask_b32_e64 v214, 0, -v214, s[92:93]
	v_cndmask_b32_e64 v215, 0, -v215, s[94:95]
	v_add_f32_e32 v146, v146, v213
	v_add_f32_e32 v193, v193, v146
	v_add_f32_e32 v146, v146, v214
	v_add_f32_e32 v192, v192, v146
	v_add_f32_e32 v146, v146, v215
	v_add_f32_e32 v191, v191, v146
	v_exp_f32_e64 v213, -|v190|
	v_exp_f32_e64 v214, -|v189|
	v_exp_f32_e64 v215, -|v188|
	v_max_f32_e32 v216, 0, v190
	v_max_f32_e32 v217, 0, v189
	v_max_f32_e32 v218, 0, v188
	v_add_f32_e32 v213, 1.0, v213
	v_add_f32_e32 v214, 1.0, v214
	v_add_f32_e32 v215, 1.0, v215
	v_log_f32_e32 v213, v213
	v_log_f32_e32 v214, v214
	v_log_f32_e32 v215, v215
	v_cmp_lt_i32_e32 vcc, 10, v212
	v_cmp_lt_i32_e64 s[92:93], 9, v212
	v_cmp_lt_i32_e64 s[94:95], 8, v212
	v_add_f32_e32 v213, v216, v213
	v_add_f32_e32 v214, v217, v214
	v_add_f32_e32 v215, v218, v215
	v_cndmask_b32_e64 v213, 0, -v213, vcc
	v_cndmask_b32_e64 v214, 0, -v214, s[92:93]
	v_cndmask_b32_e64 v215, 0, -v215, s[94:95]
	v_add_f32_e32 v146, v146, v213
	v_add_f32_e32 v190, v190, v146
	v_add_f32_e32 v146, v146, v214
	v_add_f32_e32 v189, v189, v146
	v_add_f32_e32 v146, v146, v215
	v_add_f32_e32 v188, v188, v146
	s_waitcnt lgkmcnt(1)
	v_exp_f32_e64 v213, -|v187|
	v_exp_f32_e64 v214, -|v186|
	v_exp_f32_e64 v215, -|v185|
	v_max_f32_e32 v216, 0, v187
	v_max_f32_e32 v217, 0, v186
	v_max_f32_e32 v218, 0, v185
	v_add_f32_e32 v213, 1.0, v213
	v_add_f32_e32 v214, 1.0, v214
	v_add_f32_e32 v215, 1.0, v215
	v_log_f32_e32 v213, v213
	v_log_f32_e32 v214, v214
	v_log_f32_e32 v215, v215
	v_cmp_lt_i32_e32 vcc, 7, v212
	v_cmp_lt_i32_e64 s[92:93], 6, v212
	v_cmp_lt_i32_e64 s[94:95], 5, v212
	v_add_f32_e32 v213, v216, v213
	v_add_f32_e32 v214, v217, v214
	v_add_f32_e32 v215, v218, v215
	v_cndmask_b32_e64 v213, 0, -v213, vcc
	v_cndmask_b32_e64 v214, 0, -v214, s[92:93]
	v_cndmask_b32_e64 v215, 0, -v215, s[94:95]
	v_add_f32_e32 v146, v146, v213
	v_add_f32_e32 v187, v187, v146
	v_add_f32_e32 v146, v146, v214
	v_add_f32_e32 v186, v186, v146
	v_add_f32_e32 v146, v146, v215
	v_add_f32_e32 v185, v185, v146
	s_waitcnt lgkmcnt(0)
	v_exp_f32_e64 v213, -|v184|
	v_exp_f32_e64 v214, -|v183|
	v_exp_f32_e64 v215, -|v182|
	v_max_f32_e32 v216, 0, v184
	v_max_f32_e32 v217, 0, v183
	v_max_f32_e32 v218, 0, v182
	v_add_f32_e32 v213, 1.0, v213
	v_add_f32_e32 v214, 1.0, v214
	v_add_f32_e32 v215, 1.0, v215
	v_log_f32_e32 v213, v213
	v_log_f32_e32 v214, v214
	v_log_f32_e32 v215, v215
	v_cmp_lt_i32_e32 vcc, 4, v212
	v_cmp_lt_i32_e64 s[92:93], 3, v212
	v_cmp_lt_i32_e64 s[94:95], 2, v212
	v_add_f32_e32 v213, v216, v213
	v_add_f32_e32 v214, v217, v214
	v_add_f32_e32 v215, v218, v215
	v_cndmask_b32_e64 v213, 0, -v213, vcc
	v_cndmask_b32_e64 v214, 0, -v214, s[92:93]
	v_cndmask_b32_e64 v215, 0, -v215, s[94:95]
	v_add_f32_e32 v146, v146, v213
	v_add_f32_e32 v184, v184, v146
	v_add_f32_e32 v146, v146, v214
	v_add_f32_e32 v183, v183, v146
	v_add_f32_e32 v146, v146, v215
	v_add_f32_e32 v182, v182, v146
	v_exp_f32_e64 v213, -|v181|
	v_exp_f32_e64 v214, -|v180|
	v_max_f32_e32 v216, 0, v181
	v_max_f32_e32 v217, 0, v180
	v_add_f32_e32 v213, 1.0, v213
	v_add_f32_e32 v214, 1.0, v214
	v_log_f32_e32 v213, v213
	v_log_f32_e32 v214, v214
	v_cmp_lt_i32_e32 vcc, 1, v212
	v_cmp_lt_i32_e64 s[92:93], 0, v212
	s_nop 0
	v_add_f32_e32 v213, v216, v213
	v_add_f32_e32 v214, v217, v214
	v_cndmask_b32_e64 v213, 0, -v213, vcc
	v_cndmask_b32_e64 v214, 0, -v214, s[92:93]
	v_add_f32_e32 v146, v146, v213
	v_add_f32_e32 v181, v181, v146
	v_add_f32_e32 v146, v146, v214
	v_add_f32_e32 v180, v180, v146
	s_branch .Lsb_p1done_0

; __device__ __forceinline__ unsigned pack2(float a, float b) { return (unsigned)f2bf(a) | ((unsigned)f2bf(b) << 16); }
; template <int DH, int MODE>
; __device__ void attn_item(const Params& p, int layer, int b, int blk, int head, char* smem) {
;     ...
;           s4[c] = make_float4(e[0], e[1], e[2], e[3]);
;         }
;         float other = __shfl_xor(run, 1);
;         float offs = m_run + (half == 0 ? other : 0.f);
; #pragma unroll 2
;         for (int s8 = 0; s8 < 4; ++s8) {
;           float4 va = s4[2 * s8], vb = s4[2 * s8 + 1];
;           float e[8] = {va.x, va.y, va.z, va.w, vb.x, vb.y, vb.z, vb.w};
;           float pv[8];
; #pragma unroll
;           for (int k = 0; k < 8; ++k) {
;             bool valid = (kpb + s8 * 8 + k) < qpos;
;             pv[k] = valid ? __builtin_amdgcn_exp2f(e[k] + offs) : 0.f;
;           }
;           uint4 ov;
;           ov.x = pack2(pv[0], pv[1]); ov.y = pack2(pv[2], pv[3]);
;           ov.z = pack2(pv[4], pv[5]); ov.w = pack2(pv[6], pv[7]);
;           *reinterpret_cast<uint4*>(prow + s8 * 16) = ov;
;         }
.Lsb_p1done_0:
	ds_write_b128 v167, v[180:183]
	ds_write_b128 v167, v[184:187] offset:16
	ds_write_b128 v167, v[188:191] offset:32
	ds_write_b128 v167, v[192:195] offset:48
	ds_write_b128 v167, v[196:199] offset:64
	ds_write_b128 v167, v[200:203] offset:80
	ds_write_b128 v167, v[204:207] offset:96
	ds_write_b128 v167, v[208:211] offset:112
	ds_bpermute_b32 v147, v163, v146
	s_mov_b32 s81, 0
	v_mov_b32_e32 v175, v168
	v_mov_b32_e32 v177, v167
	s_waitcnt lgkmcnt(0)
	v_cndmask_b32_e64 v148, 0, v147, s[8:9]
	v_add_f32_e32 v176, v174, v148
	ds_read_b128 v[180:183], v177
	ds_read_b128 v[184:187], v177 offset:16
	ds_read_b128 v[188:191], v177 offset:32
	ds_read_b128 v[192:195], v177 offset:48
	ds_read_b128 v[196:199], v177 offset:64
	ds_read_b128 v[200:203], v177 offset:80
	ds_read_b128 v[204:207], v177 offset:96
	ds_read_b128 v[208:211], v177 offset:112
	v_sub_u32_e32 v212, v144, v173
	v_add_u32_e32 v212, 0xffffc040, v212
	v_cmp_lt_i32_e32 vcc, 31, v212
	s_cmp_eq_u64 vcc, exec
	s_cbranch_scc1 .Lsb_p2fast_0
	s_waitcnt lgkmcnt(7)
	v_add_f32_e32 v180, v176, v180
	v_add_f32_e32 v181, v176, v181
	v_add_f32_e32 v182, v176, v182
	v_exp_f32_e32 v180, v180
	v_exp_f32_e32 v181, v181
	v_exp_f32_e32 v182, v182
	v_cmp_lt_i32_e32 vcc, 0, v212
	v_cmp_lt_i32_e64 s[92:93], 1, v212
	v_cmp_lt_i32_e64 s[94:95], 2, v212
	v_cndmask_b32_e32 v180, 0, v180, vcc
	v_cndmask_b32_e64 v181, 0, v181, s[92:93]
	v_cndmask_b32_e64 v182, 0, v182, s[94:95]
	s_waitcnt lgkmcnt(6)
	v_add_f32_e32 v183, v176, v183
	v_add_f32_e32 v184, v176, v184
	v_add_f32_e32 v185, v176, v185
	v_exp_f32_e32 v183, v183
	v_exp_f32_e32 v184, v184
	v_exp_f32_e32 v185, v185
	v_cmp_lt_i32_e32 vcc, 3, v212
	v_cmp_lt_i32_e64 s[92:93], 4, v212
	v_cmp_lt_i32_e64 s[94:95], 5, v212
	v_cndmask_b32_e32 v183, 0, v183, vcc
	v_cndmask_b32_e64 v184, 0, v184, s[92:93]
	v_cndmask_b32_e64 v185, 0, v185, s[94:95]
	s_waitcnt lgkmcnt(5)
	v_add_f32_e32 v186, v176, v186
	v_add_f32_e32 v187, v176, v187
	v_add_f32_e32 v188, v176, v188
	v_exp_f32_e32 v186, v186
	v_exp_f32_e32 v187, v187
	v_exp_f32_e32 v188, v188
	v_cmp_lt_i32_e32 vcc, 6, v212
	v_cmp_lt_i32_e64 s[92:93], 7, v212
	v_cmp_lt_i32_e64 s[94:95], 8, v212
	v_cndmask_b32_e32 v186, 0, v186, vcc
	v_cndmask_b32_e64 v187, 0, v187, s[92:93]
	v_cndmask_b32_e64 v188, 0, v188, s[94:95]
	v_add_f32_e32 v189, v176, v189
	v_add_f32_e32 v190, v176, v190
	v_add_f32_e32 v191, v176, v191
	v_exp_f32_e32 v189, v189
	v_exp_f32_e32 v190, v190
	v_exp_f32_e32 v191, v191
	v_cmp_lt_i32_e32 vcc, 9, v212
	v_cmp_lt_i32_e64 s[92:93], 10, v212
	v_cmp_lt_i32_e64 s[94:95], 11, v212
	v_cndmask_b32_e32 v189, 0, v189, vcc
	v_cndmask_b32_e64 v190, 0, v190, s[92:93]
	v_cndmask_b32_e64 v191, 0, v191, s[94:95]
	s_waitcnt lgkmcnt(4)
	v_add_f32_e32 v192, v176, v192
	v_add_f32_e32 v193, v176, v193
	v_add_f32_e32 v194, v176, v194
	v_exp_f32_e32 v192, v192
	v_exp_f32_e32 v193, v193
	v_exp_f32_e32 v194, v194
	v_cmp_lt_i32_e32 vcc, 12, v212
	v_cmp_lt_i32_e64 s[92:93], 13, v212
	v_cmp_lt_i32_e64 s[94:95], 14, v212
	v_cndmask_b32_e32 v192, 0, v192, vcc
	v_cndmask_b32_e64 v193, 0, v193, s[92:93]
	v_cndmask_b32_e64 v194, 0, v194, s[94:95]
	s_waitcnt lgkmcnt(3)
	v_add_f32_e32 v195, v176, v195
	v_add_f32_e32 v196, v176, v196
	v_add_f32_e32 v197, v176, v197
	v_exp_f32_e32 v195, v195
	v_exp_f32_e32 v196, v196
	v_exp_f32_e32 v197, v197
	v_cmp_lt_i32_e32 vcc, 15, v212
	v_cmp_lt_i32_e64 s[92:93], 16, v212
	v_cmp_lt_i32_e64 s[94:95], 17, v212
	v_cndmask_b32_e32 v195, 0, v195, vcc
	v_cndmask_b32_e64 v196, 0, v196, s[92:93]
	v_cndmask_b32_e64 v197, 0, v197, s[94:95]
	s_waitcnt lgkmcnt(2)
	v_add_f32_e32 v198, v176, v198
	v_add_f32_e32 v199, v176, v199
	v_add_f32_e32 v200, v176, v200
	v_exp_f32_e32 v198, v198
	v_exp_f32_e32 v199, v199
	v_exp_f32_e32 v200, v200
	v_cmp_lt_i32_e32 vcc, 18, v212
	v_cmp_lt_i32_e64 s[92:93], 19, v212
	v_cmp_lt_i32_e64 s[94:95], 20, v212
	v_cndmask_b32_e32 v198, 0, v198, vcc
	v_cndmask_b32_e64 v199, 0, v199, s[92:93]
	v_cndmask_b32_e64 v200, 0, v200, s[94:95]
	v_add_f32_e32 v201, v176, v201
	v_add_f32_e32 v202, v176, v202
	v_add_f32_e32 v203, v176, v203
	v_exp_f32_e32 v201, v201
	v_exp_f32_e32 v202, v202
	v_exp_f32_e32 v203, v203
	v_cmp_lt_i32_e32 vcc, 21, v212
	v_cmp_lt_i32_e64 s[92:93], 22, v212
	v_cmp_lt_i32_e64 s[94:95], 23, v212
	v_cndmask_b32_e32 v201, 0, v201, vcc
	v_cndmask_b32_e64 v202, 0, v202, s[92:93]
	v_cndmask_b32_e64 v203, 0, v203, s[94:95]
	s_waitcnt lgkmcnt(1)
	v_add_f32_e32 v204, v176, v204
	v_add_f32_e32 v205, v176, v205
	v_add_f32_e32 v206, v176, v206
	v_exp_f32_e32 v204, v204
	v_exp_f32_e32 v205, v205
	v_exp_f32_e32 v206, v206
	v_cmp_lt_i32_e32 vcc, 24, v212
	v_cmp_lt_i32_e64 s[92:93], 25, v212
	v_cmp_lt_i32_e64 s[94:95], 26, v212
	v_cndmask_b32_e32 v204, 0, v204, vcc
	v_cndmask_b32_e64 v205, 0, v205, s[92:93]
	v_cndmask_b32_e64 v206, 0, v206, s[94:95]
	s_waitcnt lgkmcnt(0)
	v_add_f32_e32 v207, v176, v207
	v_add_f32_e32 v208, v176, v208
	v_add_f32_e32 v209, v176, v209
	v_exp_f32_e32 v207, v207
	v_exp_f32_e32 v208, v208
	v_exp_f32_e32 v209, v209
	v_cmp_lt_i32_e32 vcc, 27, v212
	v_cmp_lt_i32_e64 s[92:93], 28, v212
	v_cmp_lt_i32_e64 s[94:95], 29, v212
	v_cndmask_b32_e32 v207, 0, v207, vcc
	v_cndmask_b32_e64 v208, 0, v208, s[92:93]
	v_cndmask_b32_e64 v209, 0, v209, s[94:95]
	v_add_f32_e32 v210, v176, v210
	v_add_f32_e32 v211, v176, v211
	v_exp_f32_e32 v210, v210
	v_exp_f32_e32 v211, v211
	v_cmp_lt_i32_e32 vcc, 30, v212
	v_cmp_lt_i32_e64 s[92:93], 31, v212
	s_nop 0
	v_cndmask_b32_e32 v210, 0, v210, vcc
	v_cndmask_b32_e64 v211, 0, v211, s[92:93]
	v_cvt_pk_bf16_f32 v148, v180, v181
	v_cvt_pk_bf16_f32 v149, v182, v183
	v_cvt_pk_bf16_f32 v150, v184, v185
	v_cvt_pk_bf16_f32 v151, v186, v187
	ds_write_b128 v175, v[148:151]
	s_nop 0
	v_cvt_pk_bf16_f32 v148, v188, v189
	v_cvt_pk_bf16_f32 v149, v190, v191
	v_cvt_pk_bf16_f32 v150, v192, v193
	v_cvt_pk_bf16_f32 v151, v194, v195
	ds_write_b128 v175, v[148:151] offset:16
	s_nop 0
	v_cvt_pk_bf16_f32 v148, v196, v197
	v_cvt_pk_bf16_f32 v149, v198, v199
	v_cvt_pk_bf16_f32 v150, v200, v201
	v_cvt_pk_bf16_f32 v151, v202, v203
	ds_write_b128 v175, v[148:151] offset:32
	s_nop 0
	v_cvt_pk_bf16_f32 v148, v204, v205
	v_cvt_pk_bf16_f32 v149, v206, v207
	v_cvt_pk_bf16_f32 v150, v208, v209
	v_cvt_pk_bf16_f32 v151, v210, v211
	ds_write_b128 v175, v[148:151] offset:48
	s_branch .LBB0_1176
